# GEMM phases: first K-loop iteration peeled with MFMA SrcC=0 so the 128 v_mov accumulator zeroing per tile is gone (11 of 12 GEMM loops)
# speedup vs baseline: 1.0286x; 1.0127x over previous
; #define PG8_STAGE(bufoff, gbase, voff) do { _Pragma("unroll") for (int _i = 0; _i < 2; ++_i) \
;         __builtin_amdgcn_global_load_lds((const unsigned*)((const char*)(gbase) + (voff)[_i]), (PG8_LAS unsigned*)(lds + (bufoff) + ldsw + _i * 8192), 16, 0, 0); } while (0)
; #define PG8_WAIT_V(n) asm volatile("s_waitcnt vmcnt(" #n ")" ::: "memory")
; #define PG8_WAIT_L(n) asm volatile("s_waitcnt lgkmcnt(" #n ")" ::: "memory")
; #define PG8_BAR __builtin_amdgcn_s_barrier()
; template <class Epi, class Sched, bool ALIGN_EPI = false, bool SP2 = false, bool TA = true>
; __device__ __forceinline__ void gemm_phase(PG8_LAS unsigned char* lds, const Gemm g, const Sched& S, const Epi& E) {
;     ...
;         const bool has_next = S.next(ui + 1, nxt);
;         const char* nA = has_next ? (const char*)g.A + (size_t)nxt.pm * tstep : cA; const char* nB = has_next ? (const char*)g.Bt + (size_t)nxt.pn * tstep : cB;
; #pragma unroll 1
;         for (int t = 0; t < nt; t += 2) {
;             const bool last = (t == nt - 2);
;             const char* a1 = cA + (size_t)(t + 1) * kstep;
;             const char* a2 = last ? nA : cA + (size_t)(t + 2) * kstep; const char* b2 = last ? nB : cB + (size_t)(t + 2) * kstepB;
;             const char* a3 = a2 + kstep; const char* b3 = b2 + kstepB;
;             if (last && has_next) S.a_ready(nxt);
;             if constexpr (SP2) {
;             PG8_LDB(B0, 0, 0); PG8_LDB(B1, 0, 1); PG8_SCHED; PG8_LDA(At, 0, 0); PG8_STAGE(PG8_SA(1, 1), a1 + hstep, voffA);
;             PG8_WAIT_V(8); PG8_WAIT_L(0); PG8_BAR; PG8_MMA(0, 0, At, B0); PG8_MMA(0, 1, At, B1); PG8_BAR; PG8_SCHED;
;             PG8_LDA(At, 0, 1); PG8_STAGE(PG8_SB(0, 0), b2, voffB); PG8_STAGE(PG8_SB(0, 1), b2 + hstep, voffB); PG8_STAGE(PG8_SA(0, 0), a2, voffA);
;             PG8_WAIT_V(8); PG8_WAIT_L(0); PG8_BAR; PG8_MMA(1, 0, At, B0); PG8_MMA(1, 1, At, B1); PG8_BAR; PG8_SCHED;
;             PG8_LDB(B0, 1, 0); PG8_LDB(B1, 1, 1); PG8_SCHED; PG8_LDA(At, 1, 0); PG8_STAGE(PG8_SA(0, 1), a2 + hstep, voffA);
;             PG8_WAIT_V(8); PG8_WAIT_L(0); PG8_BAR; PG8_MMA(0, 0, At, B0); PG8_MMA(0, 1, At, B1); PG8_BAR; PG8_SCHED;
;             PG8_LDA(At, 1, 1); PG8_STAGE(PG8_SB(1, 0), b3, voffB); PG8_STAGE(PG8_SB(1, 1), b3 + hstep, voffB); PG8_STAGE(PG8_SA(1, 0), a3, voffA);
;             PG8_WAIT_V(8); PG8_WAIT_L(0); PG8_BAR; PG8_MMA(1, 0, At, B0); PG8_MMA(1, 1, At, B1); PG8_BAR; PG8_SCHED;
.LBB0_692:
	s_ashr_i32 s95, s94, 31
	s_lshl_b64 s[70:71], s[94:95], 19
	s_add_u32 s26, s18, s70
	s_addc_u32 s27, s19, s71
	s_and_b64 s[72:73], s[4:5], exec
	s_cselect_b32 s61, s27, s1
	s_cselect_b32 s75, s26, s0
	s_ashr_i32 s97, s96, 31
	s_lshl_b64 s[72:73], s[96:97], 19
	s_add_u32 s92, s21, s72
	s_addc_u32 s93, s22, s73
	s_and_b64 s[78:79], s[4:5], exec
	s_cselect_b32 s59, s93, s77
	s_cselect_b32 s78, s92, s76
	s_add_u32 s0, s0, 0x44000
	s_addc_u32 s1, s1, 0
	s_add_u32 s76, s76, 0x8000
	s_addc_u32 s77, s77, 0
	s_mov_b32 s79, -2
	s_waitcnt lgkmcnt(0)
	s_waitcnt lgkmcnt(0)
	ds_read_b128 v[80:83], v179
	ds_read_b128 v[84:87], v179 offset:1024
	ds_read_b128 v[88:91], v179 offset:2048
	ds_read_b128 v[92:95], v179 offset:3072
	ds_read_b128 v[144:147], v180
	ds_read_b128 v[148:151], v180 offset:1024
	ds_read_b128 v[152:155], v180 offset:2048
	ds_read_b128 v[156:159], v180 offset:3072
	s_add_u32 s80, s0, 0xfffc4000
	s_addc_u32 s81, s1, -1
	s_cmp_eq_u32 s79, 12
	s_cselect_b32 s81, s61, s81
	s_cselect_b32 s80, s75, s80
	s_cselect_b32 s83, s59, s77
	s_cselect_b32 s82, s78, s76
	v_lshl_add_u64 v[210:211], s[0:1], 0, v[160:161]
	s_add_i32 m0, s30, 0xc000
	ds_read_b128 v[168:171], v181
	ds_read_b128 v[172:175], v181 offset:1024
	ds_read_b128 v[184:187], v181 offset:2048
	ds_read_b128 v[188:191], v181 offset:3072
	ds_read_b128 v[192:195], v181 offset:4096
	ds_read_b128 v[196:199], v181 offset:5120
	ds_read_b128 v[200:203], v181 offset:6144
	ds_read_b128 v[204:207], v181 offset:7168
	global_load_lds_dwordx4 v[210:211], off
	v_lshl_add_u64 v[210:211], v[210:211], 0, s[8:9]
	s_add_i32 m0, s30, 0xe000
	s_nop 0
	global_load_lds_dwordx4 v[210:211], off
	s_waitcnt vmcnt(8)
	s_waitcnt lgkmcnt(0)
	s_barrier
	s_setprio 1
	s_waitcnt lgkmcnt(0)
	v_mfma_f32_16x16x32_bf16 v[140:143], v[80:83], v[168:171], 0
	v_mfma_f32_16x16x32_bf16 v[136:139], v[88:91], v[168:171], 0
	v_mfma_f32_16x16x32_bf16 v[124:127], v[80:83], v[184:187], 0
	v_mfma_f32_16x16x32_bf16 v[120:123], v[88:91], v[184:187], 0
	v_mfma_f32_16x16x32_bf16 v[108:111], v[80:83], v[192:195], 0
	v_mfma_f32_16x16x32_bf16 v[104:107], v[88:91], v[192:195], 0
	v_mfma_f32_16x16x32_bf16 v[76:79], v[80:83], v[200:203], 0
	v_mfma_f32_16x16x32_bf16 v[72:75], v[88:91], v[200:203], 0
	v_mfma_f32_16x16x32_bf16 v[140:143], v[84:87], v[172:175], v[140:143]
	v_mfma_f32_16x16x32_bf16 v[136:139], v[92:95], v[172:175], v[136:139]
	v_mfma_f32_16x16x32_bf16 v[124:127], v[84:87], v[188:191], v[124:127]
	v_mfma_f32_16x16x32_bf16 v[120:123], v[92:95], v[188:191], v[120:123]
	v_mfma_f32_16x16x32_bf16 v[108:111], v[84:87], v[196:199], v[108:111]
	v_mfma_f32_16x16x32_bf16 v[104:107], v[92:95], v[196:199], v[104:107]
	v_mfma_f32_16x16x32_bf16 v[76:79], v[84:87], v[204:207], v[76:79]
	v_mfma_f32_16x16x32_bf16 v[72:75], v[92:95], v[204:207], v[72:75]
	s_setprio 0
	s_setprio 1
	v_mfma_f32_16x16x32_bf16 v[132:135], v[144:147], v[168:171], 0
	v_mfma_f32_16x16x32_bf16 v[128:131], v[152:155], v[168:171], 0
	v_mfma_f32_16x16x32_bf16 v[116:119], v[144:147], v[184:187], 0
	v_mfma_f32_16x16x32_bf16 v[112:115], v[152:155], v[184:187], 0
	v_mfma_f32_16x16x32_bf16 v[100:103], v[144:147], v[192:195], 0
	v_mfma_f32_16x16x32_bf16 v[96:99], v[152:155], v[192:195], 0
	v_mfma_f32_16x16x32_bf16 v[68:71], v[144:147], v[200:203], 0
	v_mfma_f32_16x16x32_bf16 v[64:67], v[152:155], v[200:203], 0
	v_mfma_f32_16x16x32_bf16 v[132:135], v[148:151], v[172:175], v[132:135]
	v_mfma_f32_16x16x32_bf16 v[128:131], v[156:159], v[172:175], v[128:131]
	v_mfma_f32_16x16x32_bf16 v[116:119], v[148:151], v[188:191], v[116:119]
	v_mfma_f32_16x16x32_bf16 v[112:115], v[156:159], v[188:191], v[112:115]
	v_mfma_f32_16x16x32_bf16 v[100:103], v[148:151], v[196:199], v[100:103]
	v_mfma_f32_16x16x32_bf16 v[96:99], v[156:159], v[196:199], v[96:99]
	v_mfma_f32_16x16x32_bf16 v[68:71], v[148:151], v[204:207], v[68:71]
	v_mfma_f32_16x16x32_bf16 v[64:67], v[156:159], v[204:207], v[64:67]
	s_setprio 0
	s_barrier
	v_lshl_add_u64 v[210:211], s[82:83], 0, v[160:161]
	s_add_i32 s82, s87, s23
	s_mov_b32 m0, s82
	ds_read_b128 v[168:171], v181 offset:16384
	ds_read_b128 v[172:175], v181 offset:17408
	ds_read_b128 v[184:187], v181 offset:18432
	ds_read_b128 v[188:191], v181 offset:19456
	ds_read_b128 v[192:195], v181 offset:20480
	ds_read_b128 v[196:199], v181 offset:21504
	ds_read_b128 v[200:203], v181 offset:22528
	ds_read_b128 v[204:207], v181 offset:23552
	global_load_lds_dwordx4 v[210:211], off
	v_lshl_add_u64 v[212:213], v[210:211], 0, s[8:9]
	s_add_i32 m0, s82, 0x2000
	s_add_i32 s82, s88, s23
	global_load_lds_dwordx4 v[212:213], off
	v_lshl_add_u64 v[212:213], v[210:211], 0, s[10:11]
	s_mov_b32 m0, s82
	s_nop 0
	global_load_lds_dwordx4 v[212:213], off
	v_lshl_add_u64 v[212:213], v[210:211], 0, s[12:13]
	s_add_i32 m0, s82, 0x2000
	s_nop 0
	global_load_lds_dwordx4 v[212:213], off
	v_lshl_add_u64 v[212:213], s[80:81], 0, v[160:161]
	s_mov_b32 m0, s30
	v_lshl_add_u64 v[214:215], v[212:213], 0, s[8:9]
	global_load_lds_dwordx4 v[212:213], off
	s_mov_b32 m0, s31
	s_nop 0
	global_load_lds_dwordx4 v[214:215], off
	s_waitcnt vmcnt(8)
	s_waitcnt lgkmcnt(0)
	s_barrier
; #define PG8_STAGE(bufoff, gbase, voff) do { _Pragma("unroll") for (int _i = 0; _i < 2; ++_i) \
;         __builtin_amdgcn_global_load_lds((const unsigned*)((const char*)(gbase) + (voff)[_i]), (PG8_LAS unsigned*)(lds + (bufoff) + ldsw + _i * 8192), 16, 0, 0); } while (0)
; #define PG8_LDA(dst, b, h) do { _Pragma("unroll") for (int m = 0; m < 4; ++m) _Pragma("unroll") for (int k = 0; k < 2; ++k) dst[m][k] = *(const PG8_LAS bf16x8*)(lds + PG8_SA(b, h) + aoff + m * 2048 + k * 1024); } while (0)
; #define PG8_LDB(dst, b, h) do { _Pragma("unroll") for (int n = 0; n < 2; ++n) _Pragma("unroll") for (int k = 0; k < 2; ++k) dst[n][k] = *(const PG8_LAS bf16x8*)(lds + PG8_SB(b, h) + boff + n * 2048 + k * 1024); } while (0)
; #define PG8_MMA(ai, bj, At, Bt) do { __builtin_amdgcn_s_setprio(1); _Pragma("unroll") for (int m = 0; m < 4; ++m) _Pragma("unroll") for (int n = 0; n < 2; ++n) _Pragma("unroll") for (int k = 0; k < 2; ++k) \
;         acc[ai][bj][m][n] = __builtin_amdgcn_mfma_f32_16x16x32_bf16(Bt[n][k], At[m][k], acc[ai][bj][m][n], 0, 0, 0); __builtin_amdgcn_s_setprio(0); } while (0)
; #define PG8_BAR __builtin_amdgcn_s_barrier()
; template <class Epi, class Sched, bool ALIGN_EPI = false, bool SP2 = false, bool TA = true>
; __device__ __forceinline__ void gemm_phase(PG8_LAS unsigned char* lds, const Gemm g, const Sched& S, const Epi& E) {
;     ...
;             PG8_LDB(B0, 0, 0); PG8_LDB(B1, 0, 1); PG8_SCHED; PG8_LDA(At, 0, 0); PG8_STAGE(PG8_SA(1, 1), a1 + hstep, voffA);
;             PG8_WAIT_V(8); PG8_WAIT_L(0); PG8_BAR; PG8_MMA(0, 0, At, B0); PG8_MMA(0, 1, At, B1); PG8_BAR; PG8_SCHED;
;             PG8_LDA(At, 0, 1); PG8_STAGE(PG8_SB(0, 0), b2, voffB); PG8_STAGE(PG8_SB(0, 1), b2 + hstep, voffB); PG8_STAGE(PG8_SA(0, 0), a2, voffA);
;             PG8_WAIT_V(8); PG8_WAIT_L(0); PG8_BAR; PG8_MMA(1, 0, At, B0); PG8_MMA(1, 1, At, B1); PG8_BAR; PG8_SCHED;
;             PG8_LDB(B0, 1, 0); PG8_LDB(B1, 1, 1); PG8_SCHED; PG8_LDA(At, 1, 0); PG8_STAGE(PG8_SA(0, 1), a2 + hstep, voffA);
;             PG8_WAIT_V(8); PG8_WAIT_L(0); PG8_BAR; PG8_MMA(0, 0, At, B0); PG8_MMA(0, 1, At, B1); PG8_BAR; PG8_SCHED;
;             PG8_LDA(At, 1, 1); PG8_STAGE(PG8_SB(1, 0), b3, voffB); PG8_STAGE(PG8_SB(1, 1), b3 + hstep, voffB); PG8_STAGE(PG8_SA(1, 0), a3, voffA);
;             PG8_WAIT_V(8); PG8_WAIT_L(0); PG8_BAR; PG8_MMA(1, 0, At, B0); PG8_MMA(1, 1, At, B1); PG8_BAR; PG8_SCHED;
	s_setprio 1
	s_waitcnt lgkmcnt(0)
	v_mfma_f32_16x16x32_bf16 v[60:63], v[80:83], v[168:171], 0
	v_mfma_f32_16x16x32_bf16 v[56:59], v[88:91], v[168:171], 0
	v_mfma_f32_16x16x32_bf16 v[44:47], v[80:83], v[184:187], 0
	v_mfma_f32_16x16x32_bf16 v[40:43], v[88:91], v[184:187], 0
	v_mfma_f32_16x16x32_bf16 v[28:31], v[80:83], v[192:195], 0
	v_mfma_f32_16x16x32_bf16 v[24:27], v[88:91], v[192:195], 0
	v_mfma_f32_16x16x32_bf16 v[12:15], v[80:83], v[200:203], 0
	v_mfma_f32_16x16x32_bf16 v[8:11], v[88:91], v[200:203], 0
	v_mfma_f32_16x16x32_bf16 v[60:63], v[84:87], v[172:175], v[60:63]
	v_mfma_f32_16x16x32_bf16 v[56:59], v[92:95], v[172:175], v[56:59]
	v_mfma_f32_16x16x32_bf16 v[44:47], v[84:87], v[188:191], v[44:47]
	v_mfma_f32_16x16x32_bf16 v[40:43], v[92:95], v[188:191], v[40:43]
	v_mfma_f32_16x16x32_bf16 v[28:31], v[84:87], v[196:199], v[28:31]
	v_mfma_f32_16x16x32_bf16 v[24:27], v[92:95], v[196:199], v[24:27]
	v_mfma_f32_16x16x32_bf16 v[12:15], v[84:87], v[204:207], v[12:15]
	v_mfma_f32_16x16x32_bf16 v[8:11], v[92:95], v[204:207], v[8:11]
	s_setprio 0
	s_setprio 1
	v_mfma_f32_16x16x32_bf16 v[52:55], v[144:147], v[168:171], 0
	v_mfma_f32_16x16x32_bf16 v[48:51], v[152:155], v[168:171], 0
	v_mfma_f32_16x16x32_bf16 v[36:39], v[144:147], v[184:187], 0
	v_mfma_f32_16x16x32_bf16 v[32:35], v[152:155], v[184:187], 0
	v_mfma_f32_16x16x32_bf16 v[20:23], v[144:147], v[192:195], 0
	v_mfma_f32_16x16x32_bf16 v[16:19], v[152:155], v[192:195], 0
	v_mfma_f32_16x16x32_bf16 v[4:7], v[144:147], v[200:203], 0
	v_mfma_f32_16x16x32_bf16 v[0:3], v[152:155], v[200:203], 0
	v_mfma_f32_16x16x32_bf16 v[52:55], v[148:151], v[172:175], v[52:55]
	v_mfma_f32_16x16x32_bf16 v[48:51], v[156:159], v[172:175], v[48:51]
	v_mfma_f32_16x16x32_bf16 v[36:39], v[148:151], v[188:191], v[36:39]
	v_mfma_f32_16x16x32_bf16 v[32:35], v[156:159], v[188:191], v[32:35]
	v_mfma_f32_16x16x32_bf16 v[20:23], v[148:151], v[196:199], v[20:23]
	v_mfma_f32_16x16x32_bf16 v[16:19], v[156:159], v[196:199], v[16:19]
	v_mfma_f32_16x16x32_bf16 v[4:7], v[148:151], v[204:207], v[4:7]
	v_mfma_f32_16x16x32_bf16 v[0:3], v[156:159], v[204:207], v[0:3]
	s_setprio 0
	s_barrier
	s_add_i32 s80, 0, 0x18000
	s_add_i32 s81, 0, 0x1c000
	v_add_u32_e32 v92, s80, v178
	v_add_u32_e32 v156, s81, v178
	ds_read_b128 v[80:83], v92
	ds_read_b128 v[84:87], v92 offset:1024
	ds_read_b128 v[88:91], v92 offset:2048
	ds_read_b128 v[92:95], v92 offset:3072
	ds_read_b128 v[144:147], v156
	ds_read_b128 v[148:151], v156 offset:1024
	ds_read_b128 v[152:155], v156 offset:2048
	ds_read_b128 v[156:159], v156 offset:3072
	s_mov_b32 m0, s33
	v_lshl_add_u64 v[214:215], v[212:213], 0, s[10:11]
	ds_read_b128 v[168:171], v181 offset:32768
	ds_read_b128 v[172:175], v181 offset:33792
	ds_read_b128 v[184:187], v181 offset:34816
	ds_read_b128 v[188:191], v181 offset:35840
	ds_read_b128 v[192:195], v181 offset:36864
	ds_read_b128 v[196:199], v181 offset:37888
	ds_read_b128 v[200:203], v181 offset:38912
	ds_read_b128 v[204:207], v181 offset:39936
	global_load_lds_dwordx4 v[214:215], off
	v_lshl_add_u64 v[214:215], v[212:213], 0, s[12:13]
	s_mov_b32 m0, s36
	s_nop 0
	global_load_lds_dwordx4 v[214:215], off
	s_waitcnt vmcnt(8)
	s_waitcnt lgkmcnt(0)
	s_barrier
	s_setprio 1
	s_waitcnt lgkmcnt(0)
	v_mfma_f32_16x16x32_bf16 v[140:143], v[80:83], v[168:171], v[140:143]
	v_mfma_f32_16x16x32_bf16 v[136:139], v[88:91], v[168:171], v[136:139]
	v_mfma_f32_16x16x32_bf16 v[124:127], v[80:83], v[184:187], v[124:127]
	v_mfma_f32_16x16x32_bf16 v[120:123], v[88:91], v[184:187], v[120:123]
	v_mfma_f32_16x16x32_bf16 v[108:111], v[80:83], v[192:195], v[108:111]
	v_mfma_f32_16x16x32_bf16 v[104:107], v[88:91], v[192:195], v[104:107]
	v_mfma_f32_16x16x32_bf16 v[76:79], v[80:83], v[200:203], v[76:79]
	v_mfma_f32_16x16x32_bf16 v[72:75], v[88:91], v[200:203], v[72:75]
	v_mfma_f32_16x16x32_bf16 v[140:143], v[84:87], v[172:175], v[140:143]
	v_mfma_f32_16x16x32_bf16 v[136:139], v[92:95], v[172:175], v[136:139]
	v_mfma_f32_16x16x32_bf16 v[124:127], v[84:87], v[188:191], v[124:127]
	v_mfma_f32_16x16x32_bf16 v[120:123], v[92:95], v[188:191], v[120:123]
	v_mfma_f32_16x16x32_bf16 v[108:111], v[84:87], v[196:199], v[108:111]
	v_mfma_f32_16x16x32_bf16 v[104:107], v[92:95], v[196:199], v[104:107]
	v_mfma_f32_16x16x32_bf16 v[76:79], v[84:87], v[204:207], v[76:79]
	v_mfma_f32_16x16x32_bf16 v[72:75], v[92:95], v[204:207], v[72:75]
	s_setprio 0
	s_setprio 1
	v_mfma_f32_16x16x32_bf16 v[132:135], v[144:147], v[168:171], v[132:135]
	v_mfma_f32_16x16x32_bf16 v[128:131], v[152:155], v[168:171], v[128:131]
	v_mfma_f32_16x16x32_bf16 v[116:119], v[144:147], v[184:187], v[116:119]
	v_mfma_f32_16x16x32_bf16 v[112:115], v[152:155], v[184:187], v[112:115]
	v_mfma_f32_16x16x32_bf16 v[100:103], v[144:147], v[192:195], v[100:103]
	v_mfma_f32_16x16x32_bf16 v[96:99], v[152:155], v[192:195], v[96:99]
	v_mfma_f32_16x16x32_bf16 v[68:71], v[144:147], v[200:203], v[68:71]
	v_mfma_f32_16x16x32_bf16 v[64:67], v[152:155], v[200:203], v[64:67]
	v_mfma_f32_16x16x32_bf16 v[132:135], v[148:151], v[172:175], v[132:135]
	v_mfma_f32_16x16x32_bf16 v[128:131], v[156:159], v[172:175], v[128:131]
	v_mfma_f32_16x16x32_bf16 v[116:119], v[148:151], v[188:191], v[116:119]
	v_mfma_f32_16x16x32_bf16 v[112:115], v[156:159], v[188:191], v[112:115]
	v_mfma_f32_16x16x32_bf16 v[100:103], v[148:151], v[196:199], v[100:103]
	v_mfma_f32_16x16x32_bf16 v[96:99], v[156:159], v[196:199], v[96:99]
	v_mfma_f32_16x16x32_bf16 v[68:71], v[148:151], v[204:207], v[68:71]
	v_mfma_f32_16x16x32_bf16 v[64:67], v[156:159], v[204:207], v[64:67]
	s_setprio 0
	s_barrier
; #define PG8_STAGE(bufoff, gbase, voff) do { _Pragma("unroll") for (int _i = 0; _i < 2; ++_i) \
;         __builtin_amdgcn_global_load_lds((const unsigned*)((const char*)(gbase) + (voff)[_i]), (PG8_LAS unsigned*)(lds + (bufoff) + ldsw + _i * 8192), 16, 0, 0); } while (0)
; #define PG8_LDA(dst, b, h) do { _Pragma("unroll") for (int m = 0; m < 4; ++m) _Pragma("unroll") for (int k = 0; k < 2; ++k) dst[m][k] = *(const PG8_LAS bf16x8*)(lds + PG8_SA(b, h) + aoff + m * 2048 + k * 1024); } while (0)
; #define PG8_LDB(dst, b, h) do { _Pragma("unroll") for (int n = 0; n < 2; ++n) _Pragma("unroll") for (int k = 0; k < 2; ++k) dst[n][k] = *(const PG8_LAS bf16x8*)(lds + PG8_SB(b, h) + boff + n * 2048 + k * 1024); } while (0)
; #define PG8_MMA(ai, bj, At, Bt) do { __builtin_amdgcn_s_setprio(1); _Pragma("unroll") for (int m = 0; m < 4; ++m) _Pragma("unroll") for (int n = 0; n < 2; ++n) _Pragma("unroll") for (int k = 0; k < 2; ++k) \
;         acc[ai][bj][m][n] = __builtin_amdgcn_mfma_f32_16x16x32_bf16(Bt[n][k], At[m][k], acc[ai][bj][m][n], 0, 0, 0); __builtin_amdgcn_s_setprio(0); } while (0)
; #define PG8_BAR __builtin_amdgcn_s_barrier()
; template <class Epi, class Sched, bool ALIGN_EPI = false, bool SP2 = false, bool TA = true>
; __device__ __forceinline__ void gemm_phase(PG8_LAS unsigned char* lds, const Gemm g, const Sched& S, const Epi& E) {
;     ...
;             PG8_LDB(B0, 0, 0); PG8_LDB(B1, 0, 1); PG8_SCHED; PG8_LDA(At, 0, 0); PG8_STAGE(PG8_SA(1, 1), a1 + hstep, voffA);
;             PG8_WAIT_V(8); PG8_WAIT_L(0); PG8_BAR; PG8_MMA(0, 0, At, B0); PG8_MMA(0, 1, At, B1); PG8_BAR; PG8_SCHED;
;             PG8_LDA(At, 0, 1); PG8_STAGE(PG8_SB(0, 0), b2, voffB); PG8_STAGE(PG8_SB(0, 1), b2 + hstep, voffB); PG8_STAGE(PG8_SA(0, 0), a2, voffA);
;             PG8_WAIT_V(8); PG8_WAIT_L(0); PG8_BAR; PG8_MMA(1, 0, At, B0); PG8_MMA(1, 1, At, B1); PG8_BAR; PG8_SCHED;
;             PG8_LDB(B0, 1, 0); PG8_LDB(B1, 1, 1); PG8_SCHED; PG8_LDA(At, 1, 0); PG8_STAGE(PG8_SA(0, 1), a2 + hstep, voffA);
;             PG8_WAIT_V(8); PG8_WAIT_L(0); PG8_BAR; PG8_MMA(0, 0, At, B0); PG8_MMA(0, 1, At, B1); PG8_BAR; PG8_SCHED;
;             PG8_LDA(At, 1, 1); PG8_STAGE(PG8_SB(1, 0), b3, voffB); PG8_STAGE(PG8_SB(1, 1), b3 + hstep, voffB); PG8_STAGE(PG8_SA(1, 0), a3, voffA);
;             PG8_WAIT_V(8); PG8_WAIT_L(0); PG8_BAR; PG8_MMA(1, 0, At, B0); PG8_MMA(1, 1, At, B1); PG8_BAR; PG8_SCHED;
	s_add_i32 s80, s80, s23
	v_lshl_add_u64 v[214:215], v[210:211], 0, s[44:45]
	s_mov_b32 m0, s80
	ds_read_b128 v[168:171], v181 offset:49152
	ds_read_b128 v[172:175], v181 offset:50176
	ds_read_b128 v[184:187], v181 offset:51200
	ds_read_b128 v[188:191], v181 offset:52224
	ds_read_b128 v[192:195], v181 offset:53248
	ds_read_b128 v[196:199], v181 offset:54272
	ds_read_b128 v[200:203], v181 offset:55296
	ds_read_b128 v[204:207], v181 offset:56320
	global_load_lds_dwordx4 v[214:215], off
	v_lshl_add_u64 v[214:215], v[210:211], 0, s[46:47]
	s_add_i32 m0, s80, 0x2000
	s_add_i32 s80, s81, s23
	global_load_lds_dwordx4 v[214:215], off
	v_lshl_add_u64 v[214:215], v[210:211], 0, s[48:49]
	s_mov_b32 m0, s80
	v_lshl_add_u64 v[210:211], v[210:211], 0, s[50:51]
	global_load_lds_dwordx4 v[214:215], off
	s_add_i32 m0, s80, 0x2000
	s_nop 0
	global_load_lds_dwordx4 v[210:211], off
	v_lshl_add_u64 v[210:211], v[212:213], 0, s[44:45]
	s_mov_b32 m0, s37
	s_nop 0
	global_load_lds_dwordx4 v[210:211], off
	v_lshl_add_u64 v[210:211], v[212:213], 0, s[46:47]
	s_mov_b32 m0, s38
	s_nop 0
	global_load_lds_dwordx4 v[210:211], off
	s_waitcnt vmcnt(8)
	s_waitcnt lgkmcnt(0)
	s_barrier
	s_setprio 1
	s_waitcnt lgkmcnt(0)
	v_mfma_f32_16x16x32_bf16 v[60:63], v[80:83], v[168:171], v[60:63]
	v_mfma_f32_16x16x32_bf16 v[56:59], v[88:91], v[168:171], v[56:59]
	v_mfma_f32_16x16x32_bf16 v[44:47], v[80:83], v[184:187], v[44:47]
	v_mfma_f32_16x16x32_bf16 v[40:43], v[88:91], v[184:187], v[40:43]
	v_mfma_f32_16x16x32_bf16 v[28:31], v[80:83], v[192:195], v[28:31]
	v_mfma_f32_16x16x32_bf16 v[24:27], v[88:91], v[192:195], v[24:27]
	v_mfma_f32_16x16x32_bf16 v[12:15], v[80:83], v[200:203], v[12:15]
	v_mfma_f32_16x16x32_bf16 v[8:11], v[88:91], v[200:203], v[8:11]
	v_mfma_f32_16x16x32_bf16 v[60:63], v[84:87], v[172:175], v[60:63]
	v_mfma_f32_16x16x32_bf16 v[56:59], v[92:95], v[172:175], v[56:59]
	v_mfma_f32_16x16x32_bf16 v[44:47], v[84:87], v[188:191], v[44:47]
	v_mfma_f32_16x16x32_bf16 v[40:43], v[92:95], v[188:191], v[40:43]
	v_mfma_f32_16x16x32_bf16 v[28:31], v[84:87], v[196:199], v[28:31]
	v_mfma_f32_16x16x32_bf16 v[24:27], v[92:95], v[196:199], v[24:27]
	v_mfma_f32_16x16x32_bf16 v[12:15], v[84:87], v[204:207], v[12:15]
	v_mfma_f32_16x16x32_bf16 v[8:11], v[92:95], v[204:207], v[8:11]
	s_setprio 0
	s_setprio 1
	v_mfma_f32_16x16x32_bf16 v[52:55], v[144:147], v[168:171], v[52:55]
	v_mfma_f32_16x16x32_bf16 v[48:51], v[152:155], v[168:171], v[48:51]
	v_mfma_f32_16x16x32_bf16 v[36:39], v[144:147], v[184:187], v[36:39]
	v_mfma_f32_16x16x32_bf16 v[32:35], v[152:155], v[184:187], v[32:35]
	v_mfma_f32_16x16x32_bf16 v[20:23], v[144:147], v[192:195], v[20:23]
	v_mfma_f32_16x16x32_bf16 v[16:19], v[152:155], v[192:195], v[16:19]
	v_mfma_f32_16x16x32_bf16 v[4:7], v[144:147], v[200:203], v[4:7]
	v_mfma_f32_16x16x32_bf16 v[0:3], v[152:155], v[200:203], v[0:3]
	v_mfma_f32_16x16x32_bf16 v[52:55], v[148:151], v[172:175], v[52:55]
	v_mfma_f32_16x16x32_bf16 v[48:51], v[156:159], v[172:175], v[48:51]
	v_mfma_f32_16x16x32_bf16 v[36:39], v[148:151], v[188:191], v[36:39]
	v_mfma_f32_16x16x32_bf16 v[32:35], v[156:159], v[188:191], v[32:35]
	v_mfma_f32_16x16x32_bf16 v[20:23], v[148:151], v[196:199], v[20:23]
	v_mfma_f32_16x16x32_bf16 v[16:19], v[156:159], v[196:199], v[16:19]
	v_mfma_f32_16x16x32_bf16 v[4:7], v[148:151], v[204:207], v[4:7]
	v_mfma_f32_16x16x32_bf16 v[0:3], v[156:159], v[204:207], v[0:3]
	s_setprio 0
	s_barrier
	s_add_i32 s79, s79, 2
	s_add_u32 s0, s0, 0x8000
	s_addc_u32 s1, s1, 0
	s_add_u32 s76, s76, 0x8000
	s_addc_u32 s77, s77, 0
	s_cmp_gt_u32 s79, 13

; #define PG8_STAGE(bufoff, gbase, voff) do { _Pragma("unroll") for (int _i = 0; _i < 2; ++_i) \
;         __builtin_amdgcn_global_load_lds((const unsigned*)((const char*)(gbase) + (voff)[_i]), (PG8_LAS unsigned*)(lds + (bufoff) + ldsw + _i * 8192), 16, 0, 0); } while (0)
; #define PG8_WAIT_V(n) asm volatile("s_waitcnt vmcnt(" #n ")" ::: "memory")
; #define PG8_WAIT_L(n) asm volatile("s_waitcnt lgkmcnt(" #n ")" ::: "memory")
; #define PG8_BAR __builtin_amdgcn_s_barrier()
; template <class Epi, class Sched, bool ALIGN_EPI = false, bool SP2 = false, bool TA = true>
; __device__ __forceinline__ void gemm_phase(PG8_LAS unsigned char* lds, const Gemm g, const Sched& S, const Epi& E) {
;     ...
;         const bool has_next = S.next(ui + 1, nxt);
;         const char* nA = has_next ? (const char*)g.A + (size_t)nxt.pm * tstep : cA; const char* nB = has_next ? (const char*)g.Bt + (size_t)nxt.pn * tstep : cB;
; #pragma unroll 1
;         for (int t = 0; t < nt; t += 2) {
;             const bool last = (t == nt - 2);
;             const char* a1 = cA + (size_t)(t + 1) * kstep;
;             const char* a2 = last ? nA : cA + (size_t)(t + 2) * kstep; const char* b2 = last ? nB : cB + (size_t)(t + 2) * kstepB;
;             const char* a3 = a2 + kstep; const char* b3 = b2 + kstepB;
;             if (last && has_next) S.a_ready(nxt);
;             if constexpr (SP2) {
;             PG8_LDB(B0, 0, 0); PG8_LDB(B1, 0, 1); PG8_SCHED; PG8_LDA(At, 0, 0); PG8_STAGE(PG8_SA(1, 1), a1 + hstep, voffA);
;             PG8_WAIT_V(8); PG8_WAIT_L(0); PG8_BAR; PG8_MMA(0, 0, At, B0); PG8_MMA(0, 1, At, B1); PG8_BAR; PG8_SCHED;
;             PG8_LDA(At, 0, 1); PG8_STAGE(PG8_SB(0, 0), b2, voffB); PG8_STAGE(PG8_SB(0, 1), b2 + hstep, voffB); PG8_STAGE(PG8_SA(0, 0), a2, voffA);
;             PG8_WAIT_V(8); PG8_WAIT_L(0); PG8_BAR; PG8_MMA(1, 0, At, B0); PG8_MMA(1, 1, At, B1); PG8_BAR; PG8_SCHED;
;             PG8_LDB(B0, 1, 0); PG8_LDB(B1, 1, 1); PG8_SCHED; PG8_LDA(At, 1, 0); PG8_STAGE(PG8_SA(0, 1), a2 + hstep, voffA);
;             PG8_WAIT_V(8); PG8_WAIT_L(0); PG8_BAR; PG8_MMA(0, 0, At, B0); PG8_MMA(0, 1, At, B1); PG8_BAR; PG8_SCHED;
;             PG8_LDA(At, 1, 1); PG8_STAGE(PG8_SB(1, 0), b3, voffB); PG8_STAGE(PG8_SB(1, 1), b3 + hstep, voffB); PG8_STAGE(PG8_SA(1, 0), a3, voffA);
;             PG8_WAIT_V(8); PG8_WAIT_L(0); PG8_BAR; PG8_MMA(1, 0, At, B0); PG8_MMA(1, 1, At, B1); PG8_BAR; PG8_SCHED;
.LBB0_789:
	s_ashr_i32 s55, s54, 31
	s_lshl_b64 s[56:57], s[54:55], 19
	s_add_u32 s56, s34, s56
	s_addc_u32 s57, s35, s57
	s_and_b64 s[58:59], s[4:5], exec
	s_cselect_b32 s55, s57, s71
	s_cselect_b32 s69, s56, s70
	s_ashr_i32 s53, s52, 31
	s_lshl_b64 s[58:59], s[52:53], 19
	s_add_u32 s58, s19, s58
	s_addc_u32 s59, s21, s59
	s_and_b64 s[80:81], s[4:5], exec
	s_cselect_b32 s53, s59, s73
	s_cselect_b32 s79, s58, s72
	s_add_u32 s70, s70, 0x44000
	s_addc_u32 s71, s71, 0
	s_add_u32 s72, s72, 0x8000
	s_addc_u32 s73, s73, 0
	s_mov_b32 s80, -2
	ds_read_b128 v[136:139], v147
	ds_read_b128 v[152:155], v147 offset:1024
	ds_read_b128 v[156:159], v147 offset:2048
	ds_read_b128 v[160:163], v147 offset:3072
	ds_read_b128 v[164:167], v148
	ds_read_b128 v[168:171], v148 offset:1024
	ds_read_b128 v[172:175], v148 offset:2048
	ds_read_b128 v[176:179], v148 offset:3072
	s_add_u32 s81, s70, 0xfffc4000
	s_addc_u32 s82, s71, -1
	s_cmp_eq_u32 s80, 12
	s_cselect_b32 s83, s55, s82
	s_cselect_b32 s82, s69, s81
	s_cselect_b32 s85, s53, s73
	s_cselect_b32 s84, s79, s72
	v_lshl_add_u64 v[140:141], s[70:71], 0, v[128:129]
	s_add_i32 m0, s23, 0xc000
	ds_read_b128 v[180:183], v149
	ds_read_b128 v[184:187], v149 offset:1024
	ds_read_b128 v[188:191], v149 offset:2048
	ds_read_b128 v[192:195], v149 offset:3072
	ds_read_b128 v[196:199], v149 offset:4096
	ds_read_b128 v[200:203], v149 offset:5120
	ds_read_b128 v[204:207], v149 offset:6144
	ds_read_b128 v[210:213], v149 offset:7168
	global_load_lds_dwordx4 v[140:141], off
	v_lshl_add_u64 v[140:141], v[140:141], 0, s[6:7]
	s_add_i32 m0, s23, 0xe000
	s_nop 0
	global_load_lds_dwordx4 v[140:141], off
	s_waitcnt vmcnt(8)
	s_waitcnt lgkmcnt(0)
	s_barrier
	s_setprio 1
	s_waitcnt lgkmcnt(0)
	v_mfma_f32_16x16x32_bf16 v[124:127], v[136:139], v[180:183], 0
	v_mfma_f32_16x16x32_bf16 v[116:119], v[156:159], v[180:183], 0
	v_mfma_f32_16x16x32_bf16 v[108:111], v[136:139], v[188:191], 0
	v_mfma_f32_16x16x32_bf16 v[100:103], v[156:159], v[188:191], 0
	v_mfma_f32_16x16x32_bf16 v[92:95], v[136:139], v[196:199], 0
	v_mfma_f32_16x16x32_bf16 v[84:87], v[156:159], v[196:199], 0
	v_mfma_f32_16x16x32_bf16 v[76:79], v[136:139], v[204:207], 0
	v_mfma_f32_16x16x32_bf16 v[68:71], v[156:159], v[204:207], 0
	v_mfma_f32_16x16x32_bf16 v[124:127], v[152:155], v[184:187], v[124:127]
	v_mfma_f32_16x16x32_bf16 v[116:119], v[160:163], v[184:187], v[116:119]
	v_mfma_f32_16x16x32_bf16 v[108:111], v[152:155], v[192:195], v[108:111]
	v_mfma_f32_16x16x32_bf16 v[100:103], v[160:163], v[192:195], v[100:103]
	v_mfma_f32_16x16x32_bf16 v[92:95], v[152:155], v[200:203], v[92:95]
	v_mfma_f32_16x16x32_bf16 v[84:87], v[160:163], v[200:203], v[84:87]
	v_mfma_f32_16x16x32_bf16 v[76:79], v[152:155], v[210:213], v[76:79]
	v_mfma_f32_16x16x32_bf16 v[68:71], v[160:163], v[210:213], v[68:71]
	s_setprio 0
	s_setprio 1
	v_mfma_f32_16x16x32_bf16 v[120:123], v[164:167], v[180:183], 0
	v_mfma_f32_16x16x32_bf16 v[112:115], v[172:175], v[180:183], 0
	v_mfma_f32_16x16x32_bf16 v[104:107], v[164:167], v[188:191], 0
	v_mfma_f32_16x16x32_bf16 v[96:99], v[172:175], v[188:191], 0
	v_mfma_f32_16x16x32_bf16 v[88:91], v[164:167], v[196:199], 0
	v_mfma_f32_16x16x32_bf16 v[80:83], v[172:175], v[196:199], 0
	v_mfma_f32_16x16x32_bf16 v[72:75], v[164:167], v[204:207], 0
	v_mfma_f32_16x16x32_bf16 v[64:67], v[172:175], v[204:207], 0
	v_mfma_f32_16x16x32_bf16 v[120:123], v[168:171], v[184:187], v[120:123]
	v_mfma_f32_16x16x32_bf16 v[112:115], v[176:179], v[184:187], v[112:115]
	v_mfma_f32_16x16x32_bf16 v[104:107], v[168:171], v[192:195], v[104:107]
	v_mfma_f32_16x16x32_bf16 v[96:99], v[176:179], v[192:195], v[96:99]
	v_mfma_f32_16x16x32_bf16 v[88:91], v[168:171], v[200:203], v[88:91]
	v_mfma_f32_16x16x32_bf16 v[80:83], v[176:179], v[200:203], v[80:83]
	v_mfma_f32_16x16x32_bf16 v[72:75], v[168:171], v[210:213], v[72:75]
	v_mfma_f32_16x16x32_bf16 v[64:67], v[176:179], v[210:213], v[64:67]
	s_setprio 0
	s_barrier
	s_add_i32 s81, s76, s22
	v_lshl_add_u64 v[140:141], s[84:85], 0, v[128:129]
	s_mov_b32 m0, s81
	ds_read_b128 v[180:183], v149 offset:16384
	ds_read_b128 v[184:187], v149 offset:17408
	ds_read_b128 v[188:191], v149 offset:18432
	ds_read_b128 v[192:195], v149 offset:19456
	ds_read_b128 v[196:199], v149 offset:20480
	ds_read_b128 v[200:203], v149 offset:21504
	ds_read_b128 v[204:207], v149 offset:22528
	ds_read_b128 v[210:213], v149 offset:23552
	global_load_lds_dwordx4 v[140:141], off
	v_lshl_add_u64 v[214:215], v[140:141], 0, s[6:7]
	s_add_i32 m0, s81, 0x2000
	s_add_i32 s81, s77, s22
	global_load_lds_dwordx4 v[214:215], off
	v_lshl_add_u64 v[214:215], v[140:141], 0, s[8:9]
	s_mov_b32 m0, s81
	s_nop 0
	global_load_lds_dwordx4 v[214:215], off
	v_lshl_add_u64 v[214:215], v[140:141], 0, s[10:11]
	s_add_i32 m0, s81, 0x2000
	s_nop 0
	global_load_lds_dwordx4 v[214:215], off
	v_lshl_add_u64 v[214:215], s[82:83], 0, v[128:129]
	s_mov_b32 m0, s23
	v_lshl_add_u64 v[216:217], v[214:215], 0, s[6:7]
	global_load_lds_dwordx4 v[214:215], off
	s_mov_b32 m0, s30
	s_nop 0
	global_load_lds_dwordx4 v[216:217], off
	s_waitcnt vmcnt(8)
	s_waitcnt lgkmcnt(0)
	s_barrier
; #define PG8_STAGE(bufoff, gbase, voff) do { _Pragma("unroll") for (int _i = 0; _i < 2; ++_i) \
;         __builtin_amdgcn_global_load_lds((const unsigned*)((const char*)(gbase) + (voff)[_i]), (PG8_LAS unsigned*)(lds + (bufoff) + ldsw + _i * 8192), 16, 0, 0); } while (0)
; #define PG8_LDA(dst, b, h) do { _Pragma("unroll") for (int m = 0; m < 4; ++m) _Pragma("unroll") for (int k = 0; k < 2; ++k) dst[m][k] = *(const PG8_LAS bf16x8*)(lds + PG8_SA(b, h) + aoff + m * 2048 + k * 1024); } while (0)
; #define PG8_LDB(dst, b, h) do { _Pragma("unroll") for (int n = 0; n < 2; ++n) _Pragma("unroll") for (int k = 0; k < 2; ++k) dst[n][k] = *(const PG8_LAS bf16x8*)(lds + PG8_SB(b, h) + boff + n * 2048 + k * 1024); } while (0)
; #define PG8_MMA(ai, bj, At, Bt) do { __builtin_amdgcn_s_setprio(1); _Pragma("unroll") for (int m = 0; m < 4; ++m) _Pragma("unroll") for (int n = 0; n < 2; ++n) _Pragma("unroll") for (int k = 0; k < 2; ++k) \
;         acc[ai][bj][m][n] = __builtin_amdgcn_mfma_f32_16x16x32_bf16(Bt[n][k], At[m][k], acc[ai][bj][m][n], 0, 0, 0); __builtin_amdgcn_s_setprio(0); } while (0)
; #define PG8_BAR __builtin_amdgcn_s_barrier()
; template <class Epi, class Sched, bool ALIGN_EPI = false, bool SP2 = false, bool TA = true>
; __device__ __forceinline__ void gemm_phase(PG8_LAS unsigned char* lds, const Gemm g, const Sched& S, const Epi& E) {
;     ...
;             PG8_LDB(B0, 0, 0); PG8_LDB(B1, 0, 1); PG8_SCHED; PG8_LDA(At, 0, 0); PG8_STAGE(PG8_SA(1, 1), a1 + hstep, voffA);
;             PG8_WAIT_V(8); PG8_WAIT_L(0); PG8_BAR; PG8_MMA(0, 0, At, B0); PG8_MMA(0, 1, At, B1); PG8_BAR; PG8_SCHED;
;             PG8_LDA(At, 0, 1); PG8_STAGE(PG8_SB(0, 0), b2, voffB); PG8_STAGE(PG8_SB(0, 1), b2 + hstep, voffB); PG8_STAGE(PG8_SA(0, 0), a2, voffA);
;             PG8_WAIT_V(8); PG8_WAIT_L(0); PG8_BAR; PG8_MMA(1, 0, At, B0); PG8_MMA(1, 1, At, B1); PG8_BAR; PG8_SCHED;
;             PG8_LDB(B0, 1, 0); PG8_LDB(B1, 1, 1); PG8_SCHED; PG8_LDA(At, 1, 0); PG8_STAGE(PG8_SA(0, 1), a2 + hstep, voffA);
;             PG8_WAIT_V(8); PG8_WAIT_L(0); PG8_BAR; PG8_MMA(0, 0, At, B0); PG8_MMA(0, 1, At, B1); PG8_BAR; PG8_SCHED;
;             PG8_LDA(At, 1, 1); PG8_STAGE(PG8_SB(1, 0), b3, voffB); PG8_STAGE(PG8_SB(1, 1), b3 + hstep, voffB); PG8_STAGE(PG8_SA(1, 0), a3, voffA);
;             PG8_WAIT_V(8); PG8_WAIT_L(0); PG8_BAR; PG8_MMA(1, 0, At, B0); PG8_MMA(1, 1, At, B1); PG8_BAR; PG8_SCHED;
	s_setprio 1
	s_waitcnt lgkmcnt(0)
	v_mfma_f32_16x16x32_bf16 v[60:63], v[136:139], v[180:183], 0
	v_mfma_f32_16x16x32_bf16 v[52:55], v[156:159], v[180:183], 0
	v_mfma_f32_16x16x32_bf16 v[44:47], v[136:139], v[188:191], 0
	v_mfma_f32_16x16x32_bf16 v[36:39], v[156:159], v[188:191], 0
	v_mfma_f32_16x16x32_bf16 v[28:31], v[136:139], v[196:199], 0
	v_mfma_f32_16x16x32_bf16 v[20:23], v[156:159], v[196:199], 0
	v_mfma_f32_16x16x32_bf16 v[12:15], v[136:139], v[204:207], 0
	v_mfma_f32_16x16x32_bf16 v[4:7], v[156:159], v[204:207], 0
	v_mfma_f32_16x16x32_bf16 v[60:63], v[152:155], v[184:187], v[60:63]
	v_mfma_f32_16x16x32_bf16 v[52:55], v[160:163], v[184:187], v[52:55]
	v_mfma_f32_16x16x32_bf16 v[44:47], v[152:155], v[192:195], v[44:47]
	v_mfma_f32_16x16x32_bf16 v[36:39], v[160:163], v[192:195], v[36:39]
	v_mfma_f32_16x16x32_bf16 v[28:31], v[152:155], v[200:203], v[28:31]
	v_mfma_f32_16x16x32_bf16 v[20:23], v[160:163], v[200:203], v[20:23]
	v_mfma_f32_16x16x32_bf16 v[12:15], v[152:155], v[210:213], v[12:15]
	v_mfma_f32_16x16x32_bf16 v[4:7], v[160:163], v[210:213], v[4:7]
	s_setprio 0
	s_setprio 1
	v_mfma_f32_16x16x32_bf16 v[56:59], v[164:167], v[180:183], 0
	v_mfma_f32_16x16x32_bf16 v[48:51], v[172:175], v[180:183], 0
	v_mfma_f32_16x16x32_bf16 v[40:43], v[164:167], v[188:191], 0
	v_mfma_f32_16x16x32_bf16 v[32:35], v[172:175], v[188:191], 0
	v_mfma_f32_16x16x32_bf16 v[24:27], v[164:167], v[196:199], 0
	v_mfma_f32_16x16x32_bf16 v[16:19], v[172:175], v[196:199], 0
	v_mfma_f32_16x16x32_bf16 v[8:11], v[164:167], v[204:207], 0
	v_mfma_f32_16x16x32_bf16 v[0:3], v[172:175], v[204:207], 0
	v_mfma_f32_16x16x32_bf16 v[56:59], v[168:171], v[184:187], v[56:59]
	v_mfma_f32_16x16x32_bf16 v[48:51], v[176:179], v[184:187], v[48:51]
	v_mfma_f32_16x16x32_bf16 v[40:43], v[168:171], v[192:195], v[40:43]
	v_mfma_f32_16x16x32_bf16 v[32:35], v[176:179], v[192:195], v[32:35]
	v_mfma_f32_16x16x32_bf16 v[24:27], v[168:171], v[200:203], v[24:27]
	v_mfma_f32_16x16x32_bf16 v[16:19], v[176:179], v[200:203], v[16:19]
	v_mfma_f32_16x16x32_bf16 v[8:11], v[168:171], v[210:213], v[8:11]
	v_mfma_f32_16x16x32_bf16 v[0:3], v[176:179], v[210:213], v[0:3]
	s_setprio 0
	s_barrier
	s_add_i32 s81, 0, 0x18000
	v_add_u32_e32 v130, s81, v144
	s_add_i32 s82, 0, 0x1c000
	ds_read_b128 v[136:139], v130
	ds_read_b128 v[152:155], v130 offset:1024
	ds_read_b128 v[156:159], v130 offset:2048
	ds_read_b128 v[160:163], v130 offset:3072
	v_add_u32_e32 v130, s82, v144
	ds_read_b128 v[164:167], v130
	ds_read_b128 v[168:171], v130 offset:1024
	ds_read_b128 v[172:175], v130 offset:2048
	ds_read_b128 v[176:179], v130 offset:3072
	s_mov_b32 m0, s31
	v_lshl_add_u64 v[216:217], v[214:215], 0, s[8:9]
	ds_read_b128 v[180:183], v149 offset:32768
	ds_read_b128 v[184:187], v149 offset:33792
	ds_read_b128 v[188:191], v149 offset:34816
	ds_read_b128 v[192:195], v149 offset:35840
	ds_read_b128 v[196:199], v149 offset:36864
	ds_read_b128 v[200:203], v149 offset:37888
	ds_read_b128 v[204:207], v149 offset:38912
	ds_read_b128 v[210:213], v149 offset:39936
	global_load_lds_dwordx4 v[216:217], off
	v_lshl_add_u64 v[216:217], v[214:215], 0, s[10:11]
	s_mov_b32 m0, s33
	s_nop 0
	global_load_lds_dwordx4 v[216:217], off
	s_waitcnt vmcnt(8)
	s_waitcnt lgkmcnt(0)
	s_barrier
	s_setprio 1
	s_waitcnt lgkmcnt(0)
	v_mfma_f32_16x16x32_bf16 v[124:127], v[136:139], v[180:183], v[124:127]
	v_mfma_f32_16x16x32_bf16 v[116:119], v[156:159], v[180:183], v[116:119]
	v_mfma_f32_16x16x32_bf16 v[108:111], v[136:139], v[188:191], v[108:111]
	v_mfma_f32_16x16x32_bf16 v[100:103], v[156:159], v[188:191], v[100:103]
	v_mfma_f32_16x16x32_bf16 v[92:95], v[136:139], v[196:199], v[92:95]
	v_mfma_f32_16x16x32_bf16 v[84:87], v[156:159], v[196:199], v[84:87]
	v_mfma_f32_16x16x32_bf16 v[76:79], v[136:139], v[204:207], v[76:79]
	v_mfma_f32_16x16x32_bf16 v[68:71], v[156:159], v[204:207], v[68:71]
	v_mfma_f32_16x16x32_bf16 v[124:127], v[152:155], v[184:187], v[124:127]
	v_mfma_f32_16x16x32_bf16 v[116:119], v[160:163], v[184:187], v[116:119]
	v_mfma_f32_16x16x32_bf16 v[108:111], v[152:155], v[192:195], v[108:111]
	v_mfma_f32_16x16x32_bf16 v[100:103], v[160:163], v[192:195], v[100:103]
	v_mfma_f32_16x16x32_bf16 v[92:95], v[152:155], v[200:203], v[92:95]
	v_mfma_f32_16x16x32_bf16 v[84:87], v[160:163], v[200:203], v[84:87]
	v_mfma_f32_16x16x32_bf16 v[76:79], v[152:155], v[210:213], v[76:79]
	v_mfma_f32_16x16x32_bf16 v[68:71], v[160:163], v[210:213], v[68:71]
	s_setprio 0
	s_setprio 1
	v_mfma_f32_16x16x32_bf16 v[120:123], v[164:167], v[180:183], v[120:123]
	v_mfma_f32_16x16x32_bf16 v[112:115], v[172:175], v[180:183], v[112:115]
	v_mfma_f32_16x16x32_bf16 v[104:107], v[164:167], v[188:191], v[104:107]
	v_mfma_f32_16x16x32_bf16 v[96:99], v[172:175], v[188:191], v[96:99]
	v_mfma_f32_16x16x32_bf16 v[88:91], v[164:167], v[196:199], v[88:91]
	v_mfma_f32_16x16x32_bf16 v[80:83], v[172:175], v[196:199], v[80:83]
	v_mfma_f32_16x16x32_bf16 v[72:75], v[164:167], v[204:207], v[72:75]
	v_mfma_f32_16x16x32_bf16 v[64:67], v[172:175], v[204:207], v[64:67]
	v_mfma_f32_16x16x32_bf16 v[120:123], v[168:171], v[184:187], v[120:123]
	v_mfma_f32_16x16x32_bf16 v[112:115], v[176:179], v[184:187], v[112:115]
	v_mfma_f32_16x16x32_bf16 v[104:107], v[168:171], v[192:195], v[104:107]
	v_mfma_f32_16x16x32_bf16 v[96:99], v[176:179], v[192:195], v[96:99]
	v_mfma_f32_16x16x32_bf16 v[88:91], v[168:171], v[200:203], v[88:91]
	v_mfma_f32_16x16x32_bf16 v[80:83], v[176:179], v[200:203], v[80:83]
	v_mfma_f32_16x16x32_bf16 v[72:75], v[168:171], v[210:213], v[72:75]
	v_mfma_f32_16x16x32_bf16 v[64:67], v[176:179], v[210:213], v[64:67]
	s_setprio 0
	s_barrier
; #define PG8_STAGE(bufoff, gbase, voff) do { _Pragma("unroll") for (int _i = 0; _i < 2; ++_i) \
;         __builtin_amdgcn_global_load_lds((const unsigned*)((const char*)(gbase) + (voff)[_i]), (PG8_LAS unsigned*)(lds + (bufoff) + ldsw + _i * 8192), 16, 0, 0); } while (0)
; #define PG8_LDA(dst, b, h) do { _Pragma("unroll") for (int m = 0; m < 4; ++m) _Pragma("unroll") for (int k = 0; k < 2; ++k) dst[m][k] = *(const PG8_LAS bf16x8*)(lds + PG8_SA(b, h) + aoff + m * 2048 + k * 1024); } while (0)
; #define PG8_LDB(dst, b, h) do { _Pragma("unroll") for (int n = 0; n < 2; ++n) _Pragma("unroll") for (int k = 0; k < 2; ++k) dst[n][k] = *(const PG8_LAS bf16x8*)(lds + PG8_SB(b, h) + boff + n * 2048 + k * 1024); } while (0)
; #define PG8_MMA(ai, bj, At, Bt) do { __builtin_amdgcn_s_setprio(1); _Pragma("unroll") for (int m = 0; m < 4; ++m) _Pragma("unroll") for (int n = 0; n < 2; ++n) _Pragma("unroll") for (int k = 0; k < 2; ++k) \
;         acc[ai][bj][m][n] = __builtin_amdgcn_mfma_f32_16x16x32_bf16(Bt[n][k], At[m][k], acc[ai][bj][m][n], 0, 0, 0); __builtin_amdgcn_s_setprio(0); } while (0)
; #define PG8_BAR __builtin_amdgcn_s_barrier()
; template <class Epi, class Sched, bool ALIGN_EPI = false, bool SP2 = false, bool TA = true>
; __device__ __forceinline__ void gemm_phase(PG8_LAS unsigned char* lds, const Gemm g, const Sched& S, const Epi& E) {
;     ...
;             PG8_LDB(B0, 0, 0); PG8_LDB(B1, 0, 1); PG8_SCHED; PG8_LDA(At, 0, 0); PG8_STAGE(PG8_SA(1, 1), a1 + hstep, voffA);
;             PG8_WAIT_V(8); PG8_WAIT_L(0); PG8_BAR; PG8_MMA(0, 0, At, B0); PG8_MMA(0, 1, At, B1); PG8_BAR; PG8_SCHED;
;             PG8_LDA(At, 0, 1); PG8_STAGE(PG8_SB(0, 0), b2, voffB); PG8_STAGE(PG8_SB(0, 1), b2 + hstep, voffB); PG8_STAGE(PG8_SA(0, 0), a2, voffA);
;             PG8_WAIT_V(8); PG8_WAIT_L(0); PG8_BAR; PG8_MMA(1, 0, At, B0); PG8_MMA(1, 1, At, B1); PG8_BAR; PG8_SCHED;
;             PG8_LDB(B0, 1, 0); PG8_LDB(B1, 1, 1); PG8_SCHED; PG8_LDA(At, 1, 0); PG8_STAGE(PG8_SA(0, 1), a2 + hstep, voffA);
;             PG8_WAIT_V(8); PG8_WAIT_L(0); PG8_BAR; PG8_MMA(0, 0, At, B0); PG8_MMA(0, 1, At, B1); PG8_BAR; PG8_SCHED;
;             PG8_LDA(At, 1, 1); PG8_STAGE(PG8_SB(1, 0), b3, voffB); PG8_STAGE(PG8_SB(1, 1), b3 + hstep, voffB); PG8_STAGE(PG8_SA(1, 0), a3, voffA);
;             PG8_WAIT_V(8); PG8_WAIT_L(0); PG8_BAR; PG8_MMA(1, 0, At, B0); PG8_MMA(1, 1, At, B1); PG8_BAR; PG8_SCHED;
	s_add_i32 s81, s81, s22
	v_lshl_add_u64 v[216:217], v[140:141], 0, s[16:17]
	s_mov_b32 m0, s81
	ds_read_b128 v[180:183], v149 offset:49152
	ds_read_b128 v[184:187], v149 offset:50176
	ds_read_b128 v[188:191], v149 offset:51200
	ds_read_b128 v[192:195], v149 offset:52224
	ds_read_b128 v[196:199], v149 offset:53248
	ds_read_b128 v[200:203], v149 offset:54272
	ds_read_b128 v[204:207], v149 offset:55296
	ds_read_b128 v[210:213], v149 offset:56320
	global_load_lds_dwordx4 v[216:217], off
	v_lshl_add_u64 v[216:217], v[140:141], 0, s[44:45]
	s_add_i32 m0, s81, 0x2000
	s_add_i32 s81, s82, s22
	global_load_lds_dwordx4 v[216:217], off
	v_lshl_add_u64 v[216:217], v[140:141], 0, s[46:47]
	s_mov_b32 m0, s81
	v_lshl_add_u64 v[140:141], v[140:141], 0, s[48:49]
	global_load_lds_dwordx4 v[216:217], off
	s_add_i32 m0, s81, 0x2000
	s_nop 0
	global_load_lds_dwordx4 v[140:141], off
	v_lshl_add_u64 v[140:141], v[214:215], 0, s[16:17]
	s_mov_b32 m0, s36
	s_nop 0
	global_load_lds_dwordx4 v[140:141], off
	v_lshl_add_u64 v[140:141], v[214:215], 0, s[44:45]
	s_mov_b32 m0, s37
	s_nop 0
	global_load_lds_dwordx4 v[140:141], off
	s_waitcnt vmcnt(8)
	s_waitcnt lgkmcnt(0)
	s_barrier
	s_setprio 1
	s_waitcnt lgkmcnt(0)
	v_mfma_f32_16x16x32_bf16 v[60:63], v[136:139], v[180:183], v[60:63]
	v_mfma_f32_16x16x32_bf16 v[52:55], v[156:159], v[180:183], v[52:55]
	v_mfma_f32_16x16x32_bf16 v[44:47], v[136:139], v[188:191], v[44:47]
	v_mfma_f32_16x16x32_bf16 v[36:39], v[156:159], v[188:191], v[36:39]
	v_mfma_f32_16x16x32_bf16 v[28:31], v[136:139], v[196:199], v[28:31]
	v_mfma_f32_16x16x32_bf16 v[20:23], v[156:159], v[196:199], v[20:23]
	v_mfma_f32_16x16x32_bf16 v[12:15], v[136:139], v[204:207], v[12:15]
	v_mfma_f32_16x16x32_bf16 v[4:7], v[156:159], v[204:207], v[4:7]
	v_mfma_f32_16x16x32_bf16 v[60:63], v[152:155], v[184:187], v[60:63]
	v_mfma_f32_16x16x32_bf16 v[52:55], v[160:163], v[184:187], v[52:55]
	v_mfma_f32_16x16x32_bf16 v[44:47], v[152:155], v[192:195], v[44:47]
	v_mfma_f32_16x16x32_bf16 v[36:39], v[160:163], v[192:195], v[36:39]
	v_mfma_f32_16x16x32_bf16 v[28:31], v[152:155], v[200:203], v[28:31]
	v_mfma_f32_16x16x32_bf16 v[20:23], v[160:163], v[200:203], v[20:23]
	v_mfma_f32_16x16x32_bf16 v[12:15], v[152:155], v[210:213], v[12:15]
	v_mfma_f32_16x16x32_bf16 v[4:7], v[160:163], v[210:213], v[4:7]
	s_setprio 0
	s_setprio 1
	v_mfma_f32_16x16x32_bf16 v[56:59], v[164:167], v[180:183], v[56:59]
	v_mfma_f32_16x16x32_bf16 v[48:51], v[172:175], v[180:183], v[48:51]
	v_mfma_f32_16x16x32_bf16 v[40:43], v[164:167], v[188:191], v[40:43]
	v_mfma_f32_16x16x32_bf16 v[32:35], v[172:175], v[188:191], v[32:35]
	v_mfma_f32_16x16x32_bf16 v[24:27], v[164:167], v[196:199], v[24:27]
	v_mfma_f32_16x16x32_bf16 v[16:19], v[172:175], v[196:199], v[16:19]
	v_mfma_f32_16x16x32_bf16 v[8:11], v[164:167], v[204:207], v[8:11]
	v_mfma_f32_16x16x32_bf16 v[0:3], v[172:175], v[204:207], v[0:3]
	v_mfma_f32_16x16x32_bf16 v[56:59], v[168:171], v[184:187], v[56:59]
	v_mfma_f32_16x16x32_bf16 v[48:51], v[176:179], v[184:187], v[48:51]
	v_mfma_f32_16x16x32_bf16 v[40:43], v[168:171], v[192:195], v[40:43]
	v_mfma_f32_16x16x32_bf16 v[32:35], v[176:179], v[192:195], v[32:35]
	v_mfma_f32_16x16x32_bf16 v[24:27], v[168:171], v[200:203], v[24:27]
	v_mfma_f32_16x16x32_bf16 v[16:19], v[176:179], v[200:203], v[16:19]
	v_mfma_f32_16x16x32_bf16 v[8:11], v[168:171], v[210:213], v[8:11]
	v_mfma_f32_16x16x32_bf16 v[0:3], v[176:179], v[210:213], v[0:3]
	s_setprio 0
	s_barrier
	s_add_i32 s80, s80, 2
	s_add_u32 s70, s70, 0x8000
	s_addc_u32 s71, s71, 0
	s_add_u32 s72, s72, 0x8000
	s_addc_u32 s73, s73, 0
	s_cmp_gt_u32 s80, 13

; #define PG8_STAGE(bufoff, gbase, voff) do { _Pragma("unroll") for (int _i = 0; _i < 2; ++_i) \
;         __builtin_amdgcn_global_load_lds((const unsigned*)((const char*)(gbase) + (voff)[_i]), (PG8_LAS unsigned*)(lds + (bufoff) + ldsw + _i * 8192), 16, 0, 0); } while (0)
; #define PG8_WAIT_V(n) asm volatile("s_waitcnt vmcnt(" #n ")" ::: "memory")
; #define PG8_WAIT_L(n) asm volatile("s_waitcnt lgkmcnt(" #n ")" ::: "memory")
; #define PG8_BAR __builtin_amdgcn_s_barrier()
; template <class Epi, class Sched, bool ALIGN_EPI = false, bool SP2 = false, bool TA = true>
; __device__ __forceinline__ void gemm_phase(PG8_LAS unsigned char* lds, const Gemm g, const Sched& S, const Epi& E) {
;     ...
;         const bool has_next = S.next(ui + 1, nxt);
;         const char* nA = has_next ? (const char*)g.A + (size_t)nxt.pm * tstep : cA; const char* nB = has_next ? (const char*)g.Bt + (size_t)nxt.pn * tstep : cB;
; #pragma unroll 1
;         for (int t = 0; t < nt; t += 2) {
;             const bool last = (t == nt - 2);
;             const char* a1 = cA + (size_t)(t + 1) * kstep;
;             const char* a2 = last ? nA : cA + (size_t)(t + 2) * kstep; const char* b2 = last ? nB : cB + (size_t)(t + 2) * kstepB;
;             const char* a3 = a2 + kstep; const char* b3 = b2 + kstepB;
;             if (last && has_next) S.a_ready(nxt);
;             if constexpr (SP2) {
;             PG8_LDB(B0, 0, 0); PG8_LDB(B1, 0, 1); PG8_SCHED; PG8_LDA(At, 0, 0); PG8_STAGE(PG8_SA(1, 1), a1 + hstep, voffA);
;             PG8_WAIT_V(8); PG8_WAIT_L(0); PG8_BAR; PG8_MMA(0, 0, At, B0); PG8_MMA(0, 1, At, B1); PG8_BAR; PG8_SCHED;
;             PG8_LDA(At, 0, 1); PG8_STAGE(PG8_SB(0, 0), b2, voffB); PG8_STAGE(PG8_SB(0, 1), b2 + hstep, voffB); PG8_STAGE(PG8_SA(0, 0), a2, voffA);
;             PG8_WAIT_V(8); PG8_WAIT_L(0); PG8_BAR; PG8_MMA(1, 0, At, B0); PG8_MMA(1, 1, At, B1); PG8_BAR; PG8_SCHED;
;             PG8_LDB(B0, 1, 0); PG8_LDB(B1, 1, 1); PG8_SCHED; PG8_LDA(At, 1, 0); PG8_STAGE(PG8_SA(0, 1), a2 + hstep, voffA);
;             PG8_WAIT_V(8); PG8_WAIT_L(0); PG8_BAR; PG8_MMA(0, 0, At, B0); PG8_MMA(0, 1, At, B1); PG8_BAR; PG8_SCHED;
;             PG8_LDA(At, 1, 1); PG8_STAGE(PG8_SB(1, 0), b3, voffB); PG8_STAGE(PG8_SB(1, 1), b3 + hstep, voffB); PG8_STAGE(PG8_SA(1, 0), a3, voffA);
;             PG8_WAIT_V(8); PG8_WAIT_L(0); PG8_BAR; PG8_MMA(1, 0, At, B0); PG8_MMA(1, 1, At, B1); PG8_BAR; PG8_SCHED;
.LBB0_876:
	s_add_u32 s58, s58, 0xb4000
	s_addc_u32 s59, s59, 0
	s_add_u32 s60, s60, 0x8000
	s_addc_u32 s61, s61, 0
	s_mov_b32 s69, -2
	s_waitcnt lgkmcnt(0)
	ds_read_b128 v[128:131], v150
	ds_read_b128 v[142:145], v150 offset:1024
	ds_read_b128 v[154:157], v150 offset:2048
	ds_read_b128 v[158:161], v150 offset:3072
	ds_read_b128 v[162:165], v151
	ds_read_b128 v[166:169], v151 offset:1024
	ds_read_b128 v[170:173], v151 offset:2048
	ds_read_b128 v[174:177], v151 offset:3072
	s_add_u32 s70, s58, 0xfff54000
	s_addc_u32 s71, s59, -1
	s_cmp_eq_u32 s69, 40
	s_cselect_b32 s71, s1, s71
	s_cselect_b32 s70, s0, s70
	s_cselect_b32 s73, s57, s61
	s_cselect_b32 s72, s56, s60
	v_lshl_add_u64 v[132:133], s[58:59], 0, v[134:135]
	s_add_i32 m0, s30, 0xc000
	ds_read_b128 v[178:181], v152
	ds_read_b128 v[182:185], v152 offset:1024
	ds_read_b128 v[186:189], v152 offset:2048
	ds_read_b128 v[190:193], v152 offset:3072
	ds_read_b128 v[194:197], v152 offset:4096
	ds_read_b128 v[198:201], v152 offset:5120
	ds_read_b128 v[202:205], v152 offset:6144
	ds_read_b128 v[210:213], v152 offset:7168
	global_load_lds_dwordx4 v[132:133], off
	v_lshl_add_u64 v[132:133], v[132:133], 0, s[10:11]
	s_add_i32 m0, s30, 0xe000
	s_nop 0
	global_load_lds_dwordx4 v[132:133], off
	s_waitcnt vmcnt(8)
	s_waitcnt lgkmcnt(0)
	s_barrier
	s_setprio 1
	s_waitcnt lgkmcnt(0)
	v_mfma_f32_16x16x32_bf16 v[124:127], v[128:131], v[178:181], 0
	v_mfma_f32_16x16x32_bf16 v[120:123], v[154:157], v[178:181], 0
	v_mfma_f32_16x16x32_bf16 v[108:111], v[128:131], v[186:189], 0
	v_mfma_f32_16x16x32_bf16 v[104:107], v[154:157], v[186:189], 0
	v_mfma_f32_16x16x32_bf16 v[92:95], v[128:131], v[194:197], 0
	v_mfma_f32_16x16x32_bf16 v[88:91], v[154:157], v[194:197], 0
	v_mfma_f32_16x16x32_bf16 v[76:79], v[128:131], v[202:205], 0
	v_mfma_f32_16x16x32_bf16 v[72:75], v[154:157], v[202:205], 0
	v_mfma_f32_16x16x32_bf16 v[124:127], v[142:145], v[182:185], v[124:127]
	v_mfma_f32_16x16x32_bf16 v[120:123], v[158:161], v[182:185], v[120:123]
	v_mfma_f32_16x16x32_bf16 v[108:111], v[142:145], v[190:193], v[108:111]
	v_mfma_f32_16x16x32_bf16 v[104:107], v[158:161], v[190:193], v[104:107]
	v_mfma_f32_16x16x32_bf16 v[92:95], v[142:145], v[198:201], v[92:95]
	v_mfma_f32_16x16x32_bf16 v[88:91], v[158:161], v[198:201], v[88:91]
	v_mfma_f32_16x16x32_bf16 v[76:79], v[142:145], v[210:213], v[76:79]
	v_mfma_f32_16x16x32_bf16 v[72:75], v[158:161], v[210:213], v[72:75]
	s_setprio 0
	s_setprio 1
	v_mfma_f32_16x16x32_bf16 v[116:119], v[162:165], v[178:181], 0
	v_mfma_f32_16x16x32_bf16 v[112:115], v[170:173], v[178:181], 0
	v_mfma_f32_16x16x32_bf16 v[100:103], v[162:165], v[186:189], 0
	v_mfma_f32_16x16x32_bf16 v[96:99], v[170:173], v[186:189], 0
	v_mfma_f32_16x16x32_bf16 v[84:87], v[162:165], v[194:197], 0
	v_mfma_f32_16x16x32_bf16 v[80:83], v[170:173], v[194:197], 0
	v_mfma_f32_16x16x32_bf16 v[68:71], v[162:165], v[202:205], 0
	v_mfma_f32_16x16x32_bf16 v[64:67], v[170:173], v[202:205], 0
	v_mfma_f32_16x16x32_bf16 v[116:119], v[166:169], v[182:185], v[116:119]
	v_mfma_f32_16x16x32_bf16 v[112:115], v[174:177], v[182:185], v[112:115]
	v_mfma_f32_16x16x32_bf16 v[100:103], v[166:169], v[190:193], v[100:103]
	v_mfma_f32_16x16x32_bf16 v[96:99], v[174:177], v[190:193], v[96:99]
	v_mfma_f32_16x16x32_bf16 v[84:87], v[166:169], v[198:201], v[84:87]
	v_mfma_f32_16x16x32_bf16 v[80:83], v[174:177], v[198:201], v[80:83]
	v_mfma_f32_16x16x32_bf16 v[68:71], v[166:169], v[210:213], v[68:71]
	v_mfma_f32_16x16x32_bf16 v[64:67], v[174:177], v[210:213], v[64:67]
	s_setprio 0
	s_barrier
	v_lshl_add_u64 v[132:133], s[72:73], 0, v[134:135]
	s_add_i32 s72, s79, s23
	s_mov_b32 m0, s72
	ds_read_b128 v[178:181], v152 offset:16384
	ds_read_b128 v[182:185], v152 offset:17408
	ds_read_b128 v[186:189], v152 offset:18432
	ds_read_b128 v[190:193], v152 offset:19456
	ds_read_b128 v[194:197], v152 offset:20480
	ds_read_b128 v[198:201], v152 offset:21504
	ds_read_b128 v[202:205], v152 offset:22528
	ds_read_b128 v[210:213], v152 offset:23552
	global_load_lds_dwordx4 v[132:133], off
	v_lshl_add_u64 v[206:207], v[132:133], 0, s[10:11]
	s_add_i32 m0, s72, 0x2000
	s_add_i32 s72, s80, s23
	global_load_lds_dwordx4 v[206:207], off
	v_lshl_add_u64 v[206:207], v[132:133], 0, s[12:13]
	s_mov_b32 m0, s72
	s_nop 0
	global_load_lds_dwordx4 v[206:207], off
	v_lshl_add_u64 v[206:207], v[132:133], 0, s[14:15]
	s_add_i32 m0, s72, 0x2000
	s_nop 0
	global_load_lds_dwordx4 v[206:207], off
	v_lshl_add_u64 v[206:207], s[70:71], 0, v[134:135]
	s_mov_b32 m0, s30
	v_lshl_add_u64 v[214:215], v[206:207], 0, s[10:11]
	global_load_lds_dwordx4 v[206:207], off
	s_mov_b32 m0, s31
	s_nop 0
	global_load_lds_dwordx4 v[214:215], off
	s_waitcnt vmcnt(8)
	s_waitcnt lgkmcnt(0)
	s_barrier
; #define PG8_STAGE(bufoff, gbase, voff) do { _Pragma("unroll") for (int _i = 0; _i < 2; ++_i) \
;         __builtin_amdgcn_global_load_lds((const unsigned*)((const char*)(gbase) + (voff)[_i]), (PG8_LAS unsigned*)(lds + (bufoff) + ldsw + _i * 8192), 16, 0, 0); } while (0)
; #define PG8_LDA(dst, b, h) do { _Pragma("unroll") for (int m = 0; m < 4; ++m) _Pragma("unroll") for (int k = 0; k < 2; ++k) dst[m][k] = *(const PG8_LAS bf16x8*)(lds + PG8_SA(b, h) + aoff + m * 2048 + k * 1024); } while (0)
; #define PG8_LDB(dst, b, h) do { _Pragma("unroll") for (int n = 0; n < 2; ++n) _Pragma("unroll") for (int k = 0; k < 2; ++k) dst[n][k] = *(const PG8_LAS bf16x8*)(lds + PG8_SB(b, h) + boff + n * 2048 + k * 1024); } while (0)
; #define PG8_MMA(ai, bj, At, Bt) do { __builtin_amdgcn_s_setprio(1); _Pragma("unroll") for (int m = 0; m < 4; ++m) _Pragma("unroll") for (int n = 0; n < 2; ++n) _Pragma("unroll") for (int k = 0; k < 2; ++k) \
;         acc[ai][bj][m][n] = __builtin_amdgcn_mfma_f32_16x16x32_bf16(Bt[n][k], At[m][k], acc[ai][bj][m][n], 0, 0, 0); __builtin_amdgcn_s_setprio(0); } while (0)
; #define PG8_BAR __builtin_amdgcn_s_barrier()
; template <class Epi, class Sched, bool ALIGN_EPI = false, bool SP2 = false, bool TA = true>
; __device__ __forceinline__ void gemm_phase(PG8_LAS unsigned char* lds, const Gemm g, const Sched& S, const Epi& E) {
;     ...
;             PG8_LDB(B0, 0, 0); PG8_LDB(B1, 0, 1); PG8_SCHED; PG8_LDA(At, 0, 0); PG8_STAGE(PG8_SA(1, 1), a1 + hstep, voffA);
;             PG8_WAIT_V(8); PG8_WAIT_L(0); PG8_BAR; PG8_MMA(0, 0, At, B0); PG8_MMA(0, 1, At, B1); PG8_BAR; PG8_SCHED;
;             PG8_LDA(At, 0, 1); PG8_STAGE(PG8_SB(0, 0), b2, voffB); PG8_STAGE(PG8_SB(0, 1), b2 + hstep, voffB); PG8_STAGE(PG8_SA(0, 0), a2, voffA);
;             PG8_WAIT_V(8); PG8_WAIT_L(0); PG8_BAR; PG8_MMA(1, 0, At, B0); PG8_MMA(1, 1, At, B1); PG8_BAR; PG8_SCHED;
;             PG8_LDB(B0, 1, 0); PG8_LDB(B1, 1, 1); PG8_SCHED; PG8_LDA(At, 1, 0); PG8_STAGE(PG8_SA(0, 1), a2 + hstep, voffA);
;             PG8_WAIT_V(8); PG8_WAIT_L(0); PG8_BAR; PG8_MMA(0, 0, At, B0); PG8_MMA(0, 1, At, B1); PG8_BAR; PG8_SCHED;
;             PG8_LDA(At, 1, 1); PG8_STAGE(PG8_SB(1, 0), b3, voffB); PG8_STAGE(PG8_SB(1, 1), b3 + hstep, voffB); PG8_STAGE(PG8_SA(1, 0), a3, voffA);
;             PG8_WAIT_V(8); PG8_WAIT_L(0); PG8_BAR; PG8_MMA(1, 0, At, B0); PG8_MMA(1, 1, At, B1); PG8_BAR; PG8_SCHED;
	s_setprio 1
	s_waitcnt lgkmcnt(0)
	v_mfma_f32_16x16x32_bf16 v[60:63], v[128:131], v[178:181], 0
	v_mfma_f32_16x16x32_bf16 v[56:59], v[154:157], v[178:181], 0
	v_mfma_f32_16x16x32_bf16 v[44:47], v[128:131], v[186:189], 0
	v_mfma_f32_16x16x32_bf16 v[40:43], v[154:157], v[186:189], 0
	v_mfma_f32_16x16x32_bf16 v[28:31], v[128:131], v[194:197], 0
	v_mfma_f32_16x16x32_bf16 v[24:27], v[154:157], v[194:197], 0
	v_mfma_f32_16x16x32_bf16 v[12:15], v[128:131], v[202:205], 0
	v_mfma_f32_16x16x32_bf16 v[8:11], v[154:157], v[202:205], 0
	v_mfma_f32_16x16x32_bf16 v[60:63], v[142:145], v[182:185], v[60:63]
	v_mfma_f32_16x16x32_bf16 v[56:59], v[158:161], v[182:185], v[56:59]
	v_mfma_f32_16x16x32_bf16 v[44:47], v[142:145], v[190:193], v[44:47]
	v_mfma_f32_16x16x32_bf16 v[40:43], v[158:161], v[190:193], v[40:43]
	v_mfma_f32_16x16x32_bf16 v[28:31], v[142:145], v[198:201], v[28:31]
	v_mfma_f32_16x16x32_bf16 v[24:27], v[158:161], v[198:201], v[24:27]
	v_mfma_f32_16x16x32_bf16 v[12:15], v[142:145], v[210:213], v[12:15]
	v_mfma_f32_16x16x32_bf16 v[8:11], v[158:161], v[210:213], v[8:11]
	s_setprio 0
	s_setprio 1
	v_mfma_f32_16x16x32_bf16 v[52:55], v[162:165], v[178:181], 0
	v_mfma_f32_16x16x32_bf16 v[48:51], v[170:173], v[178:181], 0
	v_mfma_f32_16x16x32_bf16 v[36:39], v[162:165], v[186:189], 0
	v_mfma_f32_16x16x32_bf16 v[32:35], v[170:173], v[186:189], 0
	v_mfma_f32_16x16x32_bf16 v[20:23], v[162:165], v[194:197], 0
	v_mfma_f32_16x16x32_bf16 v[16:19], v[170:173], v[194:197], 0
	v_mfma_f32_16x16x32_bf16 v[4:7], v[162:165], v[202:205], 0
	v_mfma_f32_16x16x32_bf16 v[0:3], v[170:173], v[202:205], 0
	v_mfma_f32_16x16x32_bf16 v[52:55], v[166:169], v[182:185], v[52:55]
	v_mfma_f32_16x16x32_bf16 v[48:51], v[174:177], v[182:185], v[48:51]
	v_mfma_f32_16x16x32_bf16 v[36:39], v[166:169], v[190:193], v[36:39]
	v_mfma_f32_16x16x32_bf16 v[32:35], v[174:177], v[190:193], v[32:35]
	v_mfma_f32_16x16x32_bf16 v[20:23], v[166:169], v[198:201], v[20:23]
	v_mfma_f32_16x16x32_bf16 v[16:19], v[174:177], v[198:201], v[16:19]
	v_mfma_f32_16x16x32_bf16 v[4:7], v[166:169], v[210:213], v[4:7]
	v_mfma_f32_16x16x32_bf16 v[0:3], v[174:177], v[210:213], v[0:3]
	s_setprio 0
	s_barrier
	s_add_i32 s70, 0, 0x18000
	v_add_u32_e32 v136, s70, v149
	s_add_i32 s71, 0, 0x1c000
	ds_read_b128 v[128:131], v136
	ds_read_b128 v[142:145], v136 offset:1024
	ds_read_b128 v[154:157], v136 offset:2048
	ds_read_b128 v[158:161], v136 offset:3072
	v_add_u32_e32 v136, s71, v149
	ds_read_b128 v[162:165], v136
	ds_read_b128 v[166:169], v136 offset:1024
	ds_read_b128 v[170:173], v136 offset:2048
	ds_read_b128 v[174:177], v136 offset:3072
	s_mov_b32 m0, s33
	v_lshl_add_u64 v[214:215], v[206:207], 0, s[12:13]
	ds_read_b128 v[178:181], v152 offset:32768
	ds_read_b128 v[182:185], v152 offset:33792
	ds_read_b128 v[186:189], v152 offset:34816
	ds_read_b128 v[190:193], v152 offset:35840
	ds_read_b128 v[194:197], v152 offset:36864
	ds_read_b128 v[198:201], v152 offset:37888
	ds_read_b128 v[202:205], v152 offset:38912
	ds_read_b128 v[210:213], v152 offset:39936
	global_load_lds_dwordx4 v[214:215], off
	v_lshl_add_u64 v[214:215], v[206:207], 0, s[14:15]
	s_mov_b32 m0, s36
	s_nop 0
	global_load_lds_dwordx4 v[214:215], off
	s_waitcnt vmcnt(8)
	s_waitcnt lgkmcnt(0)
	s_barrier
	s_setprio 1
	s_waitcnt lgkmcnt(0)
	v_mfma_f32_16x16x32_bf16 v[124:127], v[128:131], v[178:181], v[124:127]
	v_mfma_f32_16x16x32_bf16 v[120:123], v[154:157], v[178:181], v[120:123]
	v_mfma_f32_16x16x32_bf16 v[108:111], v[128:131], v[186:189], v[108:111]
	v_mfma_f32_16x16x32_bf16 v[104:107], v[154:157], v[186:189], v[104:107]
	v_mfma_f32_16x16x32_bf16 v[92:95], v[128:131], v[194:197], v[92:95]
	v_mfma_f32_16x16x32_bf16 v[88:91], v[154:157], v[194:197], v[88:91]
	v_mfma_f32_16x16x32_bf16 v[76:79], v[128:131], v[202:205], v[76:79]
	v_mfma_f32_16x16x32_bf16 v[72:75], v[154:157], v[202:205], v[72:75]
	v_mfma_f32_16x16x32_bf16 v[124:127], v[142:145], v[182:185], v[124:127]
	v_mfma_f32_16x16x32_bf16 v[120:123], v[158:161], v[182:185], v[120:123]
	v_mfma_f32_16x16x32_bf16 v[108:111], v[142:145], v[190:193], v[108:111]
	v_mfma_f32_16x16x32_bf16 v[104:107], v[158:161], v[190:193], v[104:107]
	v_mfma_f32_16x16x32_bf16 v[92:95], v[142:145], v[198:201], v[92:95]
	v_mfma_f32_16x16x32_bf16 v[88:91], v[158:161], v[198:201], v[88:91]
	v_mfma_f32_16x16x32_bf16 v[76:79], v[142:145], v[210:213], v[76:79]
	v_mfma_f32_16x16x32_bf16 v[72:75], v[158:161], v[210:213], v[72:75]
	s_setprio 0
	s_setprio 1
	v_mfma_f32_16x16x32_bf16 v[116:119], v[162:165], v[178:181], v[116:119]
	v_mfma_f32_16x16x32_bf16 v[112:115], v[170:173], v[178:181], v[112:115]
	v_mfma_f32_16x16x32_bf16 v[100:103], v[162:165], v[186:189], v[100:103]
	v_mfma_f32_16x16x32_bf16 v[96:99], v[170:173], v[186:189], v[96:99]
	v_mfma_f32_16x16x32_bf16 v[84:87], v[162:165], v[194:197], v[84:87]
	v_mfma_f32_16x16x32_bf16 v[80:83], v[170:173], v[194:197], v[80:83]
	v_mfma_f32_16x16x32_bf16 v[68:71], v[162:165], v[202:205], v[68:71]
	v_mfma_f32_16x16x32_bf16 v[64:67], v[170:173], v[202:205], v[64:67]
	v_mfma_f32_16x16x32_bf16 v[116:119], v[166:169], v[182:185], v[116:119]
	v_mfma_f32_16x16x32_bf16 v[112:115], v[174:177], v[182:185], v[112:115]
	v_mfma_f32_16x16x32_bf16 v[100:103], v[166:169], v[190:193], v[100:103]
	v_mfma_f32_16x16x32_bf16 v[96:99], v[174:177], v[190:193], v[96:99]
	v_mfma_f32_16x16x32_bf16 v[84:87], v[166:169], v[198:201], v[84:87]
	v_mfma_f32_16x16x32_bf16 v[80:83], v[174:177], v[198:201], v[80:83]
	v_mfma_f32_16x16x32_bf16 v[68:71], v[166:169], v[210:213], v[68:71]
	v_mfma_f32_16x16x32_bf16 v[64:67], v[174:177], v[210:213], v[64:67]
	s_setprio 0
	s_barrier
; #define PG8_STAGE(bufoff, gbase, voff) do { _Pragma("unroll") for (int _i = 0; _i < 2; ++_i) \
;         __builtin_amdgcn_global_load_lds((const unsigned*)((const char*)(gbase) + (voff)[_i]), (PG8_LAS unsigned*)(lds + (bufoff) + ldsw + _i * 8192), 16, 0, 0); } while (0)
; #define PG8_LDA(dst, b, h) do { _Pragma("unroll") for (int m = 0; m < 4; ++m) _Pragma("unroll") for (int k = 0; k < 2; ++k) dst[m][k] = *(const PG8_LAS bf16x8*)(lds + PG8_SA(b, h) + aoff + m * 2048 + k * 1024); } while (0)
; #define PG8_LDB(dst, b, h) do { _Pragma("unroll") for (int n = 0; n < 2; ++n) _Pragma("unroll") for (int k = 0; k < 2; ++k) dst[n][k] = *(const PG8_LAS bf16x8*)(lds + PG8_SB(b, h) + boff + n * 2048 + k * 1024); } while (0)
; #define PG8_MMA(ai, bj, At, Bt) do { __builtin_amdgcn_s_setprio(1); _Pragma("unroll") for (int m = 0; m < 4; ++m) _Pragma("unroll") for (int n = 0; n < 2; ++n) _Pragma("unroll") for (int k = 0; k < 2; ++k) \
;         acc[ai][bj][m][n] = __builtin_amdgcn_mfma_f32_16x16x32_bf16(Bt[n][k], At[m][k], acc[ai][bj][m][n], 0, 0, 0); __builtin_amdgcn_s_setprio(0); } while (0)
; #define PG8_BAR __builtin_amdgcn_s_barrier()
; template <class Epi, class Sched, bool ALIGN_EPI = false, bool SP2 = false, bool TA = true>
; __device__ __forceinline__ void gemm_phase(PG8_LAS unsigned char* lds, const Gemm g, const Sched& S, const Epi& E) {
;     ...
;             PG8_LDB(B0, 0, 0); PG8_LDB(B1, 0, 1); PG8_SCHED; PG8_LDA(At, 0, 0); PG8_STAGE(PG8_SA(1, 1), a1 + hstep, voffA);
;             PG8_WAIT_V(8); PG8_WAIT_L(0); PG8_BAR; PG8_MMA(0, 0, At, B0); PG8_MMA(0, 1, At, B1); PG8_BAR; PG8_SCHED;
;             PG8_LDA(At, 0, 1); PG8_STAGE(PG8_SB(0, 0), b2, voffB); PG8_STAGE(PG8_SB(0, 1), b2 + hstep, voffB); PG8_STAGE(PG8_SA(0, 0), a2, voffA);
;             PG8_WAIT_V(8); PG8_WAIT_L(0); PG8_BAR; PG8_MMA(1, 0, At, B0); PG8_MMA(1, 1, At, B1); PG8_BAR; PG8_SCHED;
;             PG8_LDB(B0, 1, 0); PG8_LDB(B1, 1, 1); PG8_SCHED; PG8_LDA(At, 1, 0); PG8_STAGE(PG8_SA(0, 1), a2 + hstep, voffA);
;             PG8_WAIT_V(8); PG8_WAIT_L(0); PG8_BAR; PG8_MMA(0, 0, At, B0); PG8_MMA(0, 1, At, B1); PG8_BAR; PG8_SCHED;
;             PG8_LDA(At, 1, 1); PG8_STAGE(PG8_SB(1, 0), b3, voffB); PG8_STAGE(PG8_SB(1, 1), b3 + hstep, voffB); PG8_STAGE(PG8_SA(1, 0), a3, voffA);
;             PG8_WAIT_V(8); PG8_WAIT_L(0); PG8_BAR; PG8_MMA(1, 0, At, B0); PG8_MMA(1, 1, At, B1); PG8_BAR; PG8_SCHED;
	s_add_i32 s70, s70, s23
	v_lshl_add_u64 v[214:215], v[132:133], 0, s[46:47]
	s_mov_b32 m0, s70
	ds_read_b128 v[178:181], v152 offset:49152
	ds_read_b128 v[182:185], v152 offset:50176
	ds_read_b128 v[186:189], v152 offset:51200
	ds_read_b128 v[190:193], v152 offset:52224
	ds_read_b128 v[194:197], v152 offset:53248
	ds_read_b128 v[198:201], v152 offset:54272
	ds_read_b128 v[202:205], v152 offset:55296
	ds_read_b128 v[210:213], v152 offset:56320
	global_load_lds_dwordx4 v[214:215], off
	v_lshl_add_u64 v[214:215], v[132:133], 0, s[48:49]
	s_add_i32 m0, s70, 0x2000
	s_add_i32 s70, s71, s23
	global_load_lds_dwordx4 v[214:215], off
	v_lshl_add_u64 v[214:215], v[132:133], 0, s[50:51]
	s_mov_b32 m0, s70
	v_lshl_add_u64 v[132:133], v[132:133], 0, s[52:53]
	global_load_lds_dwordx4 v[214:215], off
	s_add_i32 m0, s70, 0x2000
	s_nop 0
	global_load_lds_dwordx4 v[132:133], off
	v_lshl_add_u64 v[132:133], v[206:207], 0, s[46:47]
	s_mov_b32 m0, s37
	s_nop 0
	global_load_lds_dwordx4 v[132:133], off
	v_lshl_add_u64 v[132:133], v[206:207], 0, s[48:49]
	s_mov_b32 m0, s38
	s_nop 0
	global_load_lds_dwordx4 v[132:133], off
	s_waitcnt vmcnt(8)
	s_waitcnt lgkmcnt(0)
	s_barrier
	s_setprio 1
	s_waitcnt lgkmcnt(0)
	v_mfma_f32_16x16x32_bf16 v[60:63], v[128:131], v[178:181], v[60:63]
	v_mfma_f32_16x16x32_bf16 v[56:59], v[154:157], v[178:181], v[56:59]
	v_mfma_f32_16x16x32_bf16 v[44:47], v[128:131], v[186:189], v[44:47]
	v_mfma_f32_16x16x32_bf16 v[40:43], v[154:157], v[186:189], v[40:43]
	v_mfma_f32_16x16x32_bf16 v[28:31], v[128:131], v[194:197], v[28:31]
	v_mfma_f32_16x16x32_bf16 v[24:27], v[154:157], v[194:197], v[24:27]
	v_mfma_f32_16x16x32_bf16 v[12:15], v[128:131], v[202:205], v[12:15]
	v_mfma_f32_16x16x32_bf16 v[8:11], v[154:157], v[202:205], v[8:11]
	v_mfma_f32_16x16x32_bf16 v[60:63], v[142:145], v[182:185], v[60:63]
	v_mfma_f32_16x16x32_bf16 v[56:59], v[158:161], v[182:185], v[56:59]
	v_mfma_f32_16x16x32_bf16 v[44:47], v[142:145], v[190:193], v[44:47]
	v_mfma_f32_16x16x32_bf16 v[40:43], v[158:161], v[190:193], v[40:43]
	v_mfma_f32_16x16x32_bf16 v[28:31], v[142:145], v[198:201], v[28:31]
	v_mfma_f32_16x16x32_bf16 v[24:27], v[158:161], v[198:201], v[24:27]
	v_mfma_f32_16x16x32_bf16 v[12:15], v[142:145], v[210:213], v[12:15]
	v_mfma_f32_16x16x32_bf16 v[8:11], v[158:161], v[210:213], v[8:11]
	s_setprio 0
	s_setprio 1
	v_mfma_f32_16x16x32_bf16 v[52:55], v[162:165], v[178:181], v[52:55]
	v_mfma_f32_16x16x32_bf16 v[48:51], v[170:173], v[178:181], v[48:51]
	v_mfma_f32_16x16x32_bf16 v[36:39], v[162:165], v[186:189], v[36:39]
	v_mfma_f32_16x16x32_bf16 v[32:35], v[170:173], v[186:189], v[32:35]
	v_mfma_f32_16x16x32_bf16 v[20:23], v[162:165], v[194:197], v[20:23]
	v_mfma_f32_16x16x32_bf16 v[16:19], v[170:173], v[194:197], v[16:19]
	v_mfma_f32_16x16x32_bf16 v[4:7], v[162:165], v[202:205], v[4:7]
	v_mfma_f32_16x16x32_bf16 v[0:3], v[170:173], v[202:205], v[0:3]
	v_mfma_f32_16x16x32_bf16 v[52:55], v[166:169], v[182:185], v[52:55]
	v_mfma_f32_16x16x32_bf16 v[48:51], v[174:177], v[182:185], v[48:51]
	v_mfma_f32_16x16x32_bf16 v[36:39], v[166:169], v[190:193], v[36:39]
	v_mfma_f32_16x16x32_bf16 v[32:35], v[174:177], v[190:193], v[32:35]
	v_mfma_f32_16x16x32_bf16 v[20:23], v[166:169], v[198:201], v[20:23]
	v_mfma_f32_16x16x32_bf16 v[16:19], v[174:177], v[198:201], v[16:19]
	v_mfma_f32_16x16x32_bf16 v[4:7], v[166:169], v[210:213], v[4:7]
	v_mfma_f32_16x16x32_bf16 v[0:3], v[174:177], v[210:213], v[0:3]
	s_setprio 0
	s_barrier
	s_add_i32 s69, s69, 2
	s_add_u32 s58, s58, 0x8000
	s_addc_u32 s59, s59, 0
	s_add_u32 s60, s60, 0x8000
	s_addc_u32 s61, s61, 0
	s_cmp_gt_u32 s69, 41

; #define PG8_STAGE(bufoff, gbase, voff) do { _Pragma("unroll") for (int _i = 0; _i < 2; ++_i) \
;         __builtin_amdgcn_global_load_lds((const unsigned*)((const char*)(gbase) + (voff)[_i]), (PG8_LAS unsigned*)(lds + (bufoff) + ldsw + _i * 8192), 16, 0, 0); } while (0)
; #define PG8_WAIT_V(n) asm volatile("s_waitcnt vmcnt(" #n ")" ::: "memory")
; #define PG8_WAIT_L(n) asm volatile("s_waitcnt lgkmcnt(" #n ")" ::: "memory")
; #define PG8_BAR __builtin_amdgcn_s_barrier()
; template <class Epi, class Sched, bool ALIGN_EPI = false, bool SP2 = false, bool TA = true>
; __device__ __forceinline__ void gemm_phase(PG8_LAS unsigned char* lds, const Gemm g, const Sched& S, const Epi& E) {
;     ...
;         const bool has_next = S.next(ui + 1, nxt);
;         const char* nA = has_next ? (const char*)g.A + (size_t)nxt.pm * tstep : cA; const char* nB = has_next ? (const char*)g.Bt + (size_t)nxt.pn * tstep : cB;
; #pragma unroll 1
;         for (int t = 0; t < nt; t += 2) {
;             const bool last = (t == nt - 2);
;             const char* a1 = cA + (size_t)(t + 1) * kstep;
;             const char* a2 = last ? nA : cA + (size_t)(t + 2) * kstep; const char* b2 = last ? nB : cB + (size_t)(t + 2) * kstepB;
;             const char* a3 = a2 + kstep; const char* b3 = b2 + kstepB;
;             if (last && has_next) S.a_ready(nxt);
;             if constexpr (SP2) {
;             PG8_LDB(B0, 0, 0); PG8_LDB(B1, 0, 1); PG8_SCHED; PG8_LDA(At, 0, 0); PG8_STAGE(PG8_SA(1, 1), a1 + hstep, voffA);
;             PG8_WAIT_V(8); PG8_WAIT_L(0); PG8_BAR; PG8_MMA(0, 0, At, B0); PG8_MMA(0, 1, At, B1); PG8_BAR; PG8_SCHED;
;             PG8_LDA(At, 0, 1); PG8_STAGE(PG8_SB(0, 0), b2, voffB); PG8_STAGE(PG8_SB(0, 1), b2 + hstep, voffB); PG8_STAGE(PG8_SA(0, 0), a2, voffA);
;             PG8_WAIT_V(8); PG8_WAIT_L(0); PG8_BAR; PG8_MMA(1, 0, At, B0); PG8_MMA(1, 1, At, B1); PG8_BAR; PG8_SCHED;
;             PG8_LDB(B0, 1, 0); PG8_LDB(B1, 1, 1); PG8_SCHED; PG8_LDA(At, 1, 0); PG8_STAGE(PG8_SA(0, 1), a2 + hstep, voffA);
;             PG8_WAIT_V(8); PG8_WAIT_L(0); PG8_BAR; PG8_MMA(0, 0, At, B0); PG8_MMA(0, 1, At, B1); PG8_BAR; PG8_SCHED;
;             PG8_LDA(At, 1, 1); PG8_STAGE(PG8_SB(1, 0), b3, voffB); PG8_STAGE(PG8_SB(1, 1), b3 + hstep, voffB); PG8_STAGE(PG8_SA(1, 0), a3, voffA);
;             PG8_WAIT_V(8); PG8_WAIT_L(0); PG8_BAR; PG8_MMA(1, 0, At, B0); PG8_MMA(1, 1, At, B1); PG8_BAR; PG8_SCHED;
.LBB0_916:
	s_ashr_i32 s53, s52, 31
	s_lshl_b64 s[54:55], s[52:53], 17
	s_add_u32 s54, s19, s54
	s_addc_u32 s55, s21, s55
	s_and_b64 s[56:57], s[2:3], exec
	s_cselect_b32 s53, s55, s69
	s_cselect_b32 s86, s54, s68
	s_ashr_i32 s51, s50, 31
	s_lshl_b64 s[56:57], s[50:51], 17
	s_add_u32 s56, s22, s56
	s_addc_u32 s57, s23, s57
	s_and_b64 s[70:71], s[2:3], exec
	s_cselect_b32 s51, s57, s61
	s_cselect_b32 s87, s56, s60
	s_mov_b64 s[74:75], 0
	s_mov_b64 s[70:71], -1
	s_mov_b64 s[72:73], 0
	s_add_u32 s78, s68, s74
	s_addc_u32 s79, s69, s75
	s_add_u32 s88, s78, 0x8000
	ds_read_b128 v[140:143], v137
	ds_read_b128 v[148:151], v137 offset:1024
	ds_read_b128 v[152:155], v137 offset:2048
	ds_read_b128 v[156:159], v137 offset:3072
	ds_read_b128 v[160:163], v138
	ds_read_b128 v[164:167], v138 offset:1024
	ds_read_b128 v[168:171], v138 offset:2048
	ds_read_b128 v[172:175], v138 offset:3072
	s_addc_u32 s89, s79, 0
	s_and_b64 s[76:77], s[72:73], exec
	s_cselect_b32 s76, s86, s88
	s_cselect_b32 s77, s53, s89
	s_add_u32 s74, s60, s74
	s_addc_u32 s75, s61, s75
	s_add_u32 s74, s74, 0x8000
	s_addc_u32 s75, s75, 0
	s_and_b64 s[72:73], s[72:73], exec
	s_cselect_b32 s72, s87, s74
	s_cselect_b32 s73, s51, s75
	s_add_i32 s90, 0, 0x1c000
	s_add_i32 s91, 0, 0x18000
	s_add_i32 s75, s90, s30
	s_add_i32 s95, s83, s30
	s_add_i32 s93, s84, s30
	s_add_i32 s89, s91, s30
	s_add_i32 s74, s75, 0x2000
	s_add_i32 m0, s31, 0xc000
	s_add_i32 s96, s31, 0xe000
	s_add_i32 s94, s95, 0x2000
	s_add_i32 s92, s93, 0x2000
	s_add_i32 s88, s89, 0x2000
	v_lshl_add_u64 v[144:145], s[78:79], 0, v[134:135]
	v_lshl_add_u64 v[210:211], v[144:145], 0, s[44:45]
	ds_read_b128 v[176:179], v139
	ds_read_b128 v[180:183], v139 offset:1024
	ds_read_b128 v[184:187], v139 offset:2048
	ds_read_b128 v[188:191], v139 offset:3072
	ds_read_b128 v[192:195], v139 offset:4096
	ds_read_b128 v[196:199], v139 offset:5120
	ds_read_b128 v[200:203], v139 offset:6144
	ds_read_b128 v[204:207], v139 offset:7168
	global_load_lds_dwordx4 v[210:211], off
	v_lshl_add_u64 v[144:145], v[144:145], 0, s[46:47]
	s_mov_b32 m0, s96
	s_nop 0
	global_load_lds_dwordx4 v[144:145], off
	s_waitcnt vmcnt(8)
	s_waitcnt lgkmcnt(0)
	s_barrier
	s_setprio 1
	s_waitcnt lgkmcnt(0)
	v_mfma_f32_16x16x32_bf16 v[124:127], v[140:143], v[176:179], 0
	v_mfma_f32_16x16x32_bf16 v[120:123], v[152:155], v[176:179], 0
	v_mfma_f32_16x16x32_bf16 v[108:111], v[140:143], v[184:187], 0
	v_mfma_f32_16x16x32_bf16 v[104:107], v[152:155], v[184:187], 0
	v_mfma_f32_16x16x32_bf16 v[100:103], v[140:143], v[192:195], 0
	v_mfma_f32_16x16x32_bf16 v[92:95], v[152:155], v[192:195], 0
	v_mfma_f32_16x16x32_bf16 v[84:87], v[140:143], v[200:203], 0
	v_mfma_f32_16x16x32_bf16 v[76:79], v[152:155], v[200:203], 0
	v_mfma_f32_16x16x32_bf16 v[124:127], v[148:151], v[180:183], v[124:127]
	v_mfma_f32_16x16x32_bf16 v[120:123], v[156:159], v[180:183], v[120:123]
	v_mfma_f32_16x16x32_bf16 v[108:111], v[148:151], v[188:191], v[108:111]
	v_mfma_f32_16x16x32_bf16 v[104:107], v[156:159], v[188:191], v[104:107]
	v_mfma_f32_16x16x32_bf16 v[100:103], v[148:151], v[196:199], v[100:103]
	v_mfma_f32_16x16x32_bf16 v[92:95], v[156:159], v[196:199], v[92:95]
	v_mfma_f32_16x16x32_bf16 v[84:87], v[148:151], v[204:207], v[84:87]
	v_mfma_f32_16x16x32_bf16 v[76:79], v[156:159], v[204:207], v[76:79]
	s_setprio 0
	s_setprio 1
	v_mfma_f32_16x16x32_bf16 v[116:119], v[160:163], v[176:179], 0
	v_mfma_f32_16x16x32_bf16 v[112:115], v[168:171], v[176:179], 0
	v_mfma_f32_16x16x32_bf16 v[96:99], v[160:163], v[184:187], 0
	v_mfma_f32_16x16x32_bf16 v[88:91], v[168:171], v[184:187], 0
	v_mfma_f32_16x16x32_bf16 v[80:83], v[160:163], v[192:195], 0
	v_mfma_f32_16x16x32_bf16 v[72:75], v[168:171], v[192:195], 0
	v_mfma_f32_16x16x32_bf16 v[68:71], v[160:163], v[200:203], 0
	v_mfma_f32_16x16x32_bf16 v[64:67], v[168:171], v[200:203], 0
	v_mfma_f32_16x16x32_bf16 v[116:119], v[164:167], v[180:183], v[116:119]
	v_mfma_f32_16x16x32_bf16 v[112:115], v[172:175], v[180:183], v[112:115]
	v_mfma_f32_16x16x32_bf16 v[96:99], v[164:167], v[188:191], v[96:99]
	v_mfma_f32_16x16x32_bf16 v[88:91], v[172:175], v[188:191], v[88:91]
	v_mfma_f32_16x16x32_bf16 v[80:83], v[164:167], v[196:199], v[80:83]
	v_mfma_f32_16x16x32_bf16 v[72:75], v[172:175], v[196:199], v[72:75]
	v_mfma_f32_16x16x32_bf16 v[68:71], v[164:167], v[204:207], v[68:71]
	v_mfma_f32_16x16x32_bf16 v[64:67], v[172:175], v[204:207], v[64:67]
	s_setprio 0
	s_barrier
	s_mov_b32 m0, s95
	v_lshl_add_u64 v[144:145], s[72:73], 0, v[134:135]
	ds_read_b128 v[176:179], v139 offset:16384
	ds_read_b128 v[180:183], v139 offset:17408
	ds_read_b128 v[184:187], v139 offset:18432
	ds_read_b128 v[188:191], v139 offset:19456
	ds_read_b128 v[192:195], v139 offset:20480
	ds_read_b128 v[196:199], v139 offset:21504
	ds_read_b128 v[200:203], v139 offset:22528
	ds_read_b128 v[204:207], v139 offset:23552
	global_load_lds_dwordx4 v[144:145], off
	v_lshl_add_u64 v[210:211], v[144:145], 0, s[0:1]
	s_mov_b32 m0, s94
	s_nop 0
	global_load_lds_dwordx4 v[210:211], off
	v_lshl_add_u64 v[210:211], v[144:145], 0, s[4:5]
	s_mov_b32 m0, s93
	s_nop 0
	global_load_lds_dwordx4 v[210:211], off
	v_lshl_add_u64 v[210:211], v[144:145], 0, s[6:7]
	s_mov_b32 m0, s92
	s_nop 0
	global_load_lds_dwordx4 v[210:211], off
	v_lshl_add_u64 v[210:211], s[76:77], 0, v[134:135]
	s_mov_b32 m0, s31
	v_lshl_add_u64 v[212:213], v[210:211], 0, s[0:1]
	global_load_lds_dwordx4 v[210:211], off
	s_mov_b32 m0, s33
	s_nop 0
	global_load_lds_dwordx4 v[212:213], off
	s_waitcnt vmcnt(8)
	s_waitcnt lgkmcnt(0)
	s_barrier
; #define PG8_STAGE(bufoff, gbase, voff) do { _Pragma("unroll") for (int _i = 0; _i < 2; ++_i) \
;         __builtin_amdgcn_global_load_lds((const unsigned*)((const char*)(gbase) + (voff)[_i]), (PG8_LAS unsigned*)(lds + (bufoff) + ldsw + _i * 8192), 16, 0, 0); } while (0)
; #define PG8_LDA(dst, b, h) do { _Pragma("unroll") for (int m = 0; m < 4; ++m) _Pragma("unroll") for (int k = 0; k < 2; ++k) dst[m][k] = *(const PG8_LAS bf16x8*)(lds + PG8_SA(b, h) + aoff + m * 2048 + k * 1024); } while (0)
; #define PG8_LDB(dst, b, h) do { _Pragma("unroll") for (int n = 0; n < 2; ++n) _Pragma("unroll") for (int k = 0; k < 2; ++k) dst[n][k] = *(const PG8_LAS bf16x8*)(lds + PG8_SB(b, h) + boff + n * 2048 + k * 1024); } while (0)
; #define PG8_MMA(ai, bj, At, Bt) do { __builtin_amdgcn_s_setprio(1); _Pragma("unroll") for (int m = 0; m < 4; ++m) _Pragma("unroll") for (int n = 0; n < 2; ++n) _Pragma("unroll") for (int k = 0; k < 2; ++k) \
;         acc[ai][bj][m][n] = __builtin_amdgcn_mfma_f32_16x16x32_bf16(Bt[n][k], At[m][k], acc[ai][bj][m][n], 0, 0, 0); __builtin_amdgcn_s_setprio(0); } while (0)
; #define PG8_BAR __builtin_amdgcn_s_barrier()
; template <class Epi, class Sched, bool ALIGN_EPI = false, bool SP2 = false, bool TA = true>
; __device__ __forceinline__ void gemm_phase(PG8_LAS unsigned char* lds, const Gemm g, const Sched& S, const Epi& E) {
;     ...
;             PG8_LDB(B0, 0, 0); PG8_LDB(B1, 0, 1); PG8_SCHED; PG8_LDA(At, 0, 0); PG8_STAGE(PG8_SA(1, 1), a1 + hstep, voffA);
;             PG8_WAIT_V(8); PG8_WAIT_L(0); PG8_BAR; PG8_MMA(0, 0, At, B0); PG8_MMA(0, 1, At, B1); PG8_BAR; PG8_SCHED;
;             PG8_LDA(At, 0, 1); PG8_STAGE(PG8_SB(0, 0), b2, voffB); PG8_STAGE(PG8_SB(0, 1), b2 + hstep, voffB); PG8_STAGE(PG8_SA(0, 0), a2, voffA);
;             PG8_WAIT_V(8); PG8_WAIT_L(0); PG8_BAR; PG8_MMA(1, 0, At, B0); PG8_MMA(1, 1, At, B1); PG8_BAR; PG8_SCHED;
;             PG8_LDB(B0, 1, 0); PG8_LDB(B1, 1, 1); PG8_SCHED; PG8_LDA(At, 1, 0); PG8_STAGE(PG8_SA(0, 1), a2 + hstep, voffA);
;             PG8_WAIT_V(8); PG8_WAIT_L(0); PG8_BAR; PG8_MMA(0, 0, At, B0); PG8_MMA(0, 1, At, B1); PG8_BAR; PG8_SCHED;
;             PG8_LDA(At, 1, 1); PG8_STAGE(PG8_SB(1, 0), b3, voffB); PG8_STAGE(PG8_SB(1, 1), b3 + hstep, voffB); PG8_STAGE(PG8_SA(1, 0), a3, voffA);
;             PG8_WAIT_V(8); PG8_WAIT_L(0); PG8_BAR; PG8_MMA(1, 0, At, B0); PG8_MMA(1, 1, At, B1); PG8_BAR; PG8_SCHED;
	s_setprio 1
	s_waitcnt lgkmcnt(0)
	v_mfma_f32_16x16x32_bf16 v[60:63], v[140:143], v[176:179], 0
	v_mfma_f32_16x16x32_bf16 v[56:59], v[152:155], v[176:179], 0
	v_mfma_f32_16x16x32_bf16 v[48:51], v[140:143], v[184:187], 0
	v_mfma_f32_16x16x32_bf16 v[40:43], v[152:155], v[184:187], 0
	v_mfma_f32_16x16x32_bf16 v[32:35], v[140:143], v[192:195], 0
	v_mfma_f32_16x16x32_bf16 v[24:27], v[152:155], v[192:195], 0
	v_mfma_f32_16x16x32_bf16 v[16:19], v[140:143], v[200:203], 0
	v_mfma_f32_16x16x32_bf16 v[8:11], v[152:155], v[200:203], 0
	v_mfma_f32_16x16x32_bf16 v[60:63], v[148:151], v[180:183], v[60:63]
	v_mfma_f32_16x16x32_bf16 v[56:59], v[156:159], v[180:183], v[56:59]
	v_mfma_f32_16x16x32_bf16 v[48:51], v[148:151], v[188:191], v[48:51]
	v_mfma_f32_16x16x32_bf16 v[40:43], v[156:159], v[188:191], v[40:43]
	v_mfma_f32_16x16x32_bf16 v[32:35], v[148:151], v[196:199], v[32:35]
	v_mfma_f32_16x16x32_bf16 v[24:27], v[156:159], v[196:199], v[24:27]
	v_mfma_f32_16x16x32_bf16 v[16:19], v[148:151], v[204:207], v[16:19]
	v_mfma_f32_16x16x32_bf16 v[8:11], v[156:159], v[204:207], v[8:11]
	s_setprio 0
	s_setprio 1
	v_mfma_f32_16x16x32_bf16 v[52:55], v[160:163], v[176:179], 0
	v_mfma_f32_16x16x32_bf16 v[44:47], v[168:171], v[176:179], 0
	v_mfma_f32_16x16x32_bf16 v[36:39], v[160:163], v[184:187], 0
	v_mfma_f32_16x16x32_bf16 v[28:31], v[168:171], v[184:187], 0
	v_mfma_f32_16x16x32_bf16 v[20:23], v[160:163], v[192:195], 0
	v_mfma_f32_16x16x32_bf16 v[12:15], v[168:171], v[192:195], 0
	v_mfma_f32_16x16x32_bf16 v[4:7], v[160:163], v[200:203], 0
	v_mfma_f32_16x16x32_bf16 v[0:3], v[168:171], v[200:203], 0
	v_mfma_f32_16x16x32_bf16 v[52:55], v[164:167], v[180:183], v[52:55]
	v_mfma_f32_16x16x32_bf16 v[44:47], v[172:175], v[180:183], v[44:47]
	v_mfma_f32_16x16x32_bf16 v[36:39], v[164:167], v[188:191], v[36:39]
	v_mfma_f32_16x16x32_bf16 v[28:31], v[172:175], v[188:191], v[28:31]
	v_mfma_f32_16x16x32_bf16 v[20:23], v[164:167], v[196:199], v[20:23]
	v_mfma_f32_16x16x32_bf16 v[12:15], v[172:175], v[196:199], v[12:15]
	v_mfma_f32_16x16x32_bf16 v[4:7], v[164:167], v[204:207], v[4:7]
	v_mfma_f32_16x16x32_bf16 v[0:3], v[172:175], v[204:207], v[0:3]
	s_setprio 0
	s_barrier
	v_add_u32_e32 v128, s91, v136
	ds_read_b128 v[140:143], v128
	ds_read_b128 v[148:151], v128 offset:1024
	ds_read_b128 v[152:155], v128 offset:2048
	ds_read_b128 v[156:159], v128 offset:3072
	v_add_u32_e32 v128, s90, v136
	ds_read_b128 v[160:163], v128
	ds_read_b128 v[164:167], v128 offset:1024
	ds_read_b128 v[168:171], v128 offset:2048
	ds_read_b128 v[172:175], v128 offset:3072
	s_mov_b32 m0, s36
	v_lshl_add_u64 v[212:213], v[210:211], 0, s[4:5]
	ds_read_b128 v[176:179], v139 offset:32768
	ds_read_b128 v[180:183], v139 offset:33792
	ds_read_b128 v[184:187], v139 offset:34816
	ds_read_b128 v[188:191], v139 offset:35840
	ds_read_b128 v[192:195], v139 offset:36864
	ds_read_b128 v[196:199], v139 offset:37888
	ds_read_b128 v[200:203], v139 offset:38912
	ds_read_b128 v[204:207], v139 offset:39936
	global_load_lds_dwordx4 v[212:213], off
	v_lshl_add_u64 v[212:213], v[210:211], 0, s[6:7]
	s_mov_b32 m0, s37
	s_nop 0
	global_load_lds_dwordx4 v[212:213], off
	s_waitcnt vmcnt(8)
	s_waitcnt lgkmcnt(0)
	s_barrier
	s_setprio 1
	s_waitcnt lgkmcnt(0)
	v_mfma_f32_16x16x32_bf16 v[124:127], v[140:143], v[176:179], v[124:127]
	v_mfma_f32_16x16x32_bf16 v[120:123], v[152:155], v[176:179], v[120:123]
	v_mfma_f32_16x16x32_bf16 v[108:111], v[140:143], v[184:187], v[108:111]
	v_mfma_f32_16x16x32_bf16 v[104:107], v[152:155], v[184:187], v[104:107]
	v_mfma_f32_16x16x32_bf16 v[100:103], v[140:143], v[192:195], v[100:103]
	v_mfma_f32_16x16x32_bf16 v[92:95], v[152:155], v[192:195], v[92:95]
	v_mfma_f32_16x16x32_bf16 v[84:87], v[140:143], v[200:203], v[84:87]
	v_mfma_f32_16x16x32_bf16 v[76:79], v[152:155], v[200:203], v[76:79]
	v_mfma_f32_16x16x32_bf16 v[124:127], v[148:151], v[180:183], v[124:127]
	v_mfma_f32_16x16x32_bf16 v[120:123], v[156:159], v[180:183], v[120:123]
	v_mfma_f32_16x16x32_bf16 v[108:111], v[148:151], v[188:191], v[108:111]
	v_mfma_f32_16x16x32_bf16 v[104:107], v[156:159], v[188:191], v[104:107]
	v_mfma_f32_16x16x32_bf16 v[100:103], v[148:151], v[196:199], v[100:103]
	v_mfma_f32_16x16x32_bf16 v[92:95], v[156:159], v[196:199], v[92:95]
	v_mfma_f32_16x16x32_bf16 v[84:87], v[148:151], v[204:207], v[84:87]
	v_mfma_f32_16x16x32_bf16 v[76:79], v[156:159], v[204:207], v[76:79]
	s_setprio 0
	s_setprio 1
	v_mfma_f32_16x16x32_bf16 v[116:119], v[160:163], v[176:179], v[116:119]
	v_mfma_f32_16x16x32_bf16 v[112:115], v[168:171], v[176:179], v[112:115]
	v_mfma_f32_16x16x32_bf16 v[96:99], v[160:163], v[184:187], v[96:99]
	v_mfma_f32_16x16x32_bf16 v[88:91], v[168:171], v[184:187], v[88:91]
	v_mfma_f32_16x16x32_bf16 v[80:83], v[160:163], v[192:195], v[80:83]
	v_mfma_f32_16x16x32_bf16 v[72:75], v[168:171], v[192:195], v[72:75]
	v_mfma_f32_16x16x32_bf16 v[68:71], v[160:163], v[200:203], v[68:71]
	v_mfma_f32_16x16x32_bf16 v[64:67], v[168:171], v[200:203], v[64:67]
	v_mfma_f32_16x16x32_bf16 v[116:119], v[164:167], v[180:183], v[116:119]
	v_mfma_f32_16x16x32_bf16 v[112:115], v[172:175], v[180:183], v[112:115]
	v_mfma_f32_16x16x32_bf16 v[96:99], v[164:167], v[188:191], v[96:99]
	v_mfma_f32_16x16x32_bf16 v[88:91], v[172:175], v[188:191], v[88:91]
	v_mfma_f32_16x16x32_bf16 v[80:83], v[164:167], v[196:199], v[80:83]
	v_mfma_f32_16x16x32_bf16 v[72:75], v[172:175], v[196:199], v[72:75]
	v_mfma_f32_16x16x32_bf16 v[68:71], v[164:167], v[204:207], v[68:71]
	v_mfma_f32_16x16x32_bf16 v[64:67], v[172:175], v[204:207], v[64:67]
	s_setprio 0
	s_barrier
; #define PG8_STAGE(bufoff, gbase, voff) do { _Pragma("unroll") for (int _i = 0; _i < 2; ++_i) \
;         __builtin_amdgcn_global_load_lds((const unsigned*)((const char*)(gbase) + (voff)[_i]), (PG8_LAS unsigned*)(lds + (bufoff) + ldsw + _i * 8192), 16, 0, 0); } while (0)
; #define PG8_LDA(dst, b, h) do { _Pragma("unroll") for (int m = 0; m < 4; ++m) _Pragma("unroll") for (int k = 0; k < 2; ++k) dst[m][k] = *(const PG8_LAS bf16x8*)(lds + PG8_SA(b, h) + aoff + m * 2048 + k * 1024); } while (0)
; #define PG8_LDB(dst, b, h) do { _Pragma("unroll") for (int n = 0; n < 2; ++n) _Pragma("unroll") for (int k = 0; k < 2; ++k) dst[n][k] = *(const PG8_LAS bf16x8*)(lds + PG8_SB(b, h) + boff + n * 2048 + k * 1024); } while (0)
; #define PG8_MMA(ai, bj, At, Bt) do { __builtin_amdgcn_s_setprio(1); _Pragma("unroll") for (int m = 0; m < 4; ++m) _Pragma("unroll") for (int n = 0; n < 2; ++n) _Pragma("unroll") for (int k = 0; k < 2; ++k) \
;         acc[ai][bj][m][n] = __builtin_amdgcn_mfma_f32_16x16x32_bf16(Bt[n][k], At[m][k], acc[ai][bj][m][n], 0, 0, 0); __builtin_amdgcn_s_setprio(0); } while (0)
; #define PG8_BAR __builtin_amdgcn_s_barrier()
; template <class Epi, class Sched, bool ALIGN_EPI = false, bool SP2 = false, bool TA = true>
; __device__ __forceinline__ void gemm_phase(PG8_LAS unsigned char* lds, const Gemm g, const Sched& S, const Epi& E) {
;     ...
;             PG8_LDB(B0, 0, 0); PG8_LDB(B1, 0, 1); PG8_SCHED; PG8_LDA(At, 0, 0); PG8_STAGE(PG8_SA(1, 1), a1 + hstep, voffA);
;             PG8_WAIT_V(8); PG8_WAIT_L(0); PG8_BAR; PG8_MMA(0, 0, At, B0); PG8_MMA(0, 1, At, B1); PG8_BAR; PG8_SCHED;
;             PG8_LDA(At, 0, 1); PG8_STAGE(PG8_SB(0, 0), b2, voffB); PG8_STAGE(PG8_SB(0, 1), b2 + hstep, voffB); PG8_STAGE(PG8_SA(0, 0), a2, voffA);
;             PG8_WAIT_V(8); PG8_WAIT_L(0); PG8_BAR; PG8_MMA(1, 0, At, B0); PG8_MMA(1, 1, At, B1); PG8_BAR; PG8_SCHED;
;             PG8_LDB(B0, 1, 0); PG8_LDB(B1, 1, 1); PG8_SCHED; PG8_LDA(At, 1, 0); PG8_STAGE(PG8_SA(0, 1), a2 + hstep, voffA);
;             PG8_WAIT_V(8); PG8_WAIT_L(0); PG8_BAR; PG8_MMA(0, 0, At, B0); PG8_MMA(0, 1, At, B1); PG8_BAR; PG8_SCHED;
;             PG8_LDA(At, 1, 1); PG8_STAGE(PG8_SB(1, 0), b3, voffB); PG8_STAGE(PG8_SB(1, 1), b3 + hstep, voffB); PG8_STAGE(PG8_SA(1, 0), a3, voffA);
;             PG8_WAIT_V(8); PG8_WAIT_L(0); PG8_BAR; PG8_MMA(1, 0, At, B0); PG8_MMA(1, 1, At, B1); PG8_BAR; PG8_SCHED;
	s_mov_b32 m0, s89
	v_lshl_add_u64 v[212:213], v[144:145], 0, s[14:15]
	ds_read_b128 v[176:179], v139 offset:49152
	ds_read_b128 v[180:183], v139 offset:50176
	ds_read_b128 v[184:187], v139 offset:51200
	ds_read_b128 v[188:191], v139 offset:52224
	ds_read_b128 v[192:195], v139 offset:53248
	ds_read_b128 v[196:199], v139 offset:54272
	ds_read_b128 v[200:203], v139 offset:55296
	ds_read_b128 v[204:207], v139 offset:56320
	global_load_lds_dwordx4 v[212:213], off
	v_lshl_add_u64 v[212:213], v[144:145], 0, s[16:17]
	s_mov_b32 m0, s88
	s_nop 0
	global_load_lds_dwordx4 v[212:213], off
	v_lshl_add_u64 v[212:213], v[144:145], 0, s[44:45]
	s_mov_b32 m0, s75
	v_lshl_add_u64 v[144:145], v[144:145], 0, s[46:47]
	global_load_lds_dwordx4 v[212:213], off
	s_mov_b32 m0, s74
	s_nop 0
	global_load_lds_dwordx4 v[144:145], off
	v_lshl_add_u64 v[144:145], v[210:211], 0, s[14:15]
	s_mov_b32 m0, s39
	s_nop 0
	global_load_lds_dwordx4 v[144:145], off
	v_lshl_add_u64 v[144:145], v[210:211], 0, s[16:17]
	s_mov_b32 m0, s40
	s_nop 0
	global_load_lds_dwordx4 v[144:145], off
	s_waitcnt vmcnt(8)
	s_waitcnt lgkmcnt(0)
	s_barrier
	s_setprio 1
	s_waitcnt lgkmcnt(0)
	v_mfma_f32_16x16x32_bf16 v[60:63], v[140:143], v[176:179], v[60:63]
	v_mfma_f32_16x16x32_bf16 v[56:59], v[152:155], v[176:179], v[56:59]
	v_mfma_f32_16x16x32_bf16 v[48:51], v[140:143], v[184:187], v[48:51]
	v_mfma_f32_16x16x32_bf16 v[40:43], v[152:155], v[184:187], v[40:43]
	v_mfma_f32_16x16x32_bf16 v[32:35], v[140:143], v[192:195], v[32:35]
	v_mfma_f32_16x16x32_bf16 v[24:27], v[152:155], v[192:195], v[24:27]
	v_mfma_f32_16x16x32_bf16 v[16:19], v[140:143], v[200:203], v[16:19]
	v_mfma_f32_16x16x32_bf16 v[8:11], v[152:155], v[200:203], v[8:11]
	v_mfma_f32_16x16x32_bf16 v[60:63], v[148:151], v[180:183], v[60:63]
	v_mfma_f32_16x16x32_bf16 v[56:59], v[156:159], v[180:183], v[56:59]
	v_mfma_f32_16x16x32_bf16 v[48:51], v[148:151], v[188:191], v[48:51]
	v_mfma_f32_16x16x32_bf16 v[40:43], v[156:159], v[188:191], v[40:43]
	v_mfma_f32_16x16x32_bf16 v[32:35], v[148:151], v[196:199], v[32:35]
	v_mfma_f32_16x16x32_bf16 v[24:27], v[156:159], v[196:199], v[24:27]
	v_mfma_f32_16x16x32_bf16 v[16:19], v[148:151], v[204:207], v[16:19]
	v_mfma_f32_16x16x32_bf16 v[8:11], v[156:159], v[204:207], v[8:11]
	s_setprio 0
	s_setprio 1
	v_mfma_f32_16x16x32_bf16 v[52:55], v[160:163], v[176:179], v[52:55]
	v_mfma_f32_16x16x32_bf16 v[44:47], v[168:171], v[176:179], v[44:47]
	v_mfma_f32_16x16x32_bf16 v[36:39], v[160:163], v[184:187], v[36:39]
	v_mfma_f32_16x16x32_bf16 v[28:31], v[168:171], v[184:187], v[28:31]
	v_mfma_f32_16x16x32_bf16 v[20:23], v[160:163], v[192:195], v[20:23]
	v_mfma_f32_16x16x32_bf16 v[12:15], v[168:171], v[192:195], v[12:15]
	v_mfma_f32_16x16x32_bf16 v[4:7], v[160:163], v[200:203], v[4:7]
	v_mfma_f32_16x16x32_bf16 v[0:3], v[168:171], v[200:203], v[0:3]
	v_mfma_f32_16x16x32_bf16 v[52:55], v[164:167], v[180:183], v[52:55]
	v_mfma_f32_16x16x32_bf16 v[44:47], v[172:175], v[180:183], v[44:47]
	v_mfma_f32_16x16x32_bf16 v[36:39], v[164:167], v[188:191], v[36:39]
	v_mfma_f32_16x16x32_bf16 v[28:31], v[172:175], v[188:191], v[28:31]
	v_mfma_f32_16x16x32_bf16 v[20:23], v[164:167], v[196:199], v[20:23]
	v_mfma_f32_16x16x32_bf16 v[12:15], v[172:175], v[196:199], v[12:15]
	v_mfma_f32_16x16x32_bf16 v[4:7], v[164:167], v[204:207], v[4:7]
	v_mfma_f32_16x16x32_bf16 v[0:3], v[172:175], v[204:207], v[0:3]
	s_setprio 0
	s_barrier
	s_andn2_b64 vcc, exec, s[70:71]
	s_mov_b64 s[72:73], -1
	s_mov_b64 s[70:71], 0
	s_mov_b64 s[74:75], 0x8000

; #define PG8_STAGE(bufoff, gbase, voff) do { _Pragma("unroll") for (int _i = 0; _i < 2; ++_i) \
;         __builtin_amdgcn_global_load_lds((const unsigned*)((const char*)(gbase) + (voff)[_i]), (PG8_LAS unsigned*)(lds + (bufoff) + ldsw + _i * 8192), 16, 0, 0); } while (0)
; #define PG8_WAIT_V(n) asm volatile("s_waitcnt vmcnt(" #n ")" ::: "memory")
; #define PG8_WAIT_L(n) asm volatile("s_waitcnt lgkmcnt(" #n ")" ::: "memory")
; #define PG8_BAR __builtin_amdgcn_s_barrier()
; template <class Epi, class Sched, bool ALIGN_EPI = false, bool SP2 = false, bool TA = true>
; __device__ __forceinline__ void gemm_phase(PG8_LAS unsigned char* lds, const Gemm g, const Sched& S, const Epi& E) {
;     ...
;         const bool has_next = S.next(ui + 1, nxt);
;         const char* nA = has_next ? (const char*)g.A + (size_t)nxt.pm * tstep : cA; const char* nB = has_next ? (const char*)g.Bt + (size_t)nxt.pn * tstep : cB;
; #pragma unroll 1
;         for (int t = 0; t < nt; t += 2) {
;             const bool last = (t == nt - 2);
;             const char* a1 = cA + (size_t)(t + 1) * kstep;
;             const char* a2 = last ? nA : cA + (size_t)(t + 2) * kstep; const char* b2 = last ? nB : cB + (size_t)(t + 2) * kstepB;
;             const char* a3 = a2 + kstep; const char* b3 = b2 + kstepB;
;             if (last && has_next) S.a_ready(nxt);
;             if constexpr (SP2) {
;             PG8_LDB(B0, 0, 0); PG8_LDB(B1, 0, 1); PG8_SCHED; PG8_LDA(At, 0, 0); PG8_STAGE(PG8_SA(1, 1), a1 + hstep, voffA);
;             PG8_WAIT_V(8); PG8_WAIT_L(0); PG8_BAR; PG8_MMA(0, 0, At, B0); PG8_MMA(0, 1, At, B1); PG8_BAR; PG8_SCHED;
;             PG8_LDA(At, 0, 1); PG8_STAGE(PG8_SB(0, 0), b2, voffB); PG8_STAGE(PG8_SB(0, 1), b2 + hstep, voffB); PG8_STAGE(PG8_SA(0, 0), a2, voffA);
;             PG8_WAIT_V(8); PG8_WAIT_L(0); PG8_BAR; PG8_MMA(1, 0, At, B0); PG8_MMA(1, 1, At, B1); PG8_BAR; PG8_SCHED;
;             PG8_LDB(B0, 1, 0); PG8_LDB(B1, 1, 1); PG8_SCHED; PG8_LDA(At, 1, 0); PG8_STAGE(PG8_SA(0, 1), a2 + hstep, voffA);
;             PG8_WAIT_V(8); PG8_WAIT_L(0); PG8_BAR; PG8_MMA(0, 0, At, B0); PG8_MMA(0, 1, At, B1); PG8_BAR; PG8_SCHED;
;             PG8_LDA(At, 1, 1); PG8_STAGE(PG8_SB(1, 0), b3, voffB); PG8_STAGE(PG8_SB(1, 1), b3 + hstep, voffB); PG8_STAGE(PG8_SA(1, 0), a3, voffA);
;             PG8_WAIT_V(8); PG8_WAIT_L(0); PG8_BAR; PG8_MMA(1, 0, At, B0); PG8_MMA(1, 1, At, B1); PG8_BAR; PG8_SCHED;
.LBB0_999:
	s_ashr_i32 s69, s68, 31
	s_lshl_b64 s[70:71], s[68:69], 19
	s_add_u32 s70, s34, s70
	s_addc_u32 s71, s35, s71
	s_and_b64 s[72:73], s[6:7], exec
	s_cselect_b32 s69, s71, s77
	s_cselect_b32 s75, s70, s76
	s_ashr_i32 s61, s60, 31
	s_lshl_b64 s[72:73], s[60:61], 19
	s_add_u32 s72, s33, s72
	s_addc_u32 s73, s93, s73
	s_and_b64 s[80:81], s[6:7], exec
	s_cselect_b32 s61, s73, s79
	s_cselect_b32 s80, s72, s78
	s_add_u32 s76, s76, 0x44000
	s_addc_u32 s77, s77, 0
	s_add_u32 s78, s78, 0x8000
	s_addc_u32 s79, s79, 0
	s_mov_b32 s81, -2
	s_waitcnt lgkmcnt(0)
	ds_read_b128 v[128:131], v163
	ds_read_b128 v[132:135], v163 offset:1024
	ds_read_b128 v[136:139], v163 offset:2048
	ds_read_b128 v[140:143], v163 offset:3072
	ds_read_b128 v[152:155], v164
	ds_read_b128 v[168:171], v164 offset:1024
	ds_read_b128 v[172:175], v164 offset:2048
	ds_read_b128 v[176:179], v164 offset:3072
	s_add_u32 s82, s76, 0xfffc4000
	s_addc_u32 s83, s77, -1
	s_cmp_eq_u32 s81, 12
	s_cselect_b32 s83, s69, s83
	s_cselect_b32 s82, s75, s82
	s_cselect_b32 s85, s61, s79
	s_cselect_b32 s84, s80, s78
	v_lshl_add_u64 v[156:157], s[76:77], 0, v[144:145]
	s_add_i32 m0, s95, 0xc000
	ds_read_b128 v[180:183], v165
	ds_read_b128 v[184:187], v165 offset:1024
	ds_read_b128 v[188:191], v165 offset:2048
	ds_read_b128 v[192:195], v165 offset:3072
	ds_read_b128 v[196:199], v165 offset:4096
	ds_read_b128 v[200:203], v165 offset:5120
	ds_read_b128 v[204:207], v165 offset:6144
	ds_read_b128 v[210:213], v165 offset:7168
	global_load_lds_dwordx4 v[156:157], off
	v_lshl_add_u64 v[156:157], v[156:157], 0, s[12:13]
	s_add_i32 m0, s95, 0xe000
	s_nop 0
	global_load_lds_dwordx4 v[156:157], off
	s_waitcnt vmcnt(8)
	s_waitcnt lgkmcnt(0)
	s_barrier
	s_setprio 1
	s_waitcnt lgkmcnt(0)
	v_mfma_f32_16x16x32_bf16 v[124:127], v[128:131], v[180:183], 0
	v_mfma_f32_16x16x32_bf16 v[120:123], v[136:139], v[180:183], 0
	v_mfma_f32_16x16x32_bf16 v[108:111], v[128:131], v[188:191], 0
	v_mfma_f32_16x16x32_bf16 v[104:107], v[136:139], v[188:191], 0
	v_mfma_f32_16x16x32_bf16 v[92:95], v[128:131], v[196:199], 0
	v_mfma_f32_16x16x32_bf16 v[88:91], v[136:139], v[196:199], 0
	v_mfma_f32_16x16x32_bf16 v[76:79], v[128:131], v[204:207], 0
	v_mfma_f32_16x16x32_bf16 v[72:75], v[136:139], v[204:207], 0
	v_mfma_f32_16x16x32_bf16 v[124:127], v[132:135], v[184:187], v[124:127]
	v_mfma_f32_16x16x32_bf16 v[120:123], v[140:143], v[184:187], v[120:123]
	v_mfma_f32_16x16x32_bf16 v[108:111], v[132:135], v[192:195], v[108:111]
	v_mfma_f32_16x16x32_bf16 v[104:107], v[140:143], v[192:195], v[104:107]
	v_mfma_f32_16x16x32_bf16 v[92:95], v[132:135], v[200:203], v[92:95]
	v_mfma_f32_16x16x32_bf16 v[88:91], v[140:143], v[200:203], v[88:91]
	v_mfma_f32_16x16x32_bf16 v[76:79], v[132:135], v[210:213], v[76:79]
	v_mfma_f32_16x16x32_bf16 v[72:75], v[140:143], v[210:213], v[72:75]
	s_setprio 0
	s_setprio 1
	v_mfma_f32_16x16x32_bf16 v[116:119], v[152:155], v[180:183], 0
	v_mfma_f32_16x16x32_bf16 v[112:115], v[172:175], v[180:183], 0
	v_mfma_f32_16x16x32_bf16 v[100:103], v[152:155], v[188:191], 0
	v_mfma_f32_16x16x32_bf16 v[96:99], v[172:175], v[188:191], 0
	v_mfma_f32_16x16x32_bf16 v[84:87], v[152:155], v[196:199], 0
	v_mfma_f32_16x16x32_bf16 v[80:83], v[172:175], v[196:199], 0
	v_mfma_f32_16x16x32_bf16 v[68:71], v[152:155], v[204:207], 0
	v_mfma_f32_16x16x32_bf16 v[64:67], v[172:175], v[204:207], 0
	v_mfma_f32_16x16x32_bf16 v[116:119], v[168:171], v[184:187], v[116:119]
	v_mfma_f32_16x16x32_bf16 v[112:115], v[176:179], v[184:187], v[112:115]
	v_mfma_f32_16x16x32_bf16 v[100:103], v[168:171], v[192:195], v[100:103]
	v_mfma_f32_16x16x32_bf16 v[96:99], v[176:179], v[192:195], v[96:99]
	v_mfma_f32_16x16x32_bf16 v[84:87], v[168:171], v[200:203], v[84:87]
	v_mfma_f32_16x16x32_bf16 v[80:83], v[176:179], v[200:203], v[80:83]
	v_mfma_f32_16x16x32_bf16 v[68:71], v[168:171], v[210:213], v[68:71]
	v_mfma_f32_16x16x32_bf16 v[64:67], v[176:179], v[210:213], v[64:67]
	s_setprio 0
	s_barrier
	v_lshl_add_u64 v[156:157], s[84:85], 0, v[144:145]
	s_add_i32 s84, s42, s94
	s_mov_b32 m0, s84
	ds_read_b128 v[180:183], v165 offset:16384
	ds_read_b128 v[184:187], v165 offset:17408
	ds_read_b128 v[188:191], v165 offset:18432
	ds_read_b128 v[192:195], v165 offset:19456
	ds_read_b128 v[196:199], v165 offset:20480
	ds_read_b128 v[200:203], v165 offset:21504
	ds_read_b128 v[204:207], v165 offset:22528
	ds_read_b128 v[210:213], v165 offset:23552
	global_load_lds_dwordx4 v[156:157], off
	v_lshl_add_u64 v[214:215], v[156:157], 0, s[12:13]
	s_add_i32 m0, s84, 0x2000
	s_add_i32 s84, s43, s94
	global_load_lds_dwordx4 v[214:215], off
	v_lshl_add_u64 v[214:215], v[156:157], 0, s[14:15]
	s_mov_b32 m0, s84
	s_nop 0
	global_load_lds_dwordx4 v[214:215], off
	v_lshl_add_u64 v[214:215], v[156:157], 0, s[16:17]
	s_add_i32 m0, s84, 0x2000
	s_nop 0
	global_load_lds_dwordx4 v[214:215], off
	v_lshl_add_u64 v[214:215], s[82:83], 0, v[144:145]
	s_mov_b32 m0, s95
	v_lshl_add_u64 v[216:217], v[214:215], 0, s[12:13]
	global_load_lds_dwordx4 v[214:215], off
	s_mov_b32 m0, s96
	s_nop 0
	global_load_lds_dwordx4 v[216:217], off
	s_waitcnt vmcnt(8)
	s_waitcnt lgkmcnt(0)
	s_barrier
; #define PG8_STAGE(bufoff, gbase, voff) do { _Pragma("unroll") for (int _i = 0; _i < 2; ++_i) \
;         __builtin_amdgcn_global_load_lds((const unsigned*)((const char*)(gbase) + (voff)[_i]), (PG8_LAS unsigned*)(lds + (bufoff) + ldsw + _i * 8192), 16, 0, 0); } while (0)
; #define PG8_LDA(dst, b, h) do { _Pragma("unroll") for (int m = 0; m < 4; ++m) _Pragma("unroll") for (int k = 0; k < 2; ++k) dst[m][k] = *(const PG8_LAS bf16x8*)(lds + PG8_SA(b, h) + aoff + m * 2048 + k * 1024); } while (0)
; #define PG8_LDB(dst, b, h) do { _Pragma("unroll") for (int n = 0; n < 2; ++n) _Pragma("unroll") for (int k = 0; k < 2; ++k) dst[n][k] = *(const PG8_LAS bf16x8*)(lds + PG8_SB(b, h) + boff + n * 2048 + k * 1024); } while (0)
; #define PG8_MMA(ai, bj, At, Bt) do { __builtin_amdgcn_s_setprio(1); _Pragma("unroll") for (int m = 0; m < 4; ++m) _Pragma("unroll") for (int n = 0; n < 2; ++n) _Pragma("unroll") for (int k = 0; k < 2; ++k) \
;         acc[ai][bj][m][n] = __builtin_amdgcn_mfma_f32_16x16x32_bf16(Bt[n][k], At[m][k], acc[ai][bj][m][n], 0, 0, 0); __builtin_amdgcn_s_setprio(0); } while (0)
; #define PG8_BAR __builtin_amdgcn_s_barrier()
; template <class Epi, class Sched, bool ALIGN_EPI = false, bool SP2 = false, bool TA = true>
; __device__ __forceinline__ void gemm_phase(PG8_LAS unsigned char* lds, const Gemm g, const Sched& S, const Epi& E) {
;     ...
;             PG8_LDB(B0, 0, 0); PG8_LDB(B1, 0, 1); PG8_SCHED; PG8_LDA(At, 0, 0); PG8_STAGE(PG8_SA(1, 1), a1 + hstep, voffA);
;             PG8_WAIT_V(8); PG8_WAIT_L(0); PG8_BAR; PG8_MMA(0, 0, At, B0); PG8_MMA(0, 1, At, B1); PG8_BAR; PG8_SCHED;
;             PG8_LDA(At, 0, 1); PG8_STAGE(PG8_SB(0, 0), b2, voffB); PG8_STAGE(PG8_SB(0, 1), b2 + hstep, voffB); PG8_STAGE(PG8_SA(0, 0), a2, voffA);
;             PG8_WAIT_V(8); PG8_WAIT_L(0); PG8_BAR; PG8_MMA(1, 0, At, B0); PG8_MMA(1, 1, At, B1); PG8_BAR; PG8_SCHED;
;             PG8_LDB(B0, 1, 0); PG8_LDB(B1, 1, 1); PG8_SCHED; PG8_LDA(At, 1, 0); PG8_STAGE(PG8_SA(0, 1), a2 + hstep, voffA);
;             PG8_WAIT_V(8); PG8_WAIT_L(0); PG8_BAR; PG8_MMA(0, 0, At, B0); PG8_MMA(0, 1, At, B1); PG8_BAR; PG8_SCHED;
;             PG8_LDA(At, 1, 1); PG8_STAGE(PG8_SB(1, 0), b3, voffB); PG8_STAGE(PG8_SB(1, 1), b3 + hstep, voffB); PG8_STAGE(PG8_SA(1, 0), a3, voffA);
;             PG8_WAIT_V(8); PG8_WAIT_L(0); PG8_BAR; PG8_MMA(1, 0, At, B0); PG8_MMA(1, 1, At, B1); PG8_BAR; PG8_SCHED;
	s_setprio 1
	s_waitcnt lgkmcnt(0)
	v_mfma_f32_16x16x32_bf16 v[60:63], v[128:131], v[180:183], 0
	v_mfma_f32_16x16x32_bf16 v[56:59], v[136:139], v[180:183], 0
	v_mfma_f32_16x16x32_bf16 v[44:47], v[128:131], v[188:191], 0
	v_mfma_f32_16x16x32_bf16 v[40:43], v[136:139], v[188:191], 0
	v_mfma_f32_16x16x32_bf16 v[28:31], v[128:131], v[196:199], 0
	v_mfma_f32_16x16x32_bf16 v[24:27], v[136:139], v[196:199], 0
	v_mfma_f32_16x16x32_bf16 v[12:15], v[128:131], v[204:207], 0
	v_mfma_f32_16x16x32_bf16 v[8:11], v[136:139], v[204:207], 0
	v_mfma_f32_16x16x32_bf16 v[60:63], v[132:135], v[184:187], v[60:63]
	v_mfma_f32_16x16x32_bf16 v[56:59], v[140:143], v[184:187], v[56:59]
	v_mfma_f32_16x16x32_bf16 v[44:47], v[132:135], v[192:195], v[44:47]
	v_mfma_f32_16x16x32_bf16 v[40:43], v[140:143], v[192:195], v[40:43]
	v_mfma_f32_16x16x32_bf16 v[28:31], v[132:135], v[200:203], v[28:31]
	v_mfma_f32_16x16x32_bf16 v[24:27], v[140:143], v[200:203], v[24:27]
	v_mfma_f32_16x16x32_bf16 v[12:15], v[132:135], v[210:213], v[12:15]
	v_mfma_f32_16x16x32_bf16 v[8:11], v[140:143], v[210:213], v[8:11]
	s_setprio 0
	s_setprio 1
	v_mfma_f32_16x16x32_bf16 v[52:55], v[152:155], v[180:183], 0
	v_mfma_f32_16x16x32_bf16 v[48:51], v[172:175], v[180:183], 0
	v_mfma_f32_16x16x32_bf16 v[36:39], v[152:155], v[188:191], 0
	v_mfma_f32_16x16x32_bf16 v[32:35], v[172:175], v[188:191], 0
	v_mfma_f32_16x16x32_bf16 v[20:23], v[152:155], v[196:199], 0
	v_mfma_f32_16x16x32_bf16 v[16:19], v[172:175], v[196:199], 0
	v_mfma_f32_16x16x32_bf16 v[4:7], v[152:155], v[204:207], 0
	v_mfma_f32_16x16x32_bf16 v[0:3], v[172:175], v[204:207], 0
	v_mfma_f32_16x16x32_bf16 v[52:55], v[168:171], v[184:187], v[52:55]
	v_mfma_f32_16x16x32_bf16 v[48:51], v[176:179], v[184:187], v[48:51]
	v_mfma_f32_16x16x32_bf16 v[36:39], v[168:171], v[192:195], v[36:39]
	v_mfma_f32_16x16x32_bf16 v[32:35], v[176:179], v[192:195], v[32:35]
	v_mfma_f32_16x16x32_bf16 v[20:23], v[168:171], v[200:203], v[20:23]
	v_mfma_f32_16x16x32_bf16 v[16:19], v[176:179], v[200:203], v[16:19]
	v_mfma_f32_16x16x32_bf16 v[4:7], v[168:171], v[210:213], v[4:7]
	v_mfma_f32_16x16x32_bf16 v[0:3], v[176:179], v[210:213], v[0:3]
	s_setprio 0
	s_barrier
	s_add_i32 s82, 0, 0x18000
	s_add_i32 s83, 0, 0x1c000
	v_add_u32_e32 v140, s82, v159
	v_add_u32_e32 v146, s83, v159
	ds_read_b128 v[128:131], v140
	ds_read_b128 v[132:135], v140 offset:1024
	ds_read_b128 v[136:139], v140 offset:2048
	ds_read_b128 v[140:143], v140 offset:3072
	ds_read_b128 v[152:155], v146
	ds_read_b128 v[168:171], v146 offset:1024
	ds_read_b128 v[172:175], v146 offset:2048
	ds_read_b128 v[176:179], v146 offset:3072
	s_mov_b32 m0, s97
	v_lshl_add_u64 v[216:217], v[214:215], 0, s[14:15]
	ds_read_b128 v[180:183], v165 offset:32768
	ds_read_b128 v[184:187], v165 offset:33792
	ds_read_b128 v[188:191], v165 offset:34816
	ds_read_b128 v[192:195], v165 offset:35840
	ds_read_b128 v[196:199], v165 offset:36864
	ds_read_b128 v[200:203], v165 offset:37888
	ds_read_b128 v[204:207], v165 offset:38912
	ds_read_b128 v[210:213], v165 offset:39936
	global_load_lds_dwordx4 v[216:217], off
	v_lshl_add_u64 v[216:217], v[214:215], 0, s[16:17]
	s_mov_b32 m0, s92
	s_nop 0
	global_load_lds_dwordx4 v[216:217], off
	s_waitcnt vmcnt(8)
	s_waitcnt lgkmcnt(0)
	s_barrier
	s_setprio 1
	s_waitcnt lgkmcnt(0)
	v_mfma_f32_16x16x32_bf16 v[124:127], v[128:131], v[180:183], v[124:127]
	v_mfma_f32_16x16x32_bf16 v[120:123], v[136:139], v[180:183], v[120:123]
	v_mfma_f32_16x16x32_bf16 v[108:111], v[128:131], v[188:191], v[108:111]
	v_mfma_f32_16x16x32_bf16 v[104:107], v[136:139], v[188:191], v[104:107]
	v_mfma_f32_16x16x32_bf16 v[92:95], v[128:131], v[196:199], v[92:95]
	v_mfma_f32_16x16x32_bf16 v[88:91], v[136:139], v[196:199], v[88:91]
	v_mfma_f32_16x16x32_bf16 v[76:79], v[128:131], v[204:207], v[76:79]
	v_mfma_f32_16x16x32_bf16 v[72:75], v[136:139], v[204:207], v[72:75]
	v_mfma_f32_16x16x32_bf16 v[124:127], v[132:135], v[184:187], v[124:127]
	v_mfma_f32_16x16x32_bf16 v[120:123], v[140:143], v[184:187], v[120:123]
	v_mfma_f32_16x16x32_bf16 v[108:111], v[132:135], v[192:195], v[108:111]
	v_mfma_f32_16x16x32_bf16 v[104:107], v[140:143], v[192:195], v[104:107]
	v_mfma_f32_16x16x32_bf16 v[92:95], v[132:135], v[200:203], v[92:95]
	v_mfma_f32_16x16x32_bf16 v[88:91], v[140:143], v[200:203], v[88:91]
	v_mfma_f32_16x16x32_bf16 v[76:79], v[132:135], v[210:213], v[76:79]
	v_mfma_f32_16x16x32_bf16 v[72:75], v[140:143], v[210:213], v[72:75]
	s_setprio 0
	s_setprio 1
	v_mfma_f32_16x16x32_bf16 v[116:119], v[152:155], v[180:183], v[116:119]
	v_mfma_f32_16x16x32_bf16 v[112:115], v[172:175], v[180:183], v[112:115]
	v_mfma_f32_16x16x32_bf16 v[100:103], v[152:155], v[188:191], v[100:103]
	v_mfma_f32_16x16x32_bf16 v[96:99], v[172:175], v[188:191], v[96:99]
	v_mfma_f32_16x16x32_bf16 v[84:87], v[152:155], v[196:199], v[84:87]
	v_mfma_f32_16x16x32_bf16 v[80:83], v[172:175], v[196:199], v[80:83]
	v_mfma_f32_16x16x32_bf16 v[68:71], v[152:155], v[204:207], v[68:71]
	v_mfma_f32_16x16x32_bf16 v[64:67], v[172:175], v[204:207], v[64:67]
	v_mfma_f32_16x16x32_bf16 v[116:119], v[168:171], v[184:187], v[116:119]
	v_mfma_f32_16x16x32_bf16 v[112:115], v[176:179], v[184:187], v[112:115]
	v_mfma_f32_16x16x32_bf16 v[100:103], v[168:171], v[192:195], v[100:103]
	v_mfma_f32_16x16x32_bf16 v[96:99], v[176:179], v[192:195], v[96:99]
	v_mfma_f32_16x16x32_bf16 v[84:87], v[168:171], v[200:203], v[84:87]
	v_mfma_f32_16x16x32_bf16 v[80:83], v[176:179], v[200:203], v[80:83]
	v_mfma_f32_16x16x32_bf16 v[68:71], v[168:171], v[210:213], v[68:71]
	v_mfma_f32_16x16x32_bf16 v[64:67], v[176:179], v[210:213], v[64:67]
	s_setprio 0
	s_barrier
; #define PG8_STAGE(bufoff, gbase, voff) do { _Pragma("unroll") for (int _i = 0; _i < 2; ++_i) \
;         __builtin_amdgcn_global_load_lds((const unsigned*)((const char*)(gbase) + (voff)[_i]), (PG8_LAS unsigned*)(lds + (bufoff) + ldsw + _i * 8192), 16, 0, 0); } while (0)
; #define PG8_LDA(dst, b, h) do { _Pragma("unroll") for (int m = 0; m < 4; ++m) _Pragma("unroll") for (int k = 0; k < 2; ++k) dst[m][k] = *(const PG8_LAS bf16x8*)(lds + PG8_SA(b, h) + aoff + m * 2048 + k * 1024); } while (0)
; #define PG8_LDB(dst, b, h) do { _Pragma("unroll") for (int n = 0; n < 2; ++n) _Pragma("unroll") for (int k = 0; k < 2; ++k) dst[n][k] = *(const PG8_LAS bf16x8*)(lds + PG8_SB(b, h) + boff + n * 2048 + k * 1024); } while (0)
; #define PG8_MMA(ai, bj, At, Bt) do { __builtin_amdgcn_s_setprio(1); _Pragma("unroll") for (int m = 0; m < 4; ++m) _Pragma("unroll") for (int n = 0; n < 2; ++n) _Pragma("unroll") for (int k = 0; k < 2; ++k) \
;         acc[ai][bj][m][n] = __builtin_amdgcn_mfma_f32_16x16x32_bf16(Bt[n][k], At[m][k], acc[ai][bj][m][n], 0, 0, 0); __builtin_amdgcn_s_setprio(0); } while (0)
; #define PG8_BAR __builtin_amdgcn_s_barrier()
; template <class Epi, class Sched, bool ALIGN_EPI = false, bool SP2 = false, bool TA = true>
; __device__ __forceinline__ void gemm_phase(PG8_LAS unsigned char* lds, const Gemm g, const Sched& S, const Epi& E) {
;     ...
;             PG8_LDB(B0, 0, 0); PG8_LDB(B1, 0, 1); PG8_SCHED; PG8_LDA(At, 0, 0); PG8_STAGE(PG8_SA(1, 1), a1 + hstep, voffA);
;             PG8_WAIT_V(8); PG8_WAIT_L(0); PG8_BAR; PG8_MMA(0, 0, At, B0); PG8_MMA(0, 1, At, B1); PG8_BAR; PG8_SCHED;
;             PG8_LDA(At, 0, 1); PG8_STAGE(PG8_SB(0, 0), b2, voffB); PG8_STAGE(PG8_SB(0, 1), b2 + hstep, voffB); PG8_STAGE(PG8_SA(0, 0), a2, voffA);
;             PG8_WAIT_V(8); PG8_WAIT_L(0); PG8_BAR; PG8_MMA(1, 0, At, B0); PG8_MMA(1, 1, At, B1); PG8_BAR; PG8_SCHED;
;             PG8_LDB(B0, 1, 0); PG8_LDB(B1, 1, 1); PG8_SCHED; PG8_LDA(At, 1, 0); PG8_STAGE(PG8_SA(0, 1), a2 + hstep, voffA);
;             PG8_WAIT_V(8); PG8_WAIT_L(0); PG8_BAR; PG8_MMA(0, 0, At, B0); PG8_MMA(0, 1, At, B1); PG8_BAR; PG8_SCHED;
;             PG8_LDA(At, 1, 1); PG8_STAGE(PG8_SB(1, 0), b3, voffB); PG8_STAGE(PG8_SB(1, 1), b3 + hstep, voffB); PG8_STAGE(PG8_SA(1, 0), a3, voffA);
;             PG8_WAIT_V(8); PG8_WAIT_L(0); PG8_BAR; PG8_MMA(1, 0, At, B0); PG8_MMA(1, 1, At, B1); PG8_BAR; PG8_SCHED;
	s_add_i32 s82, s82, s94
	v_lshl_add_u64 v[216:217], v[156:157], 0, s[50:51]
	s_mov_b32 m0, s82
	ds_read_b128 v[180:183], v165 offset:49152
	ds_read_b128 v[184:187], v165 offset:50176
	ds_read_b128 v[188:191], v165 offset:51200
	ds_read_b128 v[192:195], v165 offset:52224
	ds_read_b128 v[196:199], v165 offset:53248
	ds_read_b128 v[200:203], v165 offset:54272
	ds_read_b128 v[204:207], v165 offset:55296
	ds_read_b128 v[210:213], v165 offset:56320
	global_load_lds_dwordx4 v[216:217], off
	v_lshl_add_u64 v[216:217], v[156:157], 0, s[52:53]
	s_add_i32 m0, s82, 0x2000
	s_add_i32 s82, s83, s94
	global_load_lds_dwordx4 v[216:217], off
	v_lshl_add_u64 v[216:217], v[156:157], 0, s[54:55]
	s_mov_b32 m0, s82
	v_lshl_add_u64 v[156:157], v[156:157], 0, s[56:57]
	global_load_lds_dwordx4 v[216:217], off
	s_add_i32 m0, s82, 0x2000
	s_nop 0
	global_load_lds_dwordx4 v[156:157], off
	v_lshl_add_u64 v[156:157], v[214:215], 0, s[50:51]
	s_mov_b32 m0, s18
	s_nop 0
	global_load_lds_dwordx4 v[156:157], off
	v_lshl_add_u64 v[156:157], v[214:215], 0, s[52:53]
	s_mov_b32 m0, s19
	s_nop 0
	global_load_lds_dwordx4 v[156:157], off
	s_waitcnt vmcnt(8)
	s_waitcnt lgkmcnt(0)
	s_barrier
	s_setprio 1
	s_waitcnt lgkmcnt(0)
	v_mfma_f32_16x16x32_bf16 v[60:63], v[128:131], v[180:183], v[60:63]
	v_mfma_f32_16x16x32_bf16 v[56:59], v[136:139], v[180:183], v[56:59]
	v_mfma_f32_16x16x32_bf16 v[44:47], v[128:131], v[188:191], v[44:47]
	v_mfma_f32_16x16x32_bf16 v[40:43], v[136:139], v[188:191], v[40:43]
	v_mfma_f32_16x16x32_bf16 v[28:31], v[128:131], v[196:199], v[28:31]
	v_mfma_f32_16x16x32_bf16 v[24:27], v[136:139], v[196:199], v[24:27]
	v_mfma_f32_16x16x32_bf16 v[12:15], v[128:131], v[204:207], v[12:15]
	v_mfma_f32_16x16x32_bf16 v[8:11], v[136:139], v[204:207], v[8:11]
	v_mfma_f32_16x16x32_bf16 v[60:63], v[132:135], v[184:187], v[60:63]
	v_mfma_f32_16x16x32_bf16 v[56:59], v[140:143], v[184:187], v[56:59]
	v_mfma_f32_16x16x32_bf16 v[44:47], v[132:135], v[192:195], v[44:47]
	v_mfma_f32_16x16x32_bf16 v[40:43], v[140:143], v[192:195], v[40:43]
	v_mfma_f32_16x16x32_bf16 v[28:31], v[132:135], v[200:203], v[28:31]
	v_mfma_f32_16x16x32_bf16 v[24:27], v[140:143], v[200:203], v[24:27]
	v_mfma_f32_16x16x32_bf16 v[12:15], v[132:135], v[210:213], v[12:15]
	v_mfma_f32_16x16x32_bf16 v[8:11], v[140:143], v[210:213], v[8:11]
	s_setprio 0
	s_setprio 1
	v_mfma_f32_16x16x32_bf16 v[52:55], v[152:155], v[180:183], v[52:55]
	v_mfma_f32_16x16x32_bf16 v[48:51], v[172:175], v[180:183], v[48:51]
	v_mfma_f32_16x16x32_bf16 v[36:39], v[152:155], v[188:191], v[36:39]
	v_mfma_f32_16x16x32_bf16 v[32:35], v[172:175], v[188:191], v[32:35]
	v_mfma_f32_16x16x32_bf16 v[20:23], v[152:155], v[196:199], v[20:23]
	v_mfma_f32_16x16x32_bf16 v[16:19], v[172:175], v[196:199], v[16:19]
	v_mfma_f32_16x16x32_bf16 v[4:7], v[152:155], v[204:207], v[4:7]
	v_mfma_f32_16x16x32_bf16 v[0:3], v[172:175], v[204:207], v[0:3]
	v_mfma_f32_16x16x32_bf16 v[52:55], v[168:171], v[184:187], v[52:55]
	v_mfma_f32_16x16x32_bf16 v[48:51], v[176:179], v[184:187], v[48:51]
	v_mfma_f32_16x16x32_bf16 v[36:39], v[168:171], v[192:195], v[36:39]
	v_mfma_f32_16x16x32_bf16 v[32:35], v[176:179], v[192:195], v[32:35]
	v_mfma_f32_16x16x32_bf16 v[20:23], v[168:171], v[200:203], v[20:23]
	v_mfma_f32_16x16x32_bf16 v[16:19], v[176:179], v[200:203], v[16:19]
	v_mfma_f32_16x16x32_bf16 v[4:7], v[168:171], v[210:213], v[4:7]
	v_mfma_f32_16x16x32_bf16 v[0:3], v[176:179], v[210:213], v[0:3]
	s_setprio 0
	s_barrier
	s_add_i32 s81, s81, 2
	s_add_u32 s76, s76, 0x8000
	s_addc_u32 s77, s77, 0
	s_add_u32 s78, s78, 0x8000
	s_addc_u32 s79, s79, 0
	s_cmp_gt_u32 s81, 13

; #define PG8_STAGE(bufoff, gbase, voff) do { _Pragma("unroll") for (int _i = 0; _i < 2; ++_i) \
;         __builtin_amdgcn_global_load_lds((const unsigned*)((const char*)(gbase) + (voff)[_i]), (PG8_LAS unsigned*)(lds + (bufoff) + ldsw + _i * 8192), 16, 0, 0); } while (0)
; #define PG8_LDA(dst, b, h) do { _Pragma("unroll") for (int m = 0; m < 4; ++m) _Pragma("unroll") for (int k = 0; k < 2; ++k) dst[m][k] = *(const PG8_LAS bf16x8*)(lds + PG8_SA(b, h) + aoff + m * 2048 + k * 1024); } while (0)
; #define PG8_LDB(dst, b, h) do { _Pragma("unroll") for (int n = 0; n < 2; ++n) _Pragma("unroll") for (int k = 0; k < 2; ++k) dst[n][k] = *(const PG8_LAS bf16x8*)(lds + PG8_SB(b, h) + boff + n * 2048 + k * 1024); } while (0)
; #define PG8_WAIT_V(n) asm volatile("s_waitcnt vmcnt(" #n ")" ::: "memory")
; #define PG8_WAIT_L(n) asm volatile("s_waitcnt lgkmcnt(" #n ")" ::: "memory")
; #define PG8_BAR __builtin_amdgcn_s_barrier()
; #define PG8_SCHED __builtin_amdgcn_sched_barrier(0)
; template <class Epi, class Sched, bool ALIGN_EPI = false, bool SP2 = false, bool TA = true>
; __device__ __forceinline__ void gemm_phase(PG8_LAS unsigned char* lds, const Gemm g, const Sched& S, const Epi& E) {
;     ...
;         const bool has_next = S.next(ui + 1, nxt);
;         const char* nA = has_next ? (const char*)g.A + (size_t)nxt.pm * tstep : cA; const char* nB = has_next ? (const char*)g.Bt + (size_t)nxt.pn * tstep : cB;
; #pragma unroll 1
;         for (int t = 0; t < nt; t += 2) {
;             const bool last = (t == nt - 2);
;             const char* a1 = cA + (size_t)(t + 1) * kstep;
;             const char* a2 = last ? nA : cA + (size_t)(t + 2) * kstep; const char* b2 = last ? nB : cB + (size_t)(t + 2) * kstepB;
;             const char* a3 = a2 + kstep; const char* b3 = b2 + kstepB;
;             if (last && has_next) S.a_ready(nxt);
;             if constexpr (SP2) {
;             PG8_LDB(B0, 0, 0); PG8_LDB(B1, 0, 1); PG8_SCHED; PG8_LDA(At, 0, 0); PG8_STAGE(PG8_SA(1, 1), a1 + hstep, voffA);
;             PG8_WAIT_V(8); PG8_WAIT_L(0); PG8_BAR; PG8_MMA(0, 0, At, B0); PG8_MMA(0, 1, At, B1); PG8_BAR; PG8_SCHED;
;             PG8_LDA(At, 0, 1); PG8_STAGE(PG8_SB(0, 0), b2, voffB); PG8_STAGE(PG8_SB(0, 1), b2 + hstep, voffB); PG8_STAGE(PG8_SA(0, 0), a2, voffA);
;             PG8_WAIT_V(8); PG8_WAIT_L(0); PG8_BAR; PG8_MMA(1, 0, At, B0); PG8_MMA(1, 1, At, B1); PG8_BAR; PG8_SCHED;
.LBB0_1092:
	s_ashr_i32 s57, s56, 31
	s_lshl_b64 s[58:59], s[56:57], 19
	s_add_u32 s58, s8, s58
	s_addc_u32 s59, s9, s59
	s_and_b64 s[60:61], s[4:5], exec
	s_cselect_b32 s57, s59, s71
	s_cselect_b32 s69, s58, s70
	s_ashr_i32 s55, s54, 31
	s_lshl_b64 s[60:61], s[54:55], 19
	s_add_u32 s60, s18, s60
	s_addc_u32 s61, s19, s61
	s_and_b64 s[78:79], s[4:5], exec
	s_cselect_b32 s55, s61, s73
	s_cselect_b32 s77, s60, s72
	s_add_u32 s70, s70, 0x44000
	s_addc_u32 s71, s71, 0
	s_add_u32 s72, s72, 0x8000
	s_addc_u32 s73, s73, 0
	s_mov_b32 s78, -2
	ds_read_b128 v[128:131], v189
	ds_read_b128 v[132:135], v189 offset:1024
	ds_read_b128 v[136:139], v189 offset:2048
	s_waitcnt lgkmcnt(0)
	ds_read_b128 v[156:159], v189 offset:3072
	ds_read_b128 v[160:163], v190
	ds_read_b128 v[164:167], v190 offset:1024
	ds_read_b128 v[168:171], v190 offset:2048
	ds_read_b128 v[172:175], v190 offset:3072
	s_add_u32 s79, s70, 0xfffc4000
	s_addc_u32 s80, s71, -1
	s_cmp_eq_u32 s78, 12
	s_cselect_b32 s81, s57, s80
	s_cselect_b32 s80, s69, s79
	s_cselect_b32 s83, s55, s73
	s_cselect_b32 s82, s77, s72
	v_lshl_add_u64 v[218:219], s[70:71], 0, v[140:141]
	s_add_i32 m0, s22, 0xc000
	ds_read_b128 v[176:179], v191
	ds_read_b128 v[180:183], v191 offset:1024
	ds_read_b128 v[184:187], v191 offset:2048
	ds_read_b128 v[196:199], v191 offset:3072
	ds_read_b128 v[200:203], v191 offset:4096
	ds_read_b128 v[204:207], v191 offset:5120
	ds_read_b128 v[210:213], v191 offset:6144
	ds_read_b128 v[214:217], v191 offset:7168
	global_load_lds_dwordx4 v[218:219], off
	v_lshl_add_u64 v[218:219], v[218:219], 0, s[12:13]
	s_add_i32 m0, s22, 0xe000
	s_nop 0
	global_load_lds_dwordx4 v[218:219], off
	s_waitcnt vmcnt(8)
	s_waitcnt lgkmcnt(0)
	s_barrier
	s_setprio 1
	s_waitcnt lgkmcnt(0)
	v_mfma_f32_16x16x32_bf16 v[124:127], v[128:131], v[176:179], 0
	v_mfma_f32_16x16x32_bf16 v[120:123], v[136:139], v[176:179], 0
	v_mfma_f32_16x16x32_bf16 v[112:115], v[128:131], v[184:187], 0
	v_mfma_f32_16x16x32_bf16 v[104:107], v[136:139], v[184:187], 0
	v_mfma_f32_16x16x32_bf16 v[96:99], v[128:131], v[200:203], 0
	v_mfma_f32_16x16x32_bf16 v[88:91], v[136:139], v[200:203], 0
	v_mfma_f32_16x16x32_bf16 v[80:83], v[128:131], v[210:213], 0
	v_mfma_f32_16x16x32_bf16 v[72:75], v[136:139], v[210:213], 0
	v_mfma_f32_16x16x32_bf16 v[124:127], v[132:135], v[180:183], v[124:127]
	v_mfma_f32_16x16x32_bf16 v[120:123], v[156:159], v[180:183], v[120:123]
	v_mfma_f32_16x16x32_bf16 v[112:115], v[132:135], v[196:199], v[112:115]
	v_mfma_f32_16x16x32_bf16 v[104:107], v[156:159], v[196:199], v[104:107]
	v_mfma_f32_16x16x32_bf16 v[96:99], v[132:135], v[204:207], v[96:99]
	v_mfma_f32_16x16x32_bf16 v[88:91], v[156:159], v[204:207], v[88:91]
	v_mfma_f32_16x16x32_bf16 v[80:83], v[132:135], v[214:217], v[80:83]
	v_mfma_f32_16x16x32_bf16 v[72:75], v[156:159], v[214:217], v[72:75]
	s_setprio 0
	s_setprio 1
	v_mfma_f32_16x16x32_bf16 v[116:119], v[160:163], v[176:179], 0
	v_mfma_f32_16x16x32_bf16 v[108:111], v[168:171], v[176:179], 0
	v_mfma_f32_16x16x32_bf16 v[100:103], v[160:163], v[184:187], 0
	v_mfma_f32_16x16x32_bf16 v[92:95], v[168:171], v[184:187], 0
	v_mfma_f32_16x16x32_bf16 v[84:87], v[160:163], v[200:203], 0
	v_mfma_f32_16x16x32_bf16 v[76:79], v[168:171], v[200:203], 0
	v_mfma_f32_16x16x32_bf16 v[68:71], v[160:163], v[210:213], 0
	v_mfma_f32_16x16x32_bf16 v[64:67], v[168:171], v[210:213], 0
	v_mfma_f32_16x16x32_bf16 v[116:119], v[164:167], v[180:183], v[116:119]
	v_mfma_f32_16x16x32_bf16 v[108:111], v[172:175], v[180:183], v[108:111]
	v_mfma_f32_16x16x32_bf16 v[100:103], v[164:167], v[196:199], v[100:103]
	v_mfma_f32_16x16x32_bf16 v[92:95], v[172:175], v[196:199], v[92:95]
	v_mfma_f32_16x16x32_bf16 v[84:87], v[164:167], v[204:207], v[84:87]
	v_mfma_f32_16x16x32_bf16 v[76:79], v[172:175], v[204:207], v[76:79]
	v_mfma_f32_16x16x32_bf16 v[68:71], v[164:167], v[214:217], v[68:71]
	v_mfma_f32_16x16x32_bf16 v[64:67], v[172:175], v[214:217], v[64:67]
	s_setprio 0
	s_barrier
	s_add_i32 s79, s43, s21
	v_lshl_add_u64 v[218:219], s[82:83], 0, v[140:141]
	s_mov_b32 m0, s79
	ds_read_b128 v[176:179], v191 offset:16384
	ds_read_b128 v[180:183], v191 offset:17408
	ds_read_b128 v[184:187], v191 offset:18432
	ds_read_b128 v[196:199], v191 offset:19456
	ds_read_b128 v[200:203], v191 offset:20480
	ds_read_b128 v[204:207], v191 offset:21504
	ds_read_b128 v[210:213], v191 offset:22528
	ds_read_b128 v[214:217], v191 offset:23552
	global_load_lds_dwordx4 v[218:219], off
	v_lshl_add_u64 v[220:221], v[218:219], 0, s[12:13]
	s_add_i32 m0, s79, 0x2000
	s_add_i32 s79, s74, s21
	global_load_lds_dwordx4 v[220:221], off
	v_lshl_add_u64 v[220:221], v[218:219], 0, s[14:15]
	s_mov_b32 m0, s79
	s_nop 0
	global_load_lds_dwordx4 v[220:221], off
	v_lshl_add_u64 v[220:221], v[218:219], 0, s[16:17]
	s_add_i32 m0, s79, 0x2000
	s_nop 0
	global_load_lds_dwordx4 v[220:221], off
	v_lshl_add_u64 v[220:221], s[80:81], 0, v[140:141]
	s_mov_b32 m0, s22
	v_lshl_add_u64 v[222:223], v[220:221], 0, s[12:13]
	global_load_lds_dwordx4 v[220:221], off
	s_mov_b32 m0, s23
	s_nop 0
	global_load_lds_dwordx4 v[222:223], off
	s_waitcnt vmcnt(8)
	s_waitcnt lgkmcnt(0)
	s_barrier
; #define PG8_STAGE(bufoff, gbase, voff) do { _Pragma("unroll") for (int _i = 0; _i < 2; ++_i) \
;         __builtin_amdgcn_global_load_lds((const unsigned*)((const char*)(gbase) + (voff)[_i]), (PG8_LAS unsigned*)(lds + (bufoff) + ldsw + _i * 8192), 16, 0, 0); } while (0)
; #define PG8_LDA(dst, b, h) do { _Pragma("unroll") for (int m = 0; m < 4; ++m) _Pragma("unroll") for (int k = 0; k < 2; ++k) dst[m][k] = *(const PG8_LAS bf16x8*)(lds + PG8_SA(b, h) + aoff + m * 2048 + k * 1024); } while (0)
; #define PG8_LDB(dst, b, h) do { _Pragma("unroll") for (int n = 0; n < 2; ++n) _Pragma("unroll") for (int k = 0; k < 2; ++k) dst[n][k] = *(const PG8_LAS bf16x8*)(lds + PG8_SB(b, h) + boff + n * 2048 + k * 1024); } while (0)
; #define PG8_MMA(ai, bj, At, Bt) do { __builtin_amdgcn_s_setprio(1); _Pragma("unroll") for (int m = 0; m < 4; ++m) _Pragma("unroll") for (int n = 0; n < 2; ++n) _Pragma("unroll") for (int k = 0; k < 2; ++k) \
;         acc[ai][bj][m][n] = __builtin_amdgcn_mfma_f32_16x16x32_bf16(Bt[n][k], At[m][k], acc[ai][bj][m][n], 0, 0, 0); __builtin_amdgcn_s_setprio(0); } while (0)
; #define PG8_WAIT_V(n) asm volatile("s_waitcnt vmcnt(" #n ")" ::: "memory")
; #define PG8_WAIT_L(n) asm volatile("s_waitcnt lgkmcnt(" #n ")" ::: "memory")
; #define PG8_BAR __builtin_amdgcn_s_barrier()
; #define PG8_SCHED __builtin_amdgcn_sched_barrier(0)
; template <class Epi, class Sched, bool ALIGN_EPI = false, bool SP2 = false, bool TA = true>
; __device__ __forceinline__ void gemm_phase(PG8_LAS unsigned char* lds, const Gemm g, const Sched& S, const Epi& E) {
;     ...
;             PG8_WAIT_V(8); PG8_WAIT_L(0); PG8_BAR; PG8_MMA(0, 0, At, B0); PG8_MMA(0, 1, At, B1); PG8_BAR; PG8_SCHED;
;             PG8_LDA(At, 0, 1); PG8_STAGE(PG8_SB(0, 0), b2, voffB); PG8_STAGE(PG8_SB(0, 1), b2 + hstep, voffB); PG8_STAGE(PG8_SA(0, 0), a2, voffA);
;             PG8_WAIT_V(8); PG8_WAIT_L(0); PG8_BAR; PG8_MMA(1, 0, At, B0); PG8_MMA(1, 1, At, B1); PG8_BAR; PG8_SCHED;
;             PG8_LDB(B0, 1, 0); PG8_LDB(B1, 1, 1); PG8_SCHED; PG8_LDA(At, 1, 0); PG8_STAGE(PG8_SA(0, 1), a2 + hstep, voffA);
;             PG8_WAIT_V(8); PG8_WAIT_L(0); PG8_BAR; PG8_MMA(0, 0, At, B0); PG8_MMA(0, 1, At, B1); PG8_BAR; PG8_SCHED;
	s_setprio 1
	s_waitcnt lgkmcnt(0)
	v_mfma_f32_16x16x32_bf16 v[60:63], v[128:131], v[176:179], 0
	v_mfma_f32_16x16x32_bf16 v[56:59], v[136:139], v[176:179], 0
	v_mfma_f32_16x16x32_bf16 v[48:51], v[128:131], v[184:187], 0
	v_mfma_f32_16x16x32_bf16 v[40:43], v[136:139], v[184:187], 0
	v_mfma_f32_16x16x32_bf16 v[32:35], v[128:131], v[200:203], 0
	v_mfma_f32_16x16x32_bf16 v[24:27], v[136:139], v[200:203], 0
	v_mfma_f32_16x16x32_bf16 v[16:19], v[128:131], v[210:213], 0
	v_mfma_f32_16x16x32_bf16 v[8:11], v[136:139], v[210:213], 0
	v_mfma_f32_16x16x32_bf16 v[60:63], v[132:135], v[180:183], v[60:63]
	v_mfma_f32_16x16x32_bf16 v[56:59], v[156:159], v[180:183], v[56:59]
	v_mfma_f32_16x16x32_bf16 v[48:51], v[132:135], v[196:199], v[48:51]
	v_mfma_f32_16x16x32_bf16 v[40:43], v[156:159], v[196:199], v[40:43]
	v_mfma_f32_16x16x32_bf16 v[32:35], v[132:135], v[204:207], v[32:35]
	v_mfma_f32_16x16x32_bf16 v[24:27], v[156:159], v[204:207], v[24:27]
	v_mfma_f32_16x16x32_bf16 v[16:19], v[132:135], v[214:217], v[16:19]
	v_mfma_f32_16x16x32_bf16 v[8:11], v[156:159], v[214:217], v[8:11]
	s_setprio 0
	s_setprio 1
	v_mfma_f32_16x16x32_bf16 v[52:55], v[160:163], v[176:179], 0
	v_mfma_f32_16x16x32_bf16 v[44:47], v[168:171], v[176:179], 0
	v_mfma_f32_16x16x32_bf16 v[36:39], v[160:163], v[184:187], 0
	v_mfma_f32_16x16x32_bf16 v[28:31], v[168:171], v[184:187], 0
	v_mfma_f32_16x16x32_bf16 v[20:23], v[160:163], v[200:203], 0
	v_mfma_f32_16x16x32_bf16 v[12:15], v[168:171], v[200:203], 0
	v_mfma_f32_16x16x32_bf16 v[4:7], v[160:163], v[210:213], 0
	v_mfma_f32_16x16x32_bf16 v[0:3], v[168:171], v[210:213], 0
	v_mfma_f32_16x16x32_bf16 v[52:55], v[164:167], v[180:183], v[52:55]
	v_mfma_f32_16x16x32_bf16 v[44:47], v[172:175], v[180:183], v[44:47]
	v_mfma_f32_16x16x32_bf16 v[36:39], v[164:167], v[196:199], v[36:39]
	v_mfma_f32_16x16x32_bf16 v[28:31], v[172:175], v[196:199], v[28:31]
	v_mfma_f32_16x16x32_bf16 v[20:23], v[164:167], v[204:207], v[20:23]
	v_mfma_f32_16x16x32_bf16 v[12:15], v[172:175], v[204:207], v[12:15]
	v_mfma_f32_16x16x32_bf16 v[4:7], v[164:167], v[214:217], v[4:7]
	v_mfma_f32_16x16x32_bf16 v[0:3], v[172:175], v[214:217], v[0:3]
	s_setprio 0
	s_barrier
	s_add_i32 s79, 0, 0x18000
	v_add_u32_e32 v142, s79, v147
	s_add_i32 s80, 0, 0x1c000
	ds_read_b128 v[128:131], v142
	ds_read_b128 v[132:135], v142 offset:1024
	ds_read_b128 v[136:139], v142 offset:2048
	ds_read_b128 v[156:159], v142 offset:3072
	v_add_u32_e32 v142, s80, v147
	ds_read_b128 v[160:163], v142
	ds_read_b128 v[164:167], v142 offset:1024
	ds_read_b128 v[168:171], v142 offset:2048
	ds_read_b128 v[172:175], v142 offset:3072
	s_mov_b32 m0, s30
	v_lshl_add_u64 v[222:223], v[220:221], 0, s[14:15]
	ds_read_b128 v[176:179], v191 offset:32768
	ds_read_b128 v[180:183], v191 offset:33792
	ds_read_b128 v[184:187], v191 offset:34816
	ds_read_b128 v[196:199], v191 offset:35840
	ds_read_b128 v[200:203], v191 offset:36864
	ds_read_b128 v[204:207], v191 offset:37888
	ds_read_b128 v[210:213], v191 offset:38912
	ds_read_b128 v[214:217], v191 offset:39936
	global_load_lds_dwordx4 v[222:223], off
	v_lshl_add_u64 v[222:223], v[220:221], 0, s[16:17]
	s_mov_b32 m0, s31
	s_nop 0
	global_load_lds_dwordx4 v[222:223], off
	s_waitcnt vmcnt(8)
	s_waitcnt lgkmcnt(0)
	s_barrier
	s_setprio 1
	s_waitcnt lgkmcnt(0)
	v_mfma_f32_16x16x32_bf16 v[124:127], v[128:131], v[176:179], v[124:127]
	v_mfma_f32_16x16x32_bf16 v[120:123], v[136:139], v[176:179], v[120:123]
	v_mfma_f32_16x16x32_bf16 v[112:115], v[128:131], v[184:187], v[112:115]
	v_mfma_f32_16x16x32_bf16 v[104:107], v[136:139], v[184:187], v[104:107]
	v_mfma_f32_16x16x32_bf16 v[96:99], v[128:131], v[200:203], v[96:99]
	v_mfma_f32_16x16x32_bf16 v[88:91], v[136:139], v[200:203], v[88:91]
	v_mfma_f32_16x16x32_bf16 v[80:83], v[128:131], v[210:213], v[80:83]
	v_mfma_f32_16x16x32_bf16 v[72:75], v[136:139], v[210:213], v[72:75]
	v_mfma_f32_16x16x32_bf16 v[124:127], v[132:135], v[180:183], v[124:127]
	v_mfma_f32_16x16x32_bf16 v[120:123], v[156:159], v[180:183], v[120:123]
	v_mfma_f32_16x16x32_bf16 v[112:115], v[132:135], v[196:199], v[112:115]
	v_mfma_f32_16x16x32_bf16 v[104:107], v[156:159], v[196:199], v[104:107]
	v_mfma_f32_16x16x32_bf16 v[96:99], v[132:135], v[204:207], v[96:99]
	v_mfma_f32_16x16x32_bf16 v[88:91], v[156:159], v[204:207], v[88:91]
	v_mfma_f32_16x16x32_bf16 v[80:83], v[132:135], v[214:217], v[80:83]
	v_mfma_f32_16x16x32_bf16 v[72:75], v[156:159], v[214:217], v[72:75]
	s_setprio 0
	s_setprio 1
	v_mfma_f32_16x16x32_bf16 v[116:119], v[160:163], v[176:179], v[116:119]
	v_mfma_f32_16x16x32_bf16 v[108:111], v[168:171], v[176:179], v[108:111]
	v_mfma_f32_16x16x32_bf16 v[100:103], v[160:163], v[184:187], v[100:103]
	v_mfma_f32_16x16x32_bf16 v[92:95], v[168:171], v[184:187], v[92:95]
	v_mfma_f32_16x16x32_bf16 v[84:87], v[160:163], v[200:203], v[84:87]
	v_mfma_f32_16x16x32_bf16 v[76:79], v[168:171], v[200:203], v[76:79]
	v_mfma_f32_16x16x32_bf16 v[68:71], v[160:163], v[210:213], v[68:71]
	v_mfma_f32_16x16x32_bf16 v[64:67], v[168:171], v[210:213], v[64:67]
	v_mfma_f32_16x16x32_bf16 v[116:119], v[164:167], v[180:183], v[116:119]
	v_mfma_f32_16x16x32_bf16 v[108:111], v[172:175], v[180:183], v[108:111]
	v_mfma_f32_16x16x32_bf16 v[100:103], v[164:167], v[196:199], v[100:103]
	v_mfma_f32_16x16x32_bf16 v[92:95], v[172:175], v[196:199], v[92:95]
	v_mfma_f32_16x16x32_bf16 v[84:87], v[164:167], v[204:207], v[84:87]
	v_mfma_f32_16x16x32_bf16 v[76:79], v[172:175], v[204:207], v[76:79]
	v_mfma_f32_16x16x32_bf16 v[68:71], v[164:167], v[214:217], v[68:71]
	v_mfma_f32_16x16x32_bf16 v[64:67], v[172:175], v[214:217], v[64:67]
	s_setprio 0
	s_barrier
; #define PG8_STAGE(bufoff, gbase, voff) do { _Pragma("unroll") for (int _i = 0; _i < 2; ++_i) \
;         __builtin_amdgcn_global_load_lds((const unsigned*)((const char*)(gbase) + (voff)[_i]), (PG8_LAS unsigned*)(lds + (bufoff) + ldsw + _i * 8192), 16, 0, 0); } while (0)
; #define PG8_LDA(dst, b, h) do { _Pragma("unroll") for (int m = 0; m < 4; ++m) _Pragma("unroll") for (int k = 0; k < 2; ++k) dst[m][k] = *(const PG8_LAS bf16x8*)(lds + PG8_SA(b, h) + aoff + m * 2048 + k * 1024); } while (0)
; #define PG8_LDB(dst, b, h) do { _Pragma("unroll") for (int n = 0; n < 2; ++n) _Pragma("unroll") for (int k = 0; k < 2; ++k) dst[n][k] = *(const PG8_LAS bf16x8*)(lds + PG8_SB(b, h) + boff + n * 2048 + k * 1024); } while (0)
; #define PG8_MMA(ai, bj, At, Bt) do { __builtin_amdgcn_s_setprio(1); _Pragma("unroll") for (int m = 0; m < 4; ++m) _Pragma("unroll") for (int n = 0; n < 2; ++n) _Pragma("unroll") for (int k = 0; k < 2; ++k) \
;         acc[ai][bj][m][n] = __builtin_amdgcn_mfma_f32_16x16x32_bf16(Bt[n][k], At[m][k], acc[ai][bj][m][n], 0, 0, 0); __builtin_amdgcn_s_setprio(0); } while (0)
; #define PG8_WAIT_V(n) asm volatile("s_waitcnt vmcnt(" #n ")" ::: "memory")
; #define PG8_WAIT_L(n) asm volatile("s_waitcnt lgkmcnt(" #n ")" ::: "memory")
; #define PG8_BAR __builtin_amdgcn_s_barrier()
; template <class Epi, class Sched, bool ALIGN_EPI = false, bool SP2 = false, bool TA = true>
; __device__ __forceinline__ void gemm_phase(PG8_LAS unsigned char* lds, const Gemm g, const Sched& S, const Epi& E) {
;     ...
;         for (int t = 0; t < nt; t += 2) {
;             const bool last = (t == nt - 2);
;             const char* a1 = cA + (size_t)(t + 1) * kstep;
;             const char* a2 = last ? nA : cA + (size_t)(t + 2) * kstep; const char* b2 = last ? nB : cB + (size_t)(t + 2) * kstepB;
;             const char* a3 = a2 + kstep; const char* b3 = b2 + kstepB;
;     ...
;             PG8_LDB(B0, 1, 0); PG8_LDB(B1, 1, 1); PG8_SCHED; PG8_LDA(At, 1, 0); PG8_STAGE(PG8_SA(0, 1), a2 + hstep, voffA);
;             PG8_WAIT_V(8); PG8_WAIT_L(0); PG8_BAR; PG8_MMA(0, 0, At, B0); PG8_MMA(0, 1, At, B1); PG8_BAR; PG8_SCHED;
;             PG8_LDA(At, 1, 1); PG8_STAGE(PG8_SB(1, 0), b3, voffB); PG8_STAGE(PG8_SB(1, 1), b3 + hstep, voffB); PG8_STAGE(PG8_SA(1, 0), a3, voffA);
;             PG8_WAIT_V(8); PG8_WAIT_L(0); PG8_BAR; PG8_MMA(1, 0, At, B0); PG8_MMA(1, 1, At, B1); PG8_BAR; PG8_SCHED;
	s_add_i32 s79, s79, s21
	v_lshl_add_u64 v[222:223], v[218:219], 0, s[44:45]
	s_mov_b32 m0, s79
	ds_read_b128 v[176:179], v191 offset:49152
	ds_read_b128 v[180:183], v191 offset:50176
	ds_read_b128 v[184:187], v191 offset:51200
	ds_read_b128 v[196:199], v191 offset:52224
	ds_read_b128 v[200:203], v191 offset:53248
	ds_read_b128 v[204:207], v191 offset:54272
	ds_read_b128 v[210:213], v191 offset:55296
	ds_read_b128 v[214:217], v191 offset:56320
	global_load_lds_dwordx4 v[222:223], off
	v_lshl_add_u64 v[222:223], v[218:219], 0, s[46:47]
	s_add_i32 m0, s79, 0x2000
	s_add_i32 s79, s80, s21
	global_load_lds_dwordx4 v[222:223], off
	v_lshl_add_u64 v[222:223], v[218:219], 0, s[48:49]
	s_mov_b32 m0, s79
	v_lshl_add_u64 v[218:219], v[218:219], 0, s[50:51]
	global_load_lds_dwordx4 v[222:223], off
	s_add_i32 m0, s79, 0x2000
	s_nop 0
	global_load_lds_dwordx4 v[218:219], off
	v_lshl_add_u64 v[218:219], v[220:221], 0, s[44:45]
	s_mov_b32 m0, s33
	s_nop 0
	global_load_lds_dwordx4 v[218:219], off
	v_lshl_add_u64 v[218:219], v[220:221], 0, s[46:47]
	s_mov_b32 m0, s36
	s_nop 0
	global_load_lds_dwordx4 v[218:219], off
	s_waitcnt vmcnt(8)
	s_waitcnt lgkmcnt(0)
	s_barrier
	s_setprio 1
	s_waitcnt lgkmcnt(0)
	v_mfma_f32_16x16x32_bf16 v[60:63], v[128:131], v[176:179], v[60:63]
	v_mfma_f32_16x16x32_bf16 v[56:59], v[136:139], v[176:179], v[56:59]
	v_mfma_f32_16x16x32_bf16 v[48:51], v[128:131], v[184:187], v[48:51]
	v_mfma_f32_16x16x32_bf16 v[40:43], v[136:139], v[184:187], v[40:43]
	v_mfma_f32_16x16x32_bf16 v[32:35], v[128:131], v[200:203], v[32:35]
	v_mfma_f32_16x16x32_bf16 v[24:27], v[136:139], v[200:203], v[24:27]
	v_mfma_f32_16x16x32_bf16 v[16:19], v[128:131], v[210:213], v[16:19]
	v_mfma_f32_16x16x32_bf16 v[8:11], v[136:139], v[210:213], v[8:11]
	v_mfma_f32_16x16x32_bf16 v[60:63], v[132:135], v[180:183], v[60:63]
	v_mfma_f32_16x16x32_bf16 v[56:59], v[156:159], v[180:183], v[56:59]
	v_mfma_f32_16x16x32_bf16 v[48:51], v[132:135], v[196:199], v[48:51]
	v_mfma_f32_16x16x32_bf16 v[40:43], v[156:159], v[196:199], v[40:43]
	v_mfma_f32_16x16x32_bf16 v[32:35], v[132:135], v[204:207], v[32:35]
	v_mfma_f32_16x16x32_bf16 v[24:27], v[156:159], v[204:207], v[24:27]
	v_mfma_f32_16x16x32_bf16 v[16:19], v[132:135], v[214:217], v[16:19]
	v_mfma_f32_16x16x32_bf16 v[8:11], v[156:159], v[214:217], v[8:11]
	s_setprio 0
	s_setprio 1
	v_mfma_f32_16x16x32_bf16 v[52:55], v[160:163], v[176:179], v[52:55]
	v_mfma_f32_16x16x32_bf16 v[44:47], v[168:171], v[176:179], v[44:47]
	v_mfma_f32_16x16x32_bf16 v[36:39], v[160:163], v[184:187], v[36:39]
	v_mfma_f32_16x16x32_bf16 v[28:31], v[168:171], v[184:187], v[28:31]
	v_mfma_f32_16x16x32_bf16 v[20:23], v[160:163], v[200:203], v[20:23]
	v_mfma_f32_16x16x32_bf16 v[12:15], v[168:171], v[200:203], v[12:15]
	v_mfma_f32_16x16x32_bf16 v[4:7], v[160:163], v[210:213], v[4:7]
	v_mfma_f32_16x16x32_bf16 v[0:3], v[168:171], v[210:213], v[0:3]
	v_mfma_f32_16x16x32_bf16 v[52:55], v[164:167], v[180:183], v[52:55]
	v_mfma_f32_16x16x32_bf16 v[44:47], v[172:175], v[180:183], v[44:47]
	v_mfma_f32_16x16x32_bf16 v[36:39], v[164:167], v[196:199], v[36:39]
	v_mfma_f32_16x16x32_bf16 v[28:31], v[172:175], v[196:199], v[28:31]
	v_mfma_f32_16x16x32_bf16 v[20:23], v[164:167], v[204:207], v[20:23]
	v_mfma_f32_16x16x32_bf16 v[12:15], v[172:175], v[204:207], v[12:15]
	v_mfma_f32_16x16x32_bf16 v[4:7], v[164:167], v[214:217], v[4:7]
	v_mfma_f32_16x16x32_bf16 v[0:3], v[172:175], v[214:217], v[0:3]
	s_setprio 0
	s_barrier
	s_add_i32 s78, s78, 2
	s_add_u32 s70, s70, 0x8000
	s_addc_u32 s71, s71, 0
	s_add_u32 s72, s72, 0x8000
	s_addc_u32 s73, s73, 0
	s_cmp_gt_u32 s78, 13

; #define PG8_STAGE(bufoff, gbase, voff) do { _Pragma("unroll") for (int _i = 0; _i < 2; ++_i) \
;         __builtin_amdgcn_global_load_lds((const unsigned*)((const char*)(gbase) + (voff)[_i]), (PG8_LAS unsigned*)(lds + (bufoff) + ldsw + _i * 8192), 16, 0, 0); } while (0)
; #define PG8_LDA(dst, b, h) do { _Pragma("unroll") for (int m = 0; m < 4; ++m) _Pragma("unroll") for (int k = 0; k < 2; ++k) dst[m][k] = *(const PG8_LAS bf16x8*)(lds + PG8_SA(b, h) + aoff + m * 2048 + k * 1024); } while (0)
; #define PG8_LDB(dst, b, h) do { _Pragma("unroll") for (int n = 0; n < 2; ++n) _Pragma("unroll") for (int k = 0; k < 2; ++k) dst[n][k] = *(const PG8_LAS bf16x8*)(lds + PG8_SB(b, h) + boff + n * 2048 + k * 1024); } while (0)
; #define PG8_WAIT_V(n) asm volatile("s_waitcnt vmcnt(" #n ")" ::: "memory")
; #define PG8_WAIT_L(n) asm volatile("s_waitcnt lgkmcnt(" #n ")" ::: "memory")
; #define PG8_BAR __builtin_amdgcn_s_barrier()
; #define PG8_SCHED __builtin_amdgcn_sched_barrier(0)
; template <class Epi, class Sched, bool ALIGN_EPI = false, bool SP2 = false, bool TA = true>
; __device__ __forceinline__ void gemm_phase(PG8_LAS unsigned char* lds, const Gemm g, const Sched& S, const Epi& E) {
;     ...
;         const bool has_next = S.next(ui + 1, nxt);
;         const char* nA = has_next ? (const char*)g.A + (size_t)nxt.pm * tstep : cA; const char* nB = has_next ? (const char*)g.Bt + (size_t)nxt.pn * tstep : cB;
; #pragma unroll 1
;         for (int t = 0; t < nt; t += 2) {
;             const bool last = (t == nt - 2);
;             const char* a1 = cA + (size_t)(t + 1) * kstep;
;             const char* a2 = last ? nA : cA + (size_t)(t + 2) * kstep; const char* b2 = last ? nB : cB + (size_t)(t + 2) * kstepB;
;             const char* a3 = a2 + kstep; const char* b3 = b2 + kstepB;
;             if (last && has_next) S.a_ready(nxt);
;             if constexpr (SP2) {
;             PG8_LDB(B0, 0, 0); PG8_LDB(B1, 0, 1); PG8_SCHED; PG8_LDA(At, 0, 0); PG8_STAGE(PG8_SA(1, 1), a1 + hstep, voffA);
;             PG8_WAIT_V(8); PG8_WAIT_L(0); PG8_BAR; PG8_MMA(0, 0, At, B0); PG8_MMA(0, 1, At, B1); PG8_BAR; PG8_SCHED;
;             PG8_LDA(At, 0, 1); PG8_STAGE(PG8_SB(0, 0), b2, voffB); PG8_STAGE(PG8_SB(0, 1), b2 + hstep, voffB); PG8_STAGE(PG8_SA(0, 0), a2, voffA);
;             PG8_WAIT_V(8); PG8_WAIT_L(0); PG8_BAR; PG8_MMA(1, 0, At, B0); PG8_MMA(1, 1, At, B1); PG8_BAR; PG8_SCHED;
.LBB0_1535:
	s_ashr_i32 s49, s48, 31
	s_lshl_b64 s[50:51], s[48:49], 19
	s_add_u32 s50, s34, s50
	s_addc_u32 s51, s35, s51
	s_and_b64 s[52:53], s[4:5], exec
	s_cselect_b32 s49, s51, s57
	s_cselect_b32 s55, s50, s56
	s_ashr_i32 s47, s46, 31
	s_lshl_b64 s[52:53], s[46:47], 19
	s_add_u32 s52, s18, s52
	s_addc_u32 s53, s19, s53
	s_and_b64 s[60:61], s[4:5], exec
	s_cselect_b32 s47, s53, s59
	s_cselect_b32 s60, s52, s58
	s_add_u32 s56, s56, 0x44000
	s_addc_u32 s57, s57, 0
	s_add_u32 s58, s58, 0x8000
	s_addc_u32 s59, s59, 0
	s_mov_b32 s61, -2
	s_waitcnt lgkmcnt(0)
	ds_read_b128 v[128:131], v149
	ds_read_b128 v[142:145], v149 offset:1024
	ds_read_b128 v[154:157], v149 offset:2048
	ds_read_b128 v[158:161], v149 offset:3072
	ds_read_b128 v[162:165], v150
	ds_read_b128 v[166:169], v150 offset:1024
	ds_read_b128 v[170:173], v150 offset:2048
	ds_read_b128 v[174:177], v150 offset:3072
	s_add_u32 s62, s56, 0xfffc4000
	s_addc_u32 s63, s57, -1
	s_cmp_eq_u32 s61, 12
	s_cselect_b32 s63, s49, s63
	s_cselect_b32 s62, s55, s62
	s_cselect_b32 s65, s47, s59
	s_cselect_b32 s64, s60, s58
	v_lshl_add_u64 v[132:133], s[56:57], 0, v[134:135]
	s_add_i32 m0, s22, 0xc000
	ds_read_b128 v[178:181], v151
	ds_read_b128 v[182:185], v151 offset:1024
	ds_read_b128 v[186:189], v151 offset:2048
	ds_read_b128 v[190:193], v151 offset:3072
	ds_read_b128 v[194:197], v151 offset:4096
	ds_read_b128 v[198:201], v151 offset:5120
	ds_read_b128 v[202:205], v151 offset:6144
	ds_read_b128 v[210:213], v151 offset:7168
	global_load_lds_dwordx4 v[132:133], off
	v_lshl_add_u64 v[132:133], v[132:133], 0, s[6:7]
	s_add_i32 m0, s22, 0xe000
	s_nop 0
	global_load_lds_dwordx4 v[132:133], off
	s_waitcnt vmcnt(8)
	s_waitcnt lgkmcnt(0)
	s_barrier
	s_setprio 1
	s_waitcnt lgkmcnt(0)
	v_mfma_f32_16x16x32_bf16 v[124:127], v[128:131], v[178:181], 0
	v_mfma_f32_16x16x32_bf16 v[120:123], v[154:157], v[178:181], 0
	v_mfma_f32_16x16x32_bf16 v[108:111], v[128:131], v[186:189], 0
	v_mfma_f32_16x16x32_bf16 v[104:107], v[154:157], v[186:189], 0
	v_mfma_f32_16x16x32_bf16 v[92:95], v[128:131], v[194:197], 0
	v_mfma_f32_16x16x32_bf16 v[88:91], v[154:157], v[194:197], 0
	v_mfma_f32_16x16x32_bf16 v[76:79], v[128:131], v[202:205], 0
	v_mfma_f32_16x16x32_bf16 v[72:75], v[154:157], v[202:205], 0
	v_mfma_f32_16x16x32_bf16 v[124:127], v[142:145], v[182:185], v[124:127]
	v_mfma_f32_16x16x32_bf16 v[120:123], v[158:161], v[182:185], v[120:123]
	v_mfma_f32_16x16x32_bf16 v[108:111], v[142:145], v[190:193], v[108:111]
	v_mfma_f32_16x16x32_bf16 v[104:107], v[158:161], v[190:193], v[104:107]
	v_mfma_f32_16x16x32_bf16 v[92:95], v[142:145], v[198:201], v[92:95]
	v_mfma_f32_16x16x32_bf16 v[88:91], v[158:161], v[198:201], v[88:91]
	v_mfma_f32_16x16x32_bf16 v[76:79], v[142:145], v[210:213], v[76:79]
	v_mfma_f32_16x16x32_bf16 v[72:75], v[158:161], v[210:213], v[72:75]
	s_setprio 0
	s_setprio 1
	v_mfma_f32_16x16x32_bf16 v[116:119], v[162:165], v[178:181], 0
	v_mfma_f32_16x16x32_bf16 v[112:115], v[170:173], v[178:181], 0
	v_mfma_f32_16x16x32_bf16 v[100:103], v[162:165], v[186:189], 0
	v_mfma_f32_16x16x32_bf16 v[96:99], v[170:173], v[186:189], 0
	v_mfma_f32_16x16x32_bf16 v[84:87], v[162:165], v[194:197], 0
	v_mfma_f32_16x16x32_bf16 v[80:83], v[170:173], v[194:197], 0
	v_mfma_f32_16x16x32_bf16 v[68:71], v[162:165], v[202:205], 0
	v_mfma_f32_16x16x32_bf16 v[64:67], v[170:173], v[202:205], 0
	v_mfma_f32_16x16x32_bf16 v[116:119], v[166:169], v[182:185], v[116:119]
	v_mfma_f32_16x16x32_bf16 v[112:115], v[174:177], v[182:185], v[112:115]
	v_mfma_f32_16x16x32_bf16 v[100:103], v[166:169], v[190:193], v[100:103]
	v_mfma_f32_16x16x32_bf16 v[96:99], v[174:177], v[190:193], v[96:99]
	v_mfma_f32_16x16x32_bf16 v[84:87], v[166:169], v[198:201], v[84:87]
	v_mfma_f32_16x16x32_bf16 v[80:83], v[174:177], v[198:201], v[80:83]
	v_mfma_f32_16x16x32_bf16 v[68:71], v[166:169], v[210:213], v[68:71]
	v_mfma_f32_16x16x32_bf16 v[64:67], v[174:177], v[210:213], v[64:67]
	s_setprio 0
	s_barrier
	v_lshl_add_u64 v[132:133], s[64:65], 0, v[134:135]
	s_add_i32 s64, s76, s21
	s_mov_b32 m0, s64
	ds_read_b128 v[178:181], v151 offset:16384
	ds_read_b128 v[182:185], v151 offset:17408
	ds_read_b128 v[186:189], v151 offset:18432
	ds_read_b128 v[190:193], v151 offset:19456
	ds_read_b128 v[194:197], v151 offset:20480
	ds_read_b128 v[198:201], v151 offset:21504
	ds_read_b128 v[202:205], v151 offset:22528
	ds_read_b128 v[210:213], v151 offset:23552
	global_load_lds_dwordx4 v[132:133], off
	v_lshl_add_u64 v[206:207], v[132:133], 0, s[6:7]
	s_add_i32 m0, s64, 0x2000
	s_add_i32 s64, s77, s21
	global_load_lds_dwordx4 v[206:207], off
	v_lshl_add_u64 v[206:207], v[132:133], 0, s[12:13]
	s_mov_b32 m0, s64
	s_nop 0
	global_load_lds_dwordx4 v[206:207], off
	v_lshl_add_u64 v[206:207], v[132:133], 0, s[14:15]
	s_add_i32 m0, s64, 0x2000
	s_nop 0
	global_load_lds_dwordx4 v[206:207], off
	v_lshl_add_u64 v[206:207], s[62:63], 0, v[134:135]
	s_mov_b32 m0, s22
	v_lshl_add_u64 v[214:215], v[206:207], 0, s[6:7]
	global_load_lds_dwordx4 v[206:207], off
	s_mov_b32 m0, s23
	s_nop 0
	global_load_lds_dwordx4 v[214:215], off
	s_waitcnt vmcnt(8)
	s_waitcnt lgkmcnt(0)
	s_barrier
; #define PG8_STAGE(bufoff, gbase, voff) do { _Pragma("unroll") for (int _i = 0; _i < 2; ++_i) \
;         __builtin_amdgcn_global_load_lds((const unsigned*)((const char*)(gbase) + (voff)[_i]), (PG8_LAS unsigned*)(lds + (bufoff) + ldsw + _i * 8192), 16, 0, 0); } while (0)
; #define PG8_LDA(dst, b, h) do { _Pragma("unroll") for (int m = 0; m < 4; ++m) _Pragma("unroll") for (int k = 0; k < 2; ++k) dst[m][k] = *(const PG8_LAS bf16x8*)(lds + PG8_SA(b, h) + aoff + m * 2048 + k * 1024); } while (0)
; #define PG8_LDB(dst, b, h) do { _Pragma("unroll") for (int n = 0; n < 2; ++n) _Pragma("unroll") for (int k = 0; k < 2; ++k) dst[n][k] = *(const PG8_LAS bf16x8*)(lds + PG8_SB(b, h) + boff + n * 2048 + k * 1024); } while (0)
; #define PG8_MMA(ai, bj, At, Bt) do { __builtin_amdgcn_s_setprio(1); _Pragma("unroll") for (int m = 0; m < 4; ++m) _Pragma("unroll") for (int n = 0; n < 2; ++n) _Pragma("unroll") for (int k = 0; k < 2; ++k) \
;         acc[ai][bj][m][n] = __builtin_amdgcn_mfma_f32_16x16x32_bf16(Bt[n][k], At[m][k], acc[ai][bj][m][n], 0, 0, 0); __builtin_amdgcn_s_setprio(0); } while (0)
; #define PG8_WAIT_V(n) asm volatile("s_waitcnt vmcnt(" #n ")" ::: "memory")
; #define PG8_WAIT_L(n) asm volatile("s_waitcnt lgkmcnt(" #n ")" ::: "memory")
; #define PG8_BAR __builtin_amdgcn_s_barrier()
; #define PG8_SCHED __builtin_amdgcn_sched_barrier(0)
; template <class Epi, class Sched, bool ALIGN_EPI = false, bool SP2 = false, bool TA = true>
; __device__ __forceinline__ void gemm_phase(PG8_LAS unsigned char* lds, const Gemm g, const Sched& S, const Epi& E) {
;     ...
;             PG8_WAIT_V(8); PG8_WAIT_L(0); PG8_BAR; PG8_MMA(0, 0, At, B0); PG8_MMA(0, 1, At, B1); PG8_BAR; PG8_SCHED;
;             PG8_LDA(At, 0, 1); PG8_STAGE(PG8_SB(0, 0), b2, voffB); PG8_STAGE(PG8_SB(0, 1), b2 + hstep, voffB); PG8_STAGE(PG8_SA(0, 0), a2, voffA);
;             PG8_WAIT_V(8); PG8_WAIT_L(0); PG8_BAR; PG8_MMA(1, 0, At, B0); PG8_MMA(1, 1, At, B1); PG8_BAR; PG8_SCHED;
;             PG8_LDB(B0, 1, 0); PG8_LDB(B1, 1, 1); PG8_SCHED; PG8_LDA(At, 1, 0); PG8_STAGE(PG8_SA(0, 1), a2 + hstep, voffA);
;             PG8_WAIT_V(8); PG8_WAIT_L(0); PG8_BAR; PG8_MMA(0, 0, At, B0); PG8_MMA(0, 1, At, B1); PG8_BAR; PG8_SCHED;
	s_setprio 1
	s_waitcnt lgkmcnt(0)
	v_mfma_f32_16x16x32_bf16 v[60:63], v[128:131], v[178:181], 0
	v_mfma_f32_16x16x32_bf16 v[56:59], v[154:157], v[178:181], 0
	v_mfma_f32_16x16x32_bf16 v[44:47], v[128:131], v[186:189], 0
	v_mfma_f32_16x16x32_bf16 v[40:43], v[154:157], v[186:189], 0
	v_mfma_f32_16x16x32_bf16 v[28:31], v[128:131], v[194:197], 0
	v_mfma_f32_16x16x32_bf16 v[24:27], v[154:157], v[194:197], 0
	v_mfma_f32_16x16x32_bf16 v[12:15], v[128:131], v[202:205], 0
	v_mfma_f32_16x16x32_bf16 v[8:11], v[154:157], v[202:205], 0
	v_mfma_f32_16x16x32_bf16 v[60:63], v[142:145], v[182:185], v[60:63]
	v_mfma_f32_16x16x32_bf16 v[56:59], v[158:161], v[182:185], v[56:59]
	v_mfma_f32_16x16x32_bf16 v[44:47], v[142:145], v[190:193], v[44:47]
	v_mfma_f32_16x16x32_bf16 v[40:43], v[158:161], v[190:193], v[40:43]
	v_mfma_f32_16x16x32_bf16 v[28:31], v[142:145], v[198:201], v[28:31]
	v_mfma_f32_16x16x32_bf16 v[24:27], v[158:161], v[198:201], v[24:27]
	v_mfma_f32_16x16x32_bf16 v[12:15], v[142:145], v[210:213], v[12:15]
	v_mfma_f32_16x16x32_bf16 v[8:11], v[158:161], v[210:213], v[8:11]
	s_setprio 0
	s_setprio 1
	v_mfma_f32_16x16x32_bf16 v[52:55], v[162:165], v[178:181], 0
	v_mfma_f32_16x16x32_bf16 v[48:51], v[170:173], v[178:181], 0
	v_mfma_f32_16x16x32_bf16 v[36:39], v[162:165], v[186:189], 0
	v_mfma_f32_16x16x32_bf16 v[32:35], v[170:173], v[186:189], 0
	v_mfma_f32_16x16x32_bf16 v[20:23], v[162:165], v[194:197], 0
	v_mfma_f32_16x16x32_bf16 v[16:19], v[170:173], v[194:197], 0
	v_mfma_f32_16x16x32_bf16 v[4:7], v[162:165], v[202:205], 0
	v_mfma_f32_16x16x32_bf16 v[0:3], v[170:173], v[202:205], 0
	v_mfma_f32_16x16x32_bf16 v[52:55], v[166:169], v[182:185], v[52:55]
	v_mfma_f32_16x16x32_bf16 v[48:51], v[174:177], v[182:185], v[48:51]
	v_mfma_f32_16x16x32_bf16 v[36:39], v[166:169], v[190:193], v[36:39]
	v_mfma_f32_16x16x32_bf16 v[32:35], v[174:177], v[190:193], v[32:35]
	v_mfma_f32_16x16x32_bf16 v[20:23], v[166:169], v[198:201], v[20:23]
	v_mfma_f32_16x16x32_bf16 v[16:19], v[174:177], v[198:201], v[16:19]
	v_mfma_f32_16x16x32_bf16 v[4:7], v[166:169], v[210:213], v[4:7]
	v_mfma_f32_16x16x32_bf16 v[0:3], v[174:177], v[210:213], v[0:3]
	s_setprio 0
	s_barrier
	s_add_i32 s62, 0, 0x18000
	v_add_u32_e32 v136, s62, v148
	s_add_i32 s63, 0, 0x1c000
	ds_read_b128 v[128:131], v136
	ds_read_b128 v[142:145], v136 offset:1024
	ds_read_b128 v[154:157], v136 offset:2048
	ds_read_b128 v[158:161], v136 offset:3072
	v_add_u32_e32 v136, s63, v148
	ds_read_b128 v[162:165], v136
	ds_read_b128 v[166:169], v136 offset:1024
	ds_read_b128 v[170:173], v136 offset:2048
	ds_read_b128 v[174:177], v136 offset:3072
	s_mov_b32 m0, s30
	v_lshl_add_u64 v[214:215], v[206:207], 0, s[12:13]
	ds_read_b128 v[178:181], v151 offset:32768
	ds_read_b128 v[182:185], v151 offset:33792
	ds_read_b128 v[186:189], v151 offset:34816
	ds_read_b128 v[190:193], v151 offset:35840
	ds_read_b128 v[194:197], v151 offset:36864
	ds_read_b128 v[198:201], v151 offset:37888
	ds_read_b128 v[202:205], v151 offset:38912
	ds_read_b128 v[210:213], v151 offset:39936
	global_load_lds_dwordx4 v[214:215], off
	v_lshl_add_u64 v[214:215], v[206:207], 0, s[14:15]
	s_mov_b32 m0, s31
	s_nop 0
	global_load_lds_dwordx4 v[214:215], off
	s_waitcnt vmcnt(8)
	s_waitcnt lgkmcnt(0)
	s_barrier
	s_setprio 1
	s_waitcnt lgkmcnt(0)
	v_mfma_f32_16x16x32_bf16 v[124:127], v[128:131], v[178:181], v[124:127]
	v_mfma_f32_16x16x32_bf16 v[120:123], v[154:157], v[178:181], v[120:123]
	v_mfma_f32_16x16x32_bf16 v[108:111], v[128:131], v[186:189], v[108:111]
	v_mfma_f32_16x16x32_bf16 v[104:107], v[154:157], v[186:189], v[104:107]
	v_mfma_f32_16x16x32_bf16 v[92:95], v[128:131], v[194:197], v[92:95]
	v_mfma_f32_16x16x32_bf16 v[88:91], v[154:157], v[194:197], v[88:91]
	v_mfma_f32_16x16x32_bf16 v[76:79], v[128:131], v[202:205], v[76:79]
	v_mfma_f32_16x16x32_bf16 v[72:75], v[154:157], v[202:205], v[72:75]
	v_mfma_f32_16x16x32_bf16 v[124:127], v[142:145], v[182:185], v[124:127]
	v_mfma_f32_16x16x32_bf16 v[120:123], v[158:161], v[182:185], v[120:123]
	v_mfma_f32_16x16x32_bf16 v[108:111], v[142:145], v[190:193], v[108:111]
	v_mfma_f32_16x16x32_bf16 v[104:107], v[158:161], v[190:193], v[104:107]
	v_mfma_f32_16x16x32_bf16 v[92:95], v[142:145], v[198:201], v[92:95]
	v_mfma_f32_16x16x32_bf16 v[88:91], v[158:161], v[198:201], v[88:91]
	v_mfma_f32_16x16x32_bf16 v[76:79], v[142:145], v[210:213], v[76:79]
	v_mfma_f32_16x16x32_bf16 v[72:75], v[158:161], v[210:213], v[72:75]
	s_setprio 0
	s_setprio 1
	v_mfma_f32_16x16x32_bf16 v[116:119], v[162:165], v[178:181], v[116:119]
	v_mfma_f32_16x16x32_bf16 v[112:115], v[170:173], v[178:181], v[112:115]
	v_mfma_f32_16x16x32_bf16 v[100:103], v[162:165], v[186:189], v[100:103]
	v_mfma_f32_16x16x32_bf16 v[96:99], v[170:173], v[186:189], v[96:99]
	v_mfma_f32_16x16x32_bf16 v[84:87], v[162:165], v[194:197], v[84:87]
	v_mfma_f32_16x16x32_bf16 v[80:83], v[170:173], v[194:197], v[80:83]
	v_mfma_f32_16x16x32_bf16 v[68:71], v[162:165], v[202:205], v[68:71]
	v_mfma_f32_16x16x32_bf16 v[64:67], v[170:173], v[202:205], v[64:67]
	v_mfma_f32_16x16x32_bf16 v[116:119], v[166:169], v[182:185], v[116:119]
	v_mfma_f32_16x16x32_bf16 v[112:115], v[174:177], v[182:185], v[112:115]
	v_mfma_f32_16x16x32_bf16 v[100:103], v[166:169], v[190:193], v[100:103]
	v_mfma_f32_16x16x32_bf16 v[96:99], v[174:177], v[190:193], v[96:99]
	v_mfma_f32_16x16x32_bf16 v[84:87], v[166:169], v[198:201], v[84:87]
	v_mfma_f32_16x16x32_bf16 v[80:83], v[174:177], v[198:201], v[80:83]
	v_mfma_f32_16x16x32_bf16 v[68:71], v[166:169], v[210:213], v[68:71]
	v_mfma_f32_16x16x32_bf16 v[64:67], v[174:177], v[210:213], v[64:67]
	s_setprio 0
	s_barrier
; #define PG8_STAGE(bufoff, gbase, voff) do { _Pragma("unroll") for (int _i = 0; _i < 2; ++_i) \
;         __builtin_amdgcn_global_load_lds((const unsigned*)((const char*)(gbase) + (voff)[_i]), (PG8_LAS unsigned*)(lds + (bufoff) + ldsw + _i * 8192), 16, 0, 0); } while (0)
; #define PG8_LDA(dst, b, h) do { _Pragma("unroll") for (int m = 0; m < 4; ++m) _Pragma("unroll") for (int k = 0; k < 2; ++k) dst[m][k] = *(const PG8_LAS bf16x8*)(lds + PG8_SA(b, h) + aoff + m * 2048 + k * 1024); } while (0)
; #define PG8_LDB(dst, b, h) do { _Pragma("unroll") for (int n = 0; n < 2; ++n) _Pragma("unroll") for (int k = 0; k < 2; ++k) dst[n][k] = *(const PG8_LAS bf16x8*)(lds + PG8_SB(b, h) + boff + n * 2048 + k * 1024); } while (0)
; #define PG8_MMA(ai, bj, At, Bt) do { __builtin_amdgcn_s_setprio(1); _Pragma("unroll") for (int m = 0; m < 4; ++m) _Pragma("unroll") for (int n = 0; n < 2; ++n) _Pragma("unroll") for (int k = 0; k < 2; ++k) \
;         acc[ai][bj][m][n] = __builtin_amdgcn_mfma_f32_16x16x32_bf16(Bt[n][k], At[m][k], acc[ai][bj][m][n], 0, 0, 0); __builtin_amdgcn_s_setprio(0); } while (0)
; #define PG8_WAIT_V(n) asm volatile("s_waitcnt vmcnt(" #n ")" ::: "memory")
; #define PG8_WAIT_L(n) asm volatile("s_waitcnt lgkmcnt(" #n ")" ::: "memory")
; #define PG8_BAR __builtin_amdgcn_s_barrier()
; template <class Epi, class Sched, bool ALIGN_EPI = false, bool SP2 = false, bool TA = true>
; __device__ __forceinline__ void gemm_phase(PG8_LAS unsigned char* lds, const Gemm g, const Sched& S, const Epi& E) {
;     ...
;         for (int t = 0; t < nt; t += 2) {
;             const bool last = (t == nt - 2);
;             const char* a1 = cA + (size_t)(t + 1) * kstep;
;             const char* a2 = last ? nA : cA + (size_t)(t + 2) * kstep; const char* b2 = last ? nB : cB + (size_t)(t + 2) * kstepB;
;             const char* a3 = a2 + kstep; const char* b3 = b2 + kstepB;
;     ...
;             PG8_LDB(B0, 1, 0); PG8_LDB(B1, 1, 1); PG8_SCHED; PG8_LDA(At, 1, 0); PG8_STAGE(PG8_SA(0, 1), a2 + hstep, voffA);
;             PG8_WAIT_V(8); PG8_WAIT_L(0); PG8_BAR; PG8_MMA(0, 0, At, B0); PG8_MMA(0, 1, At, B1); PG8_BAR; PG8_SCHED;
;             PG8_LDA(At, 1, 1); PG8_STAGE(PG8_SB(1, 0), b3, voffB); PG8_STAGE(PG8_SB(1, 1), b3 + hstep, voffB); PG8_STAGE(PG8_SA(1, 0), a3, voffA);
;             PG8_WAIT_V(8); PG8_WAIT_L(0); PG8_BAR; PG8_MMA(1, 0, At, B0); PG8_MMA(1, 1, At, B1); PG8_BAR; PG8_SCHED;
	s_add_i32 s62, s62, s21
	v_lshl_add_u64 v[214:215], v[132:133], 0, s[36:37]
	s_mov_b32 m0, s62
	ds_read_b128 v[178:181], v151 offset:49152
	ds_read_b128 v[182:185], v151 offset:50176
	ds_read_b128 v[186:189], v151 offset:51200
	ds_read_b128 v[190:193], v151 offset:52224
	ds_read_b128 v[194:197], v151 offset:53248
	ds_read_b128 v[198:201], v151 offset:54272
	ds_read_b128 v[202:205], v151 offset:55296
	ds_read_b128 v[210:213], v151 offset:56320
	global_load_lds_dwordx4 v[214:215], off
	v_lshl_add_u64 v[214:215], v[132:133], 0, s[38:39]
	s_add_i32 m0, s62, 0x2000
	s_add_i32 s62, s63, s21
	global_load_lds_dwordx4 v[214:215], off
	v_lshl_add_u64 v[214:215], v[132:133], 0, s[40:41]
	s_mov_b32 m0, s62
	v_lshl_add_u64 v[132:133], v[132:133], 0, s[42:43]
	global_load_lds_dwordx4 v[214:215], off
	s_add_i32 m0, s62, 0x2000
	s_nop 0
	global_load_lds_dwordx4 v[132:133], off
	v_lshl_add_u64 v[132:133], v[206:207], 0, s[36:37]
	s_mov_b32 m0, s33
	s_nop 0
	global_load_lds_dwordx4 v[132:133], off
	v_lshl_add_u64 v[132:133], v[206:207], 0, s[38:39]
	s_mov_b32 m0, s66
	s_nop 0
	global_load_lds_dwordx4 v[132:133], off
	s_waitcnt vmcnt(8)
	s_waitcnt lgkmcnt(0)
	s_barrier
	s_setprio 1
	s_waitcnt lgkmcnt(0)
	v_mfma_f32_16x16x32_bf16 v[60:63], v[128:131], v[178:181], v[60:63]
	v_mfma_f32_16x16x32_bf16 v[56:59], v[154:157], v[178:181], v[56:59]
	v_mfma_f32_16x16x32_bf16 v[44:47], v[128:131], v[186:189], v[44:47]
	v_mfma_f32_16x16x32_bf16 v[40:43], v[154:157], v[186:189], v[40:43]
	v_mfma_f32_16x16x32_bf16 v[28:31], v[128:131], v[194:197], v[28:31]
	v_mfma_f32_16x16x32_bf16 v[24:27], v[154:157], v[194:197], v[24:27]
	v_mfma_f32_16x16x32_bf16 v[12:15], v[128:131], v[202:205], v[12:15]
	v_mfma_f32_16x16x32_bf16 v[8:11], v[154:157], v[202:205], v[8:11]
	v_mfma_f32_16x16x32_bf16 v[60:63], v[142:145], v[182:185], v[60:63]
	v_mfma_f32_16x16x32_bf16 v[56:59], v[158:161], v[182:185], v[56:59]
	v_mfma_f32_16x16x32_bf16 v[44:47], v[142:145], v[190:193], v[44:47]
	v_mfma_f32_16x16x32_bf16 v[40:43], v[158:161], v[190:193], v[40:43]
	v_mfma_f32_16x16x32_bf16 v[28:31], v[142:145], v[198:201], v[28:31]
	v_mfma_f32_16x16x32_bf16 v[24:27], v[158:161], v[198:201], v[24:27]
	v_mfma_f32_16x16x32_bf16 v[12:15], v[142:145], v[210:213], v[12:15]
	v_mfma_f32_16x16x32_bf16 v[8:11], v[158:161], v[210:213], v[8:11]
	s_setprio 0
	s_setprio 1
	v_mfma_f32_16x16x32_bf16 v[52:55], v[162:165], v[178:181], v[52:55]
	v_mfma_f32_16x16x32_bf16 v[48:51], v[170:173], v[178:181], v[48:51]
	v_mfma_f32_16x16x32_bf16 v[36:39], v[162:165], v[186:189], v[36:39]
	v_mfma_f32_16x16x32_bf16 v[32:35], v[170:173], v[186:189], v[32:35]
	v_mfma_f32_16x16x32_bf16 v[20:23], v[162:165], v[194:197], v[20:23]
	v_mfma_f32_16x16x32_bf16 v[16:19], v[170:173], v[194:197], v[16:19]
	v_mfma_f32_16x16x32_bf16 v[4:7], v[162:165], v[202:205], v[4:7]
	v_mfma_f32_16x16x32_bf16 v[0:3], v[170:173], v[202:205], v[0:3]
	v_mfma_f32_16x16x32_bf16 v[52:55], v[166:169], v[182:185], v[52:55]
	v_mfma_f32_16x16x32_bf16 v[48:51], v[174:177], v[182:185], v[48:51]
	v_mfma_f32_16x16x32_bf16 v[36:39], v[166:169], v[190:193], v[36:39]
	v_mfma_f32_16x16x32_bf16 v[32:35], v[174:177], v[190:193], v[32:35]
	v_mfma_f32_16x16x32_bf16 v[20:23], v[166:169], v[198:201], v[20:23]
	v_mfma_f32_16x16x32_bf16 v[16:19], v[174:177], v[198:201], v[16:19]
	v_mfma_f32_16x16x32_bf16 v[4:7], v[166:169], v[210:213], v[4:7]
	v_mfma_f32_16x16x32_bf16 v[0:3], v[174:177], v[210:213], v[0:3]
	s_setprio 0
	s_barrier
	s_add_i32 s61, s61, 2
	s_add_u32 s56, s56, 0x8000
	s_addc_u32 s57, s57, 0
	s_add_u32 s58, s58, 0x8000
	s_addc_u32 s59, s59, 0
	s_cmp_gt_u32 s61, 13

; #define PG8_STAGE(bufoff, gbase, voff) do { _Pragma("unroll") for (int _i = 0; _i < 2; ++_i) \
;         __builtin_amdgcn_global_load_lds((const unsigned*)((const char*)(gbase) + (voff)[_i]), (PG8_LAS unsigned*)(lds + (bufoff) + ldsw + _i * 8192), 16, 0, 0); } while (0)
; #define PG8_LDA(dst, b, h) do { _Pragma("unroll") for (int m = 0; m < 4; ++m) _Pragma("unroll") for (int k = 0; k < 2; ++k) dst[m][k] = *(const PG8_LAS bf16x8*)(lds + PG8_SA(b, h) + aoff + m * 2048 + k * 1024); } while (0)
; #define PG8_LDB(dst, b, h) do { _Pragma("unroll") for (int n = 0; n < 2; ++n) _Pragma("unroll") for (int k = 0; k < 2; ++k) dst[n][k] = *(const PG8_LAS bf16x8*)(lds + PG8_SB(b, h) + boff + n * 2048 + k * 1024); } while (0)
; #define PG8_WAIT_V(n) asm volatile("s_waitcnt vmcnt(" #n ")" ::: "memory")
; #define PG8_WAIT_L(n) asm volatile("s_waitcnt lgkmcnt(" #n ")" ::: "memory")
; #define PG8_BAR __builtin_amdgcn_s_barrier()
; #define PG8_SCHED __builtin_amdgcn_sched_barrier(0)
; template <class Epi, class Sched, bool ALIGN_EPI = false, bool SP2 = false, bool TA = true>
; __device__ __forceinline__ void gemm_phase(PG8_LAS unsigned char* lds, const Gemm g, const Sched& S, const Epi& E) {
;     ...
;         const bool has_next = S.next(ui + 1, nxt);
;         const char* nA = has_next ? (const char*)g.A + (size_t)nxt.pm * tstep : cA; const char* nB = has_next ? (const char*)g.Bt + (size_t)nxt.pn * tstep : cB;
; #pragma unroll 1
;         for (int t = 0; t < nt; t += 2) {
;             const bool last = (t == nt - 2);
;             const char* a1 = cA + (size_t)(t + 1) * kstep;
;             const char* a2 = last ? nA : cA + (size_t)(t + 2) * kstep; const char* b2 = last ? nB : cB + (size_t)(t + 2) * kstepB;
;             const char* a3 = a2 + kstep; const char* b3 = b2 + kstepB;
;             if (last && has_next) S.a_ready(nxt);
;             if constexpr (SP2) {
;             PG8_LDB(B0, 0, 0); PG8_LDB(B1, 0, 1); PG8_SCHED; PG8_LDA(At, 0, 0); PG8_STAGE(PG8_SA(1, 1), a1 + hstep, voffA);
;             PG8_WAIT_V(8); PG8_WAIT_L(0); PG8_BAR; PG8_MMA(0, 0, At, B0); PG8_MMA(0, 1, At, B1); PG8_BAR; PG8_SCHED;
;             PG8_LDA(At, 0, 1); PG8_STAGE(PG8_SB(0, 0), b2, voffB); PG8_STAGE(PG8_SB(0, 1), b2 + hstep, voffB); PG8_STAGE(PG8_SA(0, 0), a2, voffA);
;             PG8_WAIT_V(8); PG8_WAIT_L(0); PG8_BAR; PG8_MMA(1, 0, At, B0); PG8_MMA(1, 1, At, B1); PG8_BAR; PG8_SCHED;
.LBB0_1624:
	s_ashr_i32 s47, s46, 31
	s_lshl_b64 s[48:49], s[46:47], 19
	s_add_u32 s48, s8, s48
	s_addc_u32 s49, s9, s49
	s_and_b64 s[50:51], s[4:5], exec
	s_cselect_b32 s47, s49, s57
	s_cselect_b32 s55, s48, s56
	s_ashr_i32 s45, s44, 31
	s_lshl_b64 s[50:51], s[44:45], 19
	s_add_u32 s50, s19, s50
	s_addc_u32 s51, s21, s51
	s_and_b64 s[74:75], s[4:5], exec
	s_cselect_b32 s45, s51, s59
	s_cselect_b32 s73, s50, s58
	s_add_u32 s56, s56, 0x44000
	s_addc_u32 s57, s57, 0
	s_add_u32 s58, s58, 0x8000
	s_addc_u32 s59, s59, 0
	s_mov_b32 s74, -2
	ds_read_b128 v[136:139], v147
	ds_read_b128 v[152:155], v147 offset:1024
	ds_read_b128 v[156:159], v147 offset:2048
	ds_read_b128 v[160:163], v147 offset:3072
	ds_read_b128 v[164:167], v148
	ds_read_b128 v[168:171], v148 offset:1024
	ds_read_b128 v[172:175], v148 offset:2048
	ds_read_b128 v[176:179], v148 offset:3072
	s_add_u32 s75, s56, 0xfffc4000
	s_addc_u32 s76, s57, -1
	s_cmp_eq_u32 s74, 12
	s_cselect_b32 s77, s47, s76
	s_cselect_b32 s76, s55, s75
	s_cselect_b32 s79, s45, s59
	s_cselect_b32 s78, s73, s58
	v_lshl_add_u64 v[140:141], s[56:57], 0, v[128:129]
	s_add_i32 m0, s23, 0xc000
	ds_read_b128 v[180:183], v149
	ds_read_b128 v[184:187], v149 offset:1024
	ds_read_b128 v[188:191], v149 offset:2048
	ds_read_b128 v[192:195], v149 offset:3072
	ds_read_b128 v[196:199], v149 offset:4096
	ds_read_b128 v[200:203], v149 offset:5120
	ds_read_b128 v[204:207], v149 offset:6144
	ds_read_b128 v[210:213], v149 offset:7168
	global_load_lds_dwordx4 v[140:141], off
	v_lshl_add_u64 v[140:141], v[140:141], 0, s[6:7]
	s_add_i32 m0, s23, 0xe000
	s_nop 0
	global_load_lds_dwordx4 v[140:141], off
	s_waitcnt vmcnt(8)
	s_waitcnt lgkmcnt(0)
	s_barrier
	s_setprio 1
	s_waitcnt lgkmcnt(0)
	v_mfma_f32_16x16x32_bf16 v[124:127], v[136:139], v[180:183], 0
	v_mfma_f32_16x16x32_bf16 v[116:119], v[156:159], v[180:183], 0
	v_mfma_f32_16x16x32_bf16 v[108:111], v[136:139], v[188:191], 0
	v_mfma_f32_16x16x32_bf16 v[100:103], v[156:159], v[188:191], 0
	v_mfma_f32_16x16x32_bf16 v[92:95], v[136:139], v[196:199], 0
	v_mfma_f32_16x16x32_bf16 v[84:87], v[156:159], v[196:199], 0
	v_mfma_f32_16x16x32_bf16 v[76:79], v[136:139], v[204:207], 0
	v_mfma_f32_16x16x32_bf16 v[68:71], v[156:159], v[204:207], 0
	v_mfma_f32_16x16x32_bf16 v[124:127], v[152:155], v[184:187], v[124:127]
	v_mfma_f32_16x16x32_bf16 v[116:119], v[160:163], v[184:187], v[116:119]
	v_mfma_f32_16x16x32_bf16 v[108:111], v[152:155], v[192:195], v[108:111]
	v_mfma_f32_16x16x32_bf16 v[100:103], v[160:163], v[192:195], v[100:103]
	v_mfma_f32_16x16x32_bf16 v[92:95], v[152:155], v[200:203], v[92:95]
	v_mfma_f32_16x16x32_bf16 v[84:87], v[160:163], v[200:203], v[84:87]
	v_mfma_f32_16x16x32_bf16 v[76:79], v[152:155], v[210:213], v[76:79]
	v_mfma_f32_16x16x32_bf16 v[68:71], v[160:163], v[210:213], v[68:71]
	s_setprio 0
	s_setprio 1
	v_mfma_f32_16x16x32_bf16 v[120:123], v[164:167], v[180:183], 0
	v_mfma_f32_16x16x32_bf16 v[112:115], v[172:175], v[180:183], 0
	v_mfma_f32_16x16x32_bf16 v[104:107], v[164:167], v[188:191], 0
	v_mfma_f32_16x16x32_bf16 v[96:99], v[172:175], v[188:191], 0
	v_mfma_f32_16x16x32_bf16 v[88:91], v[164:167], v[196:199], 0
	v_mfma_f32_16x16x32_bf16 v[80:83], v[172:175], v[196:199], 0
	v_mfma_f32_16x16x32_bf16 v[72:75], v[164:167], v[204:207], 0
	v_mfma_f32_16x16x32_bf16 v[64:67], v[172:175], v[204:207], 0
	v_mfma_f32_16x16x32_bf16 v[120:123], v[168:171], v[184:187], v[120:123]
	v_mfma_f32_16x16x32_bf16 v[112:115], v[176:179], v[184:187], v[112:115]
	v_mfma_f32_16x16x32_bf16 v[104:107], v[168:171], v[192:195], v[104:107]
	v_mfma_f32_16x16x32_bf16 v[96:99], v[176:179], v[192:195], v[96:99]
	v_mfma_f32_16x16x32_bf16 v[88:91], v[168:171], v[200:203], v[88:91]
	v_mfma_f32_16x16x32_bf16 v[80:83], v[176:179], v[200:203], v[80:83]
	v_mfma_f32_16x16x32_bf16 v[72:75], v[168:171], v[210:213], v[72:75]
	v_mfma_f32_16x16x32_bf16 v[64:67], v[176:179], v[210:213], v[64:67]
	s_setprio 0
	s_barrier
	s_add_i32 s75, s70, s22
	v_lshl_add_u64 v[140:141], s[78:79], 0, v[128:129]
	s_mov_b32 m0, s75
	ds_read_b128 v[180:183], v149 offset:16384
	ds_read_b128 v[184:187], v149 offset:17408
	ds_read_b128 v[188:191], v149 offset:18432
	ds_read_b128 v[192:195], v149 offset:19456
	ds_read_b128 v[196:199], v149 offset:20480
	ds_read_b128 v[200:203], v149 offset:21504
	ds_read_b128 v[204:207], v149 offset:22528
	ds_read_b128 v[210:213], v149 offset:23552
	global_load_lds_dwordx4 v[140:141], off
	v_lshl_add_u64 v[214:215], v[140:141], 0, s[6:7]
	s_add_i32 m0, s75, 0x2000
	s_add_i32 s75, s71, s22
	global_load_lds_dwordx4 v[214:215], off
	v_lshl_add_u64 v[214:215], v[140:141], 0, s[12:13]
	s_mov_b32 m0, s75
	s_nop 0
	global_load_lds_dwordx4 v[214:215], off
	v_lshl_add_u64 v[214:215], v[140:141], 0, s[14:15]
	s_add_i32 m0, s75, 0x2000
	s_nop 0
	global_load_lds_dwordx4 v[214:215], off
	v_lshl_add_u64 v[214:215], s[76:77], 0, v[128:129]
	s_mov_b32 m0, s23
	v_lshl_add_u64 v[216:217], v[214:215], 0, s[6:7]
	global_load_lds_dwordx4 v[214:215], off
	s_mov_b32 m0, s30
	s_nop 0
	global_load_lds_dwordx4 v[216:217], off
	s_waitcnt vmcnt(8)
	s_waitcnt lgkmcnt(0)
	s_barrier
; #define PG8_STAGE(bufoff, gbase, voff) do { _Pragma("unroll") for (int _i = 0; _i < 2; ++_i) \
;         __builtin_amdgcn_global_load_lds((const unsigned*)((const char*)(gbase) + (voff)[_i]), (PG8_LAS unsigned*)(lds + (bufoff) + ldsw + _i * 8192), 16, 0, 0); } while (0)
; #define PG8_LDA(dst, b, h) do { _Pragma("unroll") for (int m = 0; m < 4; ++m) _Pragma("unroll") for (int k = 0; k < 2; ++k) dst[m][k] = *(const PG8_LAS bf16x8*)(lds + PG8_SA(b, h) + aoff + m * 2048 + k * 1024); } while (0)
; #define PG8_LDB(dst, b, h) do { _Pragma("unroll") for (int n = 0; n < 2; ++n) _Pragma("unroll") for (int k = 0; k < 2; ++k) dst[n][k] = *(const PG8_LAS bf16x8*)(lds + PG8_SB(b, h) + boff + n * 2048 + k * 1024); } while (0)
; #define PG8_MMA(ai, bj, At, Bt) do { __builtin_amdgcn_s_setprio(1); _Pragma("unroll") for (int m = 0; m < 4; ++m) _Pragma("unroll") for (int n = 0; n < 2; ++n) _Pragma("unroll") for (int k = 0; k < 2; ++k) \
;         acc[ai][bj][m][n] = __builtin_amdgcn_mfma_f32_16x16x32_bf16(Bt[n][k], At[m][k], acc[ai][bj][m][n], 0, 0, 0); __builtin_amdgcn_s_setprio(0); } while (0)
; #define PG8_WAIT_V(n) asm volatile("s_waitcnt vmcnt(" #n ")" ::: "memory")
; #define PG8_WAIT_L(n) asm volatile("s_waitcnt lgkmcnt(" #n ")" ::: "memory")
; #define PG8_BAR __builtin_amdgcn_s_barrier()
; #define PG8_SCHED __builtin_amdgcn_sched_barrier(0)
; template <class Epi, class Sched, bool ALIGN_EPI = false, bool SP2 = false, bool TA = true>
; __device__ __forceinline__ void gemm_phase(PG8_LAS unsigned char* lds, const Gemm g, const Sched& S, const Epi& E) {
;     ...
;             PG8_WAIT_V(8); PG8_WAIT_L(0); PG8_BAR; PG8_MMA(0, 0, At, B0); PG8_MMA(0, 1, At, B1); PG8_BAR; PG8_SCHED;
;             PG8_LDA(At, 0, 1); PG8_STAGE(PG8_SB(0, 0), b2, voffB); PG8_STAGE(PG8_SB(0, 1), b2 + hstep, voffB); PG8_STAGE(PG8_SA(0, 0), a2, voffA);
;             PG8_WAIT_V(8); PG8_WAIT_L(0); PG8_BAR; PG8_MMA(1, 0, At, B0); PG8_MMA(1, 1, At, B1); PG8_BAR; PG8_SCHED;
;             PG8_LDB(B0, 1, 0); PG8_LDB(B1, 1, 1); PG8_SCHED; PG8_LDA(At, 1, 0); PG8_STAGE(PG8_SA(0, 1), a2 + hstep, voffA);
;             PG8_WAIT_V(8); PG8_WAIT_L(0); PG8_BAR; PG8_MMA(0, 0, At, B0); PG8_MMA(0, 1, At, B1); PG8_BAR; PG8_SCHED;
	s_setprio 1
	s_waitcnt lgkmcnt(0)
	v_mfma_f32_16x16x32_bf16 v[60:63], v[136:139], v[180:183], 0
	v_mfma_f32_16x16x32_bf16 v[52:55], v[156:159], v[180:183], 0
	v_mfma_f32_16x16x32_bf16 v[44:47], v[136:139], v[188:191], 0
	v_mfma_f32_16x16x32_bf16 v[36:39], v[156:159], v[188:191], 0
	v_mfma_f32_16x16x32_bf16 v[28:31], v[136:139], v[196:199], 0
	v_mfma_f32_16x16x32_bf16 v[20:23], v[156:159], v[196:199], 0
	v_mfma_f32_16x16x32_bf16 v[12:15], v[136:139], v[204:207], 0
	v_mfma_f32_16x16x32_bf16 v[4:7], v[156:159], v[204:207], 0
	v_mfma_f32_16x16x32_bf16 v[60:63], v[152:155], v[184:187], v[60:63]
	v_mfma_f32_16x16x32_bf16 v[52:55], v[160:163], v[184:187], v[52:55]
	v_mfma_f32_16x16x32_bf16 v[44:47], v[152:155], v[192:195], v[44:47]
	v_mfma_f32_16x16x32_bf16 v[36:39], v[160:163], v[192:195], v[36:39]
	v_mfma_f32_16x16x32_bf16 v[28:31], v[152:155], v[200:203], v[28:31]
	v_mfma_f32_16x16x32_bf16 v[20:23], v[160:163], v[200:203], v[20:23]
	v_mfma_f32_16x16x32_bf16 v[12:15], v[152:155], v[210:213], v[12:15]
	v_mfma_f32_16x16x32_bf16 v[4:7], v[160:163], v[210:213], v[4:7]
	s_setprio 0
	s_setprio 1
	v_mfma_f32_16x16x32_bf16 v[56:59], v[164:167], v[180:183], 0
	v_mfma_f32_16x16x32_bf16 v[48:51], v[172:175], v[180:183], 0
	v_mfma_f32_16x16x32_bf16 v[40:43], v[164:167], v[188:191], 0
	v_mfma_f32_16x16x32_bf16 v[32:35], v[172:175], v[188:191], 0
	v_mfma_f32_16x16x32_bf16 v[24:27], v[164:167], v[196:199], 0
	v_mfma_f32_16x16x32_bf16 v[16:19], v[172:175], v[196:199], 0
	v_mfma_f32_16x16x32_bf16 v[8:11], v[164:167], v[204:207], 0
	v_mfma_f32_16x16x32_bf16 v[0:3], v[172:175], v[204:207], 0
	v_mfma_f32_16x16x32_bf16 v[56:59], v[168:171], v[184:187], v[56:59]
	v_mfma_f32_16x16x32_bf16 v[48:51], v[176:179], v[184:187], v[48:51]
	v_mfma_f32_16x16x32_bf16 v[40:43], v[168:171], v[192:195], v[40:43]
	v_mfma_f32_16x16x32_bf16 v[32:35], v[176:179], v[192:195], v[32:35]
	v_mfma_f32_16x16x32_bf16 v[24:27], v[168:171], v[200:203], v[24:27]
	v_mfma_f32_16x16x32_bf16 v[16:19], v[176:179], v[200:203], v[16:19]
	v_mfma_f32_16x16x32_bf16 v[8:11], v[168:171], v[210:213], v[8:11]
	v_mfma_f32_16x16x32_bf16 v[0:3], v[176:179], v[210:213], v[0:3]
	s_setprio 0
	s_barrier
	s_add_i32 s75, 0, 0x18000
	v_add_u32_e32 v130, s75, v144
	s_add_i32 s76, 0, 0x1c000
	ds_read_b128 v[136:139], v130
	ds_read_b128 v[152:155], v130 offset:1024
	ds_read_b128 v[156:159], v130 offset:2048
	ds_read_b128 v[160:163], v130 offset:3072
	v_add_u32_e32 v130, s76, v144
	ds_read_b128 v[164:167], v130
	ds_read_b128 v[168:171], v130 offset:1024
	ds_read_b128 v[172:175], v130 offset:2048
	ds_read_b128 v[176:179], v130 offset:3072
	s_mov_b32 m0, s31
	v_lshl_add_u64 v[216:217], v[214:215], 0, s[12:13]
	ds_read_b128 v[180:183], v149 offset:32768
	ds_read_b128 v[184:187], v149 offset:33792
	ds_read_b128 v[188:191], v149 offset:34816
	ds_read_b128 v[192:195], v149 offset:35840
	ds_read_b128 v[196:199], v149 offset:36864
	ds_read_b128 v[200:203], v149 offset:37888
	ds_read_b128 v[204:207], v149 offset:38912
	ds_read_b128 v[210:213], v149 offset:39936
	global_load_lds_dwordx4 v[216:217], off
	v_lshl_add_u64 v[216:217], v[214:215], 0, s[14:15]
	s_mov_b32 m0, s33
	s_nop 0
	global_load_lds_dwordx4 v[216:217], off
	s_waitcnt vmcnt(8)
	s_waitcnt lgkmcnt(0)
	s_barrier
	s_setprio 1
	s_waitcnt lgkmcnt(0)
	v_mfma_f32_16x16x32_bf16 v[124:127], v[136:139], v[180:183], v[124:127]
	v_mfma_f32_16x16x32_bf16 v[116:119], v[156:159], v[180:183], v[116:119]
	v_mfma_f32_16x16x32_bf16 v[108:111], v[136:139], v[188:191], v[108:111]
	v_mfma_f32_16x16x32_bf16 v[100:103], v[156:159], v[188:191], v[100:103]
	v_mfma_f32_16x16x32_bf16 v[92:95], v[136:139], v[196:199], v[92:95]
	v_mfma_f32_16x16x32_bf16 v[84:87], v[156:159], v[196:199], v[84:87]
	v_mfma_f32_16x16x32_bf16 v[76:79], v[136:139], v[204:207], v[76:79]
	v_mfma_f32_16x16x32_bf16 v[68:71], v[156:159], v[204:207], v[68:71]
	v_mfma_f32_16x16x32_bf16 v[124:127], v[152:155], v[184:187], v[124:127]
	v_mfma_f32_16x16x32_bf16 v[116:119], v[160:163], v[184:187], v[116:119]
	v_mfma_f32_16x16x32_bf16 v[108:111], v[152:155], v[192:195], v[108:111]
	v_mfma_f32_16x16x32_bf16 v[100:103], v[160:163], v[192:195], v[100:103]
	v_mfma_f32_16x16x32_bf16 v[92:95], v[152:155], v[200:203], v[92:95]
	v_mfma_f32_16x16x32_bf16 v[84:87], v[160:163], v[200:203], v[84:87]
	v_mfma_f32_16x16x32_bf16 v[76:79], v[152:155], v[210:213], v[76:79]
	v_mfma_f32_16x16x32_bf16 v[68:71], v[160:163], v[210:213], v[68:71]
	s_setprio 0
	s_setprio 1
	v_mfma_f32_16x16x32_bf16 v[120:123], v[164:167], v[180:183], v[120:123]
	v_mfma_f32_16x16x32_bf16 v[112:115], v[172:175], v[180:183], v[112:115]
	v_mfma_f32_16x16x32_bf16 v[104:107], v[164:167], v[188:191], v[104:107]
	v_mfma_f32_16x16x32_bf16 v[96:99], v[172:175], v[188:191], v[96:99]
	v_mfma_f32_16x16x32_bf16 v[88:91], v[164:167], v[196:199], v[88:91]
	v_mfma_f32_16x16x32_bf16 v[80:83], v[172:175], v[196:199], v[80:83]
	v_mfma_f32_16x16x32_bf16 v[72:75], v[164:167], v[204:207], v[72:75]
	v_mfma_f32_16x16x32_bf16 v[64:67], v[172:175], v[204:207], v[64:67]
	v_mfma_f32_16x16x32_bf16 v[120:123], v[168:171], v[184:187], v[120:123]
	v_mfma_f32_16x16x32_bf16 v[112:115], v[176:179], v[184:187], v[112:115]
	v_mfma_f32_16x16x32_bf16 v[104:107], v[168:171], v[192:195], v[104:107]
	v_mfma_f32_16x16x32_bf16 v[96:99], v[176:179], v[192:195], v[96:99]
	v_mfma_f32_16x16x32_bf16 v[88:91], v[168:171], v[200:203], v[88:91]
	v_mfma_f32_16x16x32_bf16 v[80:83], v[176:179], v[200:203], v[80:83]
	v_mfma_f32_16x16x32_bf16 v[72:75], v[168:171], v[210:213], v[72:75]
	v_mfma_f32_16x16x32_bf16 v[64:67], v[176:179], v[210:213], v[64:67]
	s_setprio 0
	s_barrier
; #define PG8_STAGE(bufoff, gbase, voff) do { _Pragma("unroll") for (int _i = 0; _i < 2; ++_i) \
;         __builtin_amdgcn_global_load_lds((const unsigned*)((const char*)(gbase) + (voff)[_i]), (PG8_LAS unsigned*)(lds + (bufoff) + ldsw + _i * 8192), 16, 0, 0); } while (0)
; #define PG8_LDA(dst, b, h) do { _Pragma("unroll") for (int m = 0; m < 4; ++m) _Pragma("unroll") for (int k = 0; k < 2; ++k) dst[m][k] = *(const PG8_LAS bf16x8*)(lds + PG8_SA(b, h) + aoff + m * 2048 + k * 1024); } while (0)
; #define PG8_LDB(dst, b, h) do { _Pragma("unroll") for (int n = 0; n < 2; ++n) _Pragma("unroll") for (int k = 0; k < 2; ++k) dst[n][k] = *(const PG8_LAS bf16x8*)(lds + PG8_SB(b, h) + boff + n * 2048 + k * 1024); } while (0)
; #define PG8_MMA(ai, bj, At, Bt) do { __builtin_amdgcn_s_setprio(1); _Pragma("unroll") for (int m = 0; m < 4; ++m) _Pragma("unroll") for (int n = 0; n < 2; ++n) _Pragma("unroll") for (int k = 0; k < 2; ++k) \
;         acc[ai][bj][m][n] = __builtin_amdgcn_mfma_f32_16x16x32_bf16(Bt[n][k], At[m][k], acc[ai][bj][m][n], 0, 0, 0); __builtin_amdgcn_s_setprio(0); } while (0)
; #define PG8_WAIT_V(n) asm volatile("s_waitcnt vmcnt(" #n ")" ::: "memory")
; #define PG8_WAIT_L(n) asm volatile("s_waitcnt lgkmcnt(" #n ")" ::: "memory")
; #define PG8_BAR __builtin_amdgcn_s_barrier()
; template <class Epi, class Sched, bool ALIGN_EPI = false, bool SP2 = false, bool TA = true>
; __device__ __forceinline__ void gemm_phase(PG8_LAS unsigned char* lds, const Gemm g, const Sched& S, const Epi& E) {
;     ...
;         for (int t = 0; t < nt; t += 2) {
;             const bool last = (t == nt - 2);
;             const char* a1 = cA + (size_t)(t + 1) * kstep;
;             const char* a2 = last ? nA : cA + (size_t)(t + 2) * kstep; const char* b2 = last ? nB : cB + (size_t)(t + 2) * kstepB;
;             const char* a3 = a2 + kstep; const char* b3 = b2 + kstepB;
;     ...
;             PG8_LDB(B0, 1, 0); PG8_LDB(B1, 1, 1); PG8_SCHED; PG8_LDA(At, 1, 0); PG8_STAGE(PG8_SA(0, 1), a2 + hstep, voffA);
;             PG8_WAIT_V(8); PG8_WAIT_L(0); PG8_BAR; PG8_MMA(0, 0, At, B0); PG8_MMA(0, 1, At, B1); PG8_BAR; PG8_SCHED;
;             PG8_LDA(At, 1, 1); PG8_STAGE(PG8_SB(1, 0), b3, voffB); PG8_STAGE(PG8_SB(1, 1), b3 + hstep, voffB); PG8_STAGE(PG8_SA(1, 0), a3, voffA);
;             PG8_WAIT_V(8); PG8_WAIT_L(0); PG8_BAR; PG8_MMA(1, 0, At, B0); PG8_MMA(1, 1, At, B1); PG8_BAR; PG8_SCHED;
	s_add_i32 s75, s75, s22
	v_lshl_add_u64 v[216:217], v[140:141], 0, s[34:35]
	s_mov_b32 m0, s75
	ds_read_b128 v[180:183], v149 offset:49152
	ds_read_b128 v[184:187], v149 offset:50176
	ds_read_b128 v[188:191], v149 offset:51200
	ds_read_b128 v[192:195], v149 offset:52224
	ds_read_b128 v[196:199], v149 offset:53248
	ds_read_b128 v[200:203], v149 offset:54272
	ds_read_b128 v[204:207], v149 offset:55296
	ds_read_b128 v[210:213], v149 offset:56320
	global_load_lds_dwordx4 v[216:217], off
	v_lshl_add_u64 v[216:217], v[140:141], 0, s[36:37]
	s_add_i32 m0, s75, 0x2000
	s_add_i32 s75, s76, s22
	global_load_lds_dwordx4 v[216:217], off
	v_lshl_add_u64 v[216:217], v[140:141], 0, s[38:39]
	s_mov_b32 m0, s75
	v_lshl_add_u64 v[140:141], v[140:141], 0, s[40:41]
	global_load_lds_dwordx4 v[216:217], off
	s_add_i32 m0, s75, 0x2000
	s_nop 0
	global_load_lds_dwordx4 v[140:141], off
	v_lshl_add_u64 v[140:141], v[214:215], 0, s[34:35]
	s_mov_b32 m0, s60
	s_nop 0
	global_load_lds_dwordx4 v[140:141], off
	v_lshl_add_u64 v[140:141], v[214:215], 0, s[36:37]
	s_mov_b32 m0, s61
	s_nop 0
	global_load_lds_dwordx4 v[140:141], off
	s_waitcnt vmcnt(8)
	s_waitcnt lgkmcnt(0)
	s_barrier
	s_setprio 1
	s_waitcnt lgkmcnt(0)
	v_mfma_f32_16x16x32_bf16 v[60:63], v[136:139], v[180:183], v[60:63]
	v_mfma_f32_16x16x32_bf16 v[52:55], v[156:159], v[180:183], v[52:55]
	v_mfma_f32_16x16x32_bf16 v[44:47], v[136:139], v[188:191], v[44:47]
	v_mfma_f32_16x16x32_bf16 v[36:39], v[156:159], v[188:191], v[36:39]
	v_mfma_f32_16x16x32_bf16 v[28:31], v[136:139], v[196:199], v[28:31]
	v_mfma_f32_16x16x32_bf16 v[20:23], v[156:159], v[196:199], v[20:23]
	v_mfma_f32_16x16x32_bf16 v[12:15], v[136:139], v[204:207], v[12:15]
	v_mfma_f32_16x16x32_bf16 v[4:7], v[156:159], v[204:207], v[4:7]
	v_mfma_f32_16x16x32_bf16 v[60:63], v[152:155], v[184:187], v[60:63]
	v_mfma_f32_16x16x32_bf16 v[52:55], v[160:163], v[184:187], v[52:55]
	v_mfma_f32_16x16x32_bf16 v[44:47], v[152:155], v[192:195], v[44:47]
	v_mfma_f32_16x16x32_bf16 v[36:39], v[160:163], v[192:195], v[36:39]
	v_mfma_f32_16x16x32_bf16 v[28:31], v[152:155], v[200:203], v[28:31]
	v_mfma_f32_16x16x32_bf16 v[20:23], v[160:163], v[200:203], v[20:23]
	v_mfma_f32_16x16x32_bf16 v[12:15], v[152:155], v[210:213], v[12:15]
	v_mfma_f32_16x16x32_bf16 v[4:7], v[160:163], v[210:213], v[4:7]
	s_setprio 0
	s_setprio 1
	v_mfma_f32_16x16x32_bf16 v[56:59], v[164:167], v[180:183], v[56:59]
	v_mfma_f32_16x16x32_bf16 v[48:51], v[172:175], v[180:183], v[48:51]
	v_mfma_f32_16x16x32_bf16 v[40:43], v[164:167], v[188:191], v[40:43]
	v_mfma_f32_16x16x32_bf16 v[32:35], v[172:175], v[188:191], v[32:35]
	v_mfma_f32_16x16x32_bf16 v[24:27], v[164:167], v[196:199], v[24:27]
	v_mfma_f32_16x16x32_bf16 v[16:19], v[172:175], v[196:199], v[16:19]
	v_mfma_f32_16x16x32_bf16 v[8:11], v[164:167], v[204:207], v[8:11]
	v_mfma_f32_16x16x32_bf16 v[0:3], v[172:175], v[204:207], v[0:3]
	v_mfma_f32_16x16x32_bf16 v[56:59], v[168:171], v[184:187], v[56:59]
	v_mfma_f32_16x16x32_bf16 v[48:51], v[176:179], v[184:187], v[48:51]
	v_mfma_f32_16x16x32_bf16 v[40:43], v[168:171], v[192:195], v[40:43]
	v_mfma_f32_16x16x32_bf16 v[32:35], v[176:179], v[192:195], v[32:35]
	v_mfma_f32_16x16x32_bf16 v[24:27], v[168:171], v[200:203], v[24:27]
	v_mfma_f32_16x16x32_bf16 v[16:19], v[176:179], v[200:203], v[16:19]
	v_mfma_f32_16x16x32_bf16 v[8:11], v[168:171], v[210:213], v[8:11]
	v_mfma_f32_16x16x32_bf16 v[0:3], v[176:179], v[210:213], v[0:3]
	s_setprio 0
	s_barrier
	s_add_i32 s74, s74, 2
	s_add_u32 s56, s56, 0x8000
	s_addc_u32 s57, s57, 0
	s_add_u32 s58, s58, 0x8000
	s_addc_u32 s59, s59, 0
	s_cmp_gt_u32 s74, 13

; #define PG8_STAGE(bufoff, gbase, voff) do { _Pragma("unroll") for (int _i = 0; _i < 2; ++_i) \
;         __builtin_amdgcn_global_load_lds((const unsigned*)((const char*)(gbase) + (voff)[_i]), (PG8_LAS unsigned*)(lds + (bufoff) + ldsw + _i * 8192), 16, 0, 0); } while (0)
; #define PG8_LDA(dst, b, h) do { _Pragma("unroll") for (int m = 0; m < 4; ++m) _Pragma("unroll") for (int k = 0; k < 2; ++k) dst[m][k] = *(const PG8_LAS bf16x8*)(lds + PG8_SA(b, h) + aoff + m * 2048 + k * 1024); } while (0)
; #define PG8_LDB(dst, b, h) do { _Pragma("unroll") for (int n = 0; n < 2; ++n) _Pragma("unroll") for (int k = 0; k < 2; ++k) dst[n][k] = *(const PG8_LAS bf16x8*)(lds + PG8_SB(b, h) + boff + n * 2048 + k * 1024); } while (0)
; #define PG8_WAIT_V(n) asm volatile("s_waitcnt vmcnt(" #n ")" ::: "memory")
; #define PG8_WAIT_L(n) asm volatile("s_waitcnt lgkmcnt(" #n ")" ::: "memory")
; #define PG8_BAR __builtin_amdgcn_s_barrier()
; template <class Epi, class Sched, bool ALIGN_EPI = false, bool SP2 = false, bool TA = true>
; __device__ __forceinline__ void gemm_phase(PG8_LAS unsigned char* lds, const Gemm g, const Sched& S, const Epi& E) {
;     ...
;         const bool has_next = S.next(ui + 1, nxt);
;         const char* nA = has_next ? (const char*)g.A + (size_t)nxt.pm * tstep : cA; const char* nB = has_next ? (const char*)g.Bt + (size_t)nxt.pn * tstep : cB;
; #pragma unroll 1
;         for (int t = 0; t < nt; t += 2) {
;             const bool last = (t == nt - 2);
;             const char* a1 = cA + (size_t)(t + 1) * kstep;
;             const char* a2 = last ? nA : cA + (size_t)(t + 2) * kstep; const char* b2 = last ? nB : cB + (size_t)(t + 2) * kstepB;
;             const char* a3 = a2 + kstep; const char* b3 = b2 + kstepB;
;             if (last && has_next) S.a_ready(nxt);
;             if constexpr (SP2) {
;             PG8_LDB(B0, 0, 0); PG8_LDB(B1, 0, 1); PG8_SCHED; PG8_LDA(At, 0, 0); PG8_STAGE(PG8_SA(1, 1), a1 + hstep, voffA);
;             PG8_WAIT_V(8); PG8_WAIT_L(0); PG8_BAR; PG8_MMA(0, 0, At, B0); PG8_MMA(0, 1, At, B1); PG8_BAR; PG8_SCHED;
;             PG8_LDA(At, 0, 1); PG8_STAGE(PG8_SB(0, 0), b2, voffB); PG8_STAGE(PG8_SB(0, 1), b2 + hstep, voffB); PG8_STAGE(PG8_SA(0, 0), a2, voffA);
;             PG8_WAIT_V(8); PG8_WAIT_L(0); PG8_BAR; PG8_MMA(1, 0, At, B0); PG8_MMA(1, 1, At, B1); PG8_BAR; PG8_SCHED;
;     ...
;         cur = nxt; cA = nA; cB = nB; ++ui;
.LBB0_1711:
	s_add_u32 s50, s50, 0xb4000
	s_addc_u32 s51, s51, 0
	s_add_u32 s52, s52, 0x8000
	s_addc_u32 s53, s53, 0
	s_mov_b32 s55, -2
	s_waitcnt lgkmcnt(0)
	ds_read_b128 v[128:131], v150
	ds_read_b128 v[142:145], v150 offset:1024
	ds_read_b128 v[154:157], v150 offset:2048
	ds_read_b128 v[158:161], v150 offset:3072
	ds_read_b128 v[162:165], v151
	ds_read_b128 v[166:169], v151 offset:1024
	ds_read_b128 v[170:173], v151 offset:2048
	ds_read_b128 v[174:177], v151 offset:3072
	s_add_u32 s56, s50, 0xfff54000
	s_addc_u32 s57, s51, -1
	s_cmp_eq_u32 s55, 40
	s_cselect_b32 s57, s1, s57
	s_cselect_b32 s56, s0, s56
	s_cselect_b32 s59, s49, s53
	s_cselect_b32 s58, s48, s52
	v_lshl_add_u64 v[132:133], s[50:51], 0, v[134:135]
	s_add_i32 m0, s30, 0xc000
	ds_read_b128 v[178:181], v152
	ds_read_b128 v[182:185], v152 offset:1024
	ds_read_b128 v[186:189], v152 offset:2048
	ds_read_b128 v[190:193], v152 offset:3072
	ds_read_b128 v[194:197], v152 offset:4096
	ds_read_b128 v[198:201], v152 offset:5120
	ds_read_b128 v[202:205], v152 offset:6144
	ds_read_b128 v[210:213], v152 offset:7168
	global_load_lds_dwordx4 v[132:133], off
	v_lshl_add_u64 v[132:133], v[132:133], 0, s[14:15]
	s_add_i32 m0, s30, 0xe000
	s_nop 0
	global_load_lds_dwordx4 v[132:133], off
	s_waitcnt vmcnt(8)
	s_waitcnt lgkmcnt(0)
	s_barrier
	s_setprio 1
	s_waitcnt lgkmcnt(0)
	v_mfma_f32_16x16x32_bf16 v[124:127], v[128:131], v[178:181], 0
	v_mfma_f32_16x16x32_bf16 v[120:123], v[154:157], v[178:181], 0
	v_mfma_f32_16x16x32_bf16 v[108:111], v[128:131], v[186:189], 0
	v_mfma_f32_16x16x32_bf16 v[104:107], v[154:157], v[186:189], 0
	v_mfma_f32_16x16x32_bf16 v[92:95], v[128:131], v[194:197], 0
	v_mfma_f32_16x16x32_bf16 v[88:91], v[154:157], v[194:197], 0
	v_mfma_f32_16x16x32_bf16 v[76:79], v[128:131], v[202:205], 0
	v_mfma_f32_16x16x32_bf16 v[72:75], v[154:157], v[202:205], 0
	v_mfma_f32_16x16x32_bf16 v[124:127], v[142:145], v[182:185], v[124:127]
	v_mfma_f32_16x16x32_bf16 v[120:123], v[158:161], v[182:185], v[120:123]
	v_mfma_f32_16x16x32_bf16 v[108:111], v[142:145], v[190:193], v[108:111]
	v_mfma_f32_16x16x32_bf16 v[104:107], v[158:161], v[190:193], v[104:107]
	v_mfma_f32_16x16x32_bf16 v[92:95], v[142:145], v[198:201], v[92:95]
	v_mfma_f32_16x16x32_bf16 v[88:91], v[158:161], v[198:201], v[88:91]
	v_mfma_f32_16x16x32_bf16 v[76:79], v[142:145], v[210:213], v[76:79]
	v_mfma_f32_16x16x32_bf16 v[72:75], v[158:161], v[210:213], v[72:75]
	s_setprio 0
	s_setprio 1
	v_mfma_f32_16x16x32_bf16 v[116:119], v[162:165], v[178:181], 0
	v_mfma_f32_16x16x32_bf16 v[112:115], v[170:173], v[178:181], 0
	v_mfma_f32_16x16x32_bf16 v[100:103], v[162:165], v[186:189], 0
	v_mfma_f32_16x16x32_bf16 v[96:99], v[170:173], v[186:189], 0
	v_mfma_f32_16x16x32_bf16 v[84:87], v[162:165], v[194:197], 0
	v_mfma_f32_16x16x32_bf16 v[80:83], v[170:173], v[194:197], 0
	v_mfma_f32_16x16x32_bf16 v[68:71], v[162:165], v[202:205], 0
	v_mfma_f32_16x16x32_bf16 v[64:67], v[170:173], v[202:205], 0
	v_mfma_f32_16x16x32_bf16 v[116:119], v[166:169], v[182:185], v[116:119]
	v_mfma_f32_16x16x32_bf16 v[112:115], v[174:177], v[182:185], v[112:115]
	v_mfma_f32_16x16x32_bf16 v[100:103], v[166:169], v[190:193], v[100:103]
	v_mfma_f32_16x16x32_bf16 v[96:99], v[174:177], v[190:193], v[96:99]
	v_mfma_f32_16x16x32_bf16 v[84:87], v[166:169], v[198:201], v[84:87]
	v_mfma_f32_16x16x32_bf16 v[80:83], v[174:177], v[198:201], v[80:83]
	v_mfma_f32_16x16x32_bf16 v[68:71], v[166:169], v[210:213], v[68:71]
	v_mfma_f32_16x16x32_bf16 v[64:67], v[174:177], v[210:213], v[64:67]
	s_setprio 0
	s_barrier
	v_lshl_add_u64 v[132:133], s[58:59], 0, v[134:135]
	s_add_i32 s58, s73, s23
	s_mov_b32 m0, s58
	ds_read_b128 v[178:181], v152 offset:16384
	ds_read_b128 v[182:185], v152 offset:17408
	ds_read_b128 v[186:189], v152 offset:18432
	ds_read_b128 v[190:193], v152 offset:19456
	ds_read_b128 v[194:197], v152 offset:20480
	ds_read_b128 v[198:201], v152 offset:21504
	ds_read_b128 v[202:205], v152 offset:22528
	ds_read_b128 v[210:213], v152 offset:23552
	global_load_lds_dwordx4 v[132:133], off
	v_lshl_add_u64 v[206:207], v[132:133], 0, s[14:15]
	s_add_i32 m0, s58, 0x2000
	s_add_i32 s58, s74, s23
	global_load_lds_dwordx4 v[206:207], off
	v_lshl_add_u64 v[206:207], v[132:133], 0, s[16:17]
	s_mov_b32 m0, s58
	s_nop 0
	global_load_lds_dwordx4 v[206:207], off
	v_lshl_add_u64 v[206:207], v[132:133], 0, s[24:25]
	s_add_i32 m0, s58, 0x2000
	s_nop 0
	global_load_lds_dwordx4 v[206:207], off
	v_lshl_add_u64 v[206:207], s[56:57], 0, v[134:135]
	s_mov_b32 m0, s30
	v_lshl_add_u64 v[214:215], v[206:207], 0, s[14:15]
	global_load_lds_dwordx4 v[206:207], off
	s_mov_b32 m0, s31
	s_nop 0
	global_load_lds_dwordx4 v[214:215], off
	s_waitcnt vmcnt(8)
	s_waitcnt lgkmcnt(0)
	s_barrier
; #define PG8_STAGE(bufoff, gbase, voff) do { _Pragma("unroll") for (int _i = 0; _i < 2; ++_i) \
;         __builtin_amdgcn_global_load_lds((const unsigned*)((const char*)(gbase) + (voff)[_i]), (PG8_LAS unsigned*)(lds + (bufoff) + ldsw + _i * 8192), 16, 0, 0); } while (0)
; #define PG8_LDA(dst, b, h) do { _Pragma("unroll") for (int m = 0; m < 4; ++m) _Pragma("unroll") for (int k = 0; k < 2; ++k) dst[m][k] = *(const PG8_LAS bf16x8*)(lds + PG8_SA(b, h) + aoff + m * 2048 + k * 1024); } while (0)
; #define PG8_LDB(dst, b, h) do { _Pragma("unroll") for (int n = 0; n < 2; ++n) _Pragma("unroll") for (int k = 0; k < 2; ++k) dst[n][k] = *(const PG8_LAS bf16x8*)(lds + PG8_SB(b, h) + boff + n * 2048 + k * 1024); } while (0)
; #define PG8_MMA(ai, bj, At, Bt) do { __builtin_amdgcn_s_setprio(1); _Pragma("unroll") for (int m = 0; m < 4; ++m) _Pragma("unroll") for (int n = 0; n < 2; ++n) _Pragma("unroll") for (int k = 0; k < 2; ++k) \
;         acc[ai][bj][m][n] = __builtin_amdgcn_mfma_f32_16x16x32_bf16(Bt[n][k], At[m][k], acc[ai][bj][m][n], 0, 0, 0); __builtin_amdgcn_s_setprio(0); } while (0)
; #define PG8_WAIT_V(n) asm volatile("s_waitcnt vmcnt(" #n ")" ::: "memory")
; #define PG8_WAIT_L(n) asm volatile("s_waitcnt lgkmcnt(" #n ")" ::: "memory")
; #define PG8_BAR __builtin_amdgcn_s_barrier()
; #define PG8_SCHED __builtin_amdgcn_sched_barrier(0)
; template <class Epi, class Sched, bool ALIGN_EPI = false, bool SP2 = false, bool TA = true>
; __device__ __forceinline__ void gemm_phase(PG8_LAS unsigned char* lds, const Gemm g, const Sched& S, const Epi& E) {
;     ...
;             PG8_WAIT_V(8); PG8_WAIT_L(0); PG8_BAR; PG8_MMA(0, 0, At, B0); PG8_MMA(0, 1, At, B1); PG8_BAR; PG8_SCHED;
;             PG8_LDA(At, 0, 1); PG8_STAGE(PG8_SB(0, 0), b2, voffB); PG8_STAGE(PG8_SB(0, 1), b2 + hstep, voffB); PG8_STAGE(PG8_SA(0, 0), a2, voffA);
;             PG8_WAIT_V(8); PG8_WAIT_L(0); PG8_BAR; PG8_MMA(1, 0, At, B0); PG8_MMA(1, 1, At, B1); PG8_BAR; PG8_SCHED;
;             PG8_LDB(B0, 1, 0); PG8_LDB(B1, 1, 1); PG8_SCHED; PG8_LDA(At, 1, 0); PG8_STAGE(PG8_SA(0, 1), a2 + hstep, voffA);
;             PG8_WAIT_V(8); PG8_WAIT_L(0); PG8_BAR; PG8_MMA(0, 0, At, B0); PG8_MMA(0, 1, At, B1); PG8_BAR; PG8_SCHED;
	s_setprio 1
	s_waitcnt lgkmcnt(0)
	v_mfma_f32_16x16x32_bf16 v[60:63], v[128:131], v[178:181], 0
	v_mfma_f32_16x16x32_bf16 v[56:59], v[154:157], v[178:181], 0
	v_mfma_f32_16x16x32_bf16 v[44:47], v[128:131], v[186:189], 0
	v_mfma_f32_16x16x32_bf16 v[40:43], v[154:157], v[186:189], 0
	v_mfma_f32_16x16x32_bf16 v[28:31], v[128:131], v[194:197], 0
	v_mfma_f32_16x16x32_bf16 v[24:27], v[154:157], v[194:197], 0
	v_mfma_f32_16x16x32_bf16 v[12:15], v[128:131], v[202:205], 0
	v_mfma_f32_16x16x32_bf16 v[8:11], v[154:157], v[202:205], 0
	v_mfma_f32_16x16x32_bf16 v[60:63], v[142:145], v[182:185], v[60:63]
	v_mfma_f32_16x16x32_bf16 v[56:59], v[158:161], v[182:185], v[56:59]
	v_mfma_f32_16x16x32_bf16 v[44:47], v[142:145], v[190:193], v[44:47]
	v_mfma_f32_16x16x32_bf16 v[40:43], v[158:161], v[190:193], v[40:43]
	v_mfma_f32_16x16x32_bf16 v[28:31], v[142:145], v[198:201], v[28:31]
	v_mfma_f32_16x16x32_bf16 v[24:27], v[158:161], v[198:201], v[24:27]
	v_mfma_f32_16x16x32_bf16 v[12:15], v[142:145], v[210:213], v[12:15]
	v_mfma_f32_16x16x32_bf16 v[8:11], v[158:161], v[210:213], v[8:11]
	s_setprio 0
	s_setprio 1
	v_mfma_f32_16x16x32_bf16 v[52:55], v[162:165], v[178:181], 0
	v_mfma_f32_16x16x32_bf16 v[48:51], v[170:173], v[178:181], 0
	v_mfma_f32_16x16x32_bf16 v[36:39], v[162:165], v[186:189], 0
	v_mfma_f32_16x16x32_bf16 v[32:35], v[170:173], v[186:189], 0
	v_mfma_f32_16x16x32_bf16 v[20:23], v[162:165], v[194:197], 0
	v_mfma_f32_16x16x32_bf16 v[16:19], v[170:173], v[194:197], 0
	v_mfma_f32_16x16x32_bf16 v[4:7], v[162:165], v[202:205], 0
	v_mfma_f32_16x16x32_bf16 v[0:3], v[170:173], v[202:205], 0
	v_mfma_f32_16x16x32_bf16 v[52:55], v[166:169], v[182:185], v[52:55]
	v_mfma_f32_16x16x32_bf16 v[48:51], v[174:177], v[182:185], v[48:51]
	v_mfma_f32_16x16x32_bf16 v[36:39], v[166:169], v[190:193], v[36:39]
	v_mfma_f32_16x16x32_bf16 v[32:35], v[174:177], v[190:193], v[32:35]
	v_mfma_f32_16x16x32_bf16 v[20:23], v[166:169], v[198:201], v[20:23]
	v_mfma_f32_16x16x32_bf16 v[16:19], v[174:177], v[198:201], v[16:19]
	v_mfma_f32_16x16x32_bf16 v[4:7], v[166:169], v[210:213], v[4:7]
	v_mfma_f32_16x16x32_bf16 v[0:3], v[174:177], v[210:213], v[0:3]
	s_setprio 0
	s_barrier
	s_add_i32 s56, 0, 0x18000
	v_add_u32_e32 v136, s56, v149
	s_add_i32 s57, 0, 0x1c000
	ds_read_b128 v[128:131], v136
	ds_read_b128 v[142:145], v136 offset:1024
	ds_read_b128 v[154:157], v136 offset:2048
	ds_read_b128 v[158:161], v136 offset:3072
	v_add_u32_e32 v136, s57, v149
	ds_read_b128 v[162:165], v136
	ds_read_b128 v[166:169], v136 offset:1024
	ds_read_b128 v[170:173], v136 offset:2048
	ds_read_b128 v[174:177], v136 offset:3072
	s_mov_b32 m0, s33
	v_lshl_add_u64 v[214:215], v[206:207], 0, s[16:17]
	ds_read_b128 v[178:181], v152 offset:32768
	ds_read_b128 v[182:185], v152 offset:33792
	ds_read_b128 v[186:189], v152 offset:34816
	ds_read_b128 v[190:193], v152 offset:35840
	ds_read_b128 v[194:197], v152 offset:36864
	ds_read_b128 v[198:201], v152 offset:37888
	ds_read_b128 v[202:205], v152 offset:38912
	ds_read_b128 v[210:213], v152 offset:39936
	global_load_lds_dwordx4 v[214:215], off
	v_lshl_add_u64 v[214:215], v[206:207], 0, s[24:25]
	s_mov_b32 m0, s62
	s_nop 0
	global_load_lds_dwordx4 v[214:215], off
	s_waitcnt vmcnt(8)
	s_waitcnt lgkmcnt(0)
	s_barrier
	s_setprio 1
	s_waitcnt lgkmcnt(0)
	v_mfma_f32_16x16x32_bf16 v[124:127], v[128:131], v[178:181], v[124:127]
	v_mfma_f32_16x16x32_bf16 v[120:123], v[154:157], v[178:181], v[120:123]
	v_mfma_f32_16x16x32_bf16 v[108:111], v[128:131], v[186:189], v[108:111]
	v_mfma_f32_16x16x32_bf16 v[104:107], v[154:157], v[186:189], v[104:107]
	v_mfma_f32_16x16x32_bf16 v[92:95], v[128:131], v[194:197], v[92:95]
	v_mfma_f32_16x16x32_bf16 v[88:91], v[154:157], v[194:197], v[88:91]
	v_mfma_f32_16x16x32_bf16 v[76:79], v[128:131], v[202:205], v[76:79]
	v_mfma_f32_16x16x32_bf16 v[72:75], v[154:157], v[202:205], v[72:75]
	v_mfma_f32_16x16x32_bf16 v[124:127], v[142:145], v[182:185], v[124:127]
	v_mfma_f32_16x16x32_bf16 v[120:123], v[158:161], v[182:185], v[120:123]
	v_mfma_f32_16x16x32_bf16 v[108:111], v[142:145], v[190:193], v[108:111]
	v_mfma_f32_16x16x32_bf16 v[104:107], v[158:161], v[190:193], v[104:107]
	v_mfma_f32_16x16x32_bf16 v[92:95], v[142:145], v[198:201], v[92:95]
	v_mfma_f32_16x16x32_bf16 v[88:91], v[158:161], v[198:201], v[88:91]
	v_mfma_f32_16x16x32_bf16 v[76:79], v[142:145], v[210:213], v[76:79]
	v_mfma_f32_16x16x32_bf16 v[72:75], v[158:161], v[210:213], v[72:75]
	s_setprio 0
	s_setprio 1
	v_mfma_f32_16x16x32_bf16 v[116:119], v[162:165], v[178:181], v[116:119]
	v_mfma_f32_16x16x32_bf16 v[112:115], v[170:173], v[178:181], v[112:115]
	v_mfma_f32_16x16x32_bf16 v[100:103], v[162:165], v[186:189], v[100:103]
	v_mfma_f32_16x16x32_bf16 v[96:99], v[170:173], v[186:189], v[96:99]
	v_mfma_f32_16x16x32_bf16 v[84:87], v[162:165], v[194:197], v[84:87]
	v_mfma_f32_16x16x32_bf16 v[80:83], v[170:173], v[194:197], v[80:83]
	v_mfma_f32_16x16x32_bf16 v[68:71], v[162:165], v[202:205], v[68:71]
	v_mfma_f32_16x16x32_bf16 v[64:67], v[170:173], v[202:205], v[64:67]
	v_mfma_f32_16x16x32_bf16 v[116:119], v[166:169], v[182:185], v[116:119]
	v_mfma_f32_16x16x32_bf16 v[112:115], v[174:177], v[182:185], v[112:115]
	v_mfma_f32_16x16x32_bf16 v[100:103], v[166:169], v[190:193], v[100:103]
	v_mfma_f32_16x16x32_bf16 v[96:99], v[174:177], v[190:193], v[96:99]
	v_mfma_f32_16x16x32_bf16 v[84:87], v[166:169], v[198:201], v[84:87]
	v_mfma_f32_16x16x32_bf16 v[80:83], v[174:177], v[198:201], v[80:83]
	v_mfma_f32_16x16x32_bf16 v[68:71], v[166:169], v[210:213], v[68:71]
	v_mfma_f32_16x16x32_bf16 v[64:67], v[174:177], v[210:213], v[64:67]
	s_setprio 0
	s_barrier
; #define PG8_STAGE(bufoff, gbase, voff) do { _Pragma("unroll") for (int _i = 0; _i < 2; ++_i) \
;         __builtin_amdgcn_global_load_lds((const unsigned*)((const char*)(gbase) + (voff)[_i]), (PG8_LAS unsigned*)(lds + (bufoff) + ldsw + _i * 8192), 16, 0, 0); } while (0)
; #define PG8_LDA(dst, b, h) do { _Pragma("unroll") for (int m = 0; m < 4; ++m) _Pragma("unroll") for (int k = 0; k < 2; ++k) dst[m][k] = *(const PG8_LAS bf16x8*)(lds + PG8_SA(b, h) + aoff + m * 2048 + k * 1024); } while (0)
; #define PG8_LDB(dst, b, h) do { _Pragma("unroll") for (int n = 0; n < 2; ++n) _Pragma("unroll") for (int k = 0; k < 2; ++k) dst[n][k] = *(const PG8_LAS bf16x8*)(lds + PG8_SB(b, h) + boff + n * 2048 + k * 1024); } while (0)
; #define PG8_MMA(ai, bj, At, Bt) do { __builtin_amdgcn_s_setprio(1); _Pragma("unroll") for (int m = 0; m < 4; ++m) _Pragma("unroll") for (int n = 0; n < 2; ++n) _Pragma("unroll") for (int k = 0; k < 2; ++k) \
;         acc[ai][bj][m][n] = __builtin_amdgcn_mfma_f32_16x16x32_bf16(Bt[n][k], At[m][k], acc[ai][bj][m][n], 0, 0, 0); __builtin_amdgcn_s_setprio(0); } while (0)
; #define PG8_WAIT_V(n) asm volatile("s_waitcnt vmcnt(" #n ")" ::: "memory")
; #define PG8_WAIT_L(n) asm volatile("s_waitcnt lgkmcnt(" #n ")" ::: "memory")
; #define PG8_BAR __builtin_amdgcn_s_barrier()
; template <class Epi, class Sched, bool ALIGN_EPI = false, bool SP2 = false, bool TA = true>
; __device__ __forceinline__ void gemm_phase(PG8_LAS unsigned char* lds, const Gemm g, const Sched& S, const Epi& E) {
;     ...
;         for (int t = 0; t < nt; t += 2) {
;             const bool last = (t == nt - 2);
;             const char* a1 = cA + (size_t)(t + 1) * kstep;
;             const char* a2 = last ? nA : cA + (size_t)(t + 2) * kstep; const char* b2 = last ? nB : cB + (size_t)(t + 2) * kstepB;
;             const char* a3 = a2 + kstep; const char* b3 = b2 + kstepB;
;     ...
;             PG8_LDB(B0, 1, 0); PG8_LDB(B1, 1, 1); PG8_SCHED; PG8_LDA(At, 1, 0); PG8_STAGE(PG8_SA(0, 1), a2 + hstep, voffA);
;             PG8_WAIT_V(8); PG8_WAIT_L(0); PG8_BAR; PG8_MMA(0, 0, At, B0); PG8_MMA(0, 1, At, B1); PG8_BAR; PG8_SCHED;
;             PG8_LDA(At, 1, 1); PG8_STAGE(PG8_SB(1, 0), b3, voffB); PG8_STAGE(PG8_SB(1, 1), b3 + hstep, voffB); PG8_STAGE(PG8_SA(1, 0), a3, voffA);
;             PG8_WAIT_V(8); PG8_WAIT_L(0); PG8_BAR; PG8_MMA(1, 0, At, B0); PG8_MMA(1, 1, At, B1); PG8_BAR; PG8_SCHED;
	s_add_i32 s56, s56, s23
	v_lshl_add_u64 v[214:215], v[132:133], 0, s[38:39]
	s_mov_b32 m0, s56
	ds_read_b128 v[178:181], v152 offset:49152
	ds_read_b128 v[182:185], v152 offset:50176
	ds_read_b128 v[186:189], v152 offset:51200
	ds_read_b128 v[190:193], v152 offset:52224
	ds_read_b128 v[194:197], v152 offset:53248
	ds_read_b128 v[198:201], v152 offset:54272
	ds_read_b128 v[202:205], v152 offset:55296
	ds_read_b128 v[210:213], v152 offset:56320
	global_load_lds_dwordx4 v[214:215], off
	v_lshl_add_u64 v[214:215], v[132:133], 0, s[40:41]
	s_add_i32 m0, s56, 0x2000
	s_add_i32 s56, s57, s23
	global_load_lds_dwordx4 v[214:215], off
	v_lshl_add_u64 v[214:215], v[132:133], 0, s[42:43]
	s_mov_b32 m0, s56
	v_lshl_add_u64 v[132:133], v[132:133], 0, s[44:45]
	global_load_lds_dwordx4 v[214:215], off
	s_add_i32 m0, s56, 0x2000
	s_nop 0
	global_load_lds_dwordx4 v[132:133], off
	v_lshl_add_u64 v[132:133], v[206:207], 0, s[38:39]
	s_mov_b32 m0, s63
	s_nop 0
	global_load_lds_dwordx4 v[132:133], off
	v_lshl_add_u64 v[132:133], v[206:207], 0, s[40:41]
	s_mov_b32 m0, s64
	s_nop 0
	global_load_lds_dwordx4 v[132:133], off
	s_waitcnt vmcnt(8)
	s_waitcnt lgkmcnt(0)
	s_barrier
	s_setprio 1
	s_waitcnt lgkmcnt(0)
	v_mfma_f32_16x16x32_bf16 v[60:63], v[128:131], v[178:181], v[60:63]
	v_mfma_f32_16x16x32_bf16 v[56:59], v[154:157], v[178:181], v[56:59]
	v_mfma_f32_16x16x32_bf16 v[44:47], v[128:131], v[186:189], v[44:47]
	v_mfma_f32_16x16x32_bf16 v[40:43], v[154:157], v[186:189], v[40:43]
	v_mfma_f32_16x16x32_bf16 v[28:31], v[128:131], v[194:197], v[28:31]
	v_mfma_f32_16x16x32_bf16 v[24:27], v[154:157], v[194:197], v[24:27]
	v_mfma_f32_16x16x32_bf16 v[12:15], v[128:131], v[202:205], v[12:15]
	v_mfma_f32_16x16x32_bf16 v[8:11], v[154:157], v[202:205], v[8:11]
	v_mfma_f32_16x16x32_bf16 v[60:63], v[142:145], v[182:185], v[60:63]
	v_mfma_f32_16x16x32_bf16 v[56:59], v[158:161], v[182:185], v[56:59]
	v_mfma_f32_16x16x32_bf16 v[44:47], v[142:145], v[190:193], v[44:47]
	v_mfma_f32_16x16x32_bf16 v[40:43], v[158:161], v[190:193], v[40:43]
	v_mfma_f32_16x16x32_bf16 v[28:31], v[142:145], v[198:201], v[28:31]
	v_mfma_f32_16x16x32_bf16 v[24:27], v[158:161], v[198:201], v[24:27]
	v_mfma_f32_16x16x32_bf16 v[12:15], v[142:145], v[210:213], v[12:15]
	v_mfma_f32_16x16x32_bf16 v[8:11], v[158:161], v[210:213], v[8:11]
	s_setprio 0
	s_setprio 1
	v_mfma_f32_16x16x32_bf16 v[52:55], v[162:165], v[178:181], v[52:55]
	v_mfma_f32_16x16x32_bf16 v[48:51], v[170:173], v[178:181], v[48:51]
	v_mfma_f32_16x16x32_bf16 v[36:39], v[162:165], v[186:189], v[36:39]
	v_mfma_f32_16x16x32_bf16 v[32:35], v[170:173], v[186:189], v[32:35]
	v_mfma_f32_16x16x32_bf16 v[20:23], v[162:165], v[194:197], v[20:23]
	v_mfma_f32_16x16x32_bf16 v[16:19], v[170:173], v[194:197], v[16:19]
	v_mfma_f32_16x16x32_bf16 v[4:7], v[162:165], v[202:205], v[4:7]
	v_mfma_f32_16x16x32_bf16 v[0:3], v[170:173], v[202:205], v[0:3]
	v_mfma_f32_16x16x32_bf16 v[52:55], v[166:169], v[182:185], v[52:55]
	v_mfma_f32_16x16x32_bf16 v[48:51], v[174:177], v[182:185], v[48:51]
	v_mfma_f32_16x16x32_bf16 v[36:39], v[166:169], v[190:193], v[36:39]
	v_mfma_f32_16x16x32_bf16 v[32:35], v[174:177], v[190:193], v[32:35]
	v_mfma_f32_16x16x32_bf16 v[20:23], v[166:169], v[198:201], v[20:23]
	v_mfma_f32_16x16x32_bf16 v[16:19], v[174:177], v[198:201], v[16:19]
	v_mfma_f32_16x16x32_bf16 v[4:7], v[166:169], v[210:213], v[4:7]
	v_mfma_f32_16x16x32_bf16 v[0:3], v[174:177], v[210:213], v[0:3]
	s_setprio 0
	s_barrier
	s_add_i32 s55, s55, 2
	s_add_u32 s50, s50, 0x8000
	s_addc_u32 s51, s51, 0
	s_add_u32 s52, s52, 0x8000
	s_addc_u32 s53, s53, 0
	s_cmp_gt_u32 s55, 41

; #define PG8_STAGE(bufoff, gbase, voff) do { _Pragma("unroll") for (int _i = 0; _i < 2; ++_i) \
;         __builtin_amdgcn_global_load_lds((const unsigned*)((const char*)(gbase) + (voff)[_i]), (PG8_LAS unsigned*)(lds + (bufoff) + ldsw + _i * 8192), 16, 0, 0); } while (0)
; #define PG8_LDA(dst, b, h) do { _Pragma("unroll") for (int m = 0; m < 4; ++m) _Pragma("unroll") for (int k = 0; k < 2; ++k) dst[m][k] = *(const PG8_LAS bf16x8*)(lds + PG8_SA(b, h) + aoff + m * 2048 + k * 1024); } while (0)
; #define PG8_LDB(dst, b, h) do { _Pragma("unroll") for (int n = 0; n < 2; ++n) _Pragma("unroll") for (int k = 0; k < 2; ++k) dst[n][k] = *(const PG8_LAS bf16x8*)(lds + PG8_SB(b, h) + boff + n * 2048 + k * 1024); } while (0)
; #define PG8_WAIT_V(n) asm volatile("s_waitcnt vmcnt(" #n ")" ::: "memory")
; #define PG8_WAIT_L(n) asm volatile("s_waitcnt lgkmcnt(" #n ")" ::: "memory")
; #define PG8_BAR __builtin_amdgcn_s_barrier()
; #define PG8_SCHED __builtin_amdgcn_sched_barrier(0)
; template <class Epi, class Sched, bool ALIGN_EPI = false, bool SP2 = false, bool TA = true>
; __device__ __forceinline__ void gemm_phase(PG8_LAS unsigned char* lds, const Gemm g, const Sched& S, const Epi& E) {
;     ...
;         const bool has_next = S.next(ui + 1, nxt);
;         const char* nA = has_next ? (const char*)g.A + (size_t)nxt.pm * tstep : cA; const char* nB = has_next ? (const char*)g.Bt + (size_t)nxt.pn * tstep : cB;
; #pragma unroll 1
;         for (int t = 0; t < nt; t += 2) {
;             const bool last = (t == nt - 2);
;             const char* a1 = cA + (size_t)(t + 1) * kstep;
;             const char* a2 = last ? nA : cA + (size_t)(t + 2) * kstep; const char* b2 = last ? nB : cB + (size_t)(t + 2) * kstepB;
;             const char* a3 = a2 + kstep; const char* b3 = b2 + kstepB;
;             if (last && has_next) S.a_ready(nxt);
;             if constexpr (SP2) {
;             PG8_LDB(B0, 0, 0); PG8_LDB(B1, 0, 1); PG8_SCHED; PG8_LDA(At, 0, 0); PG8_STAGE(PG8_SA(1, 1), a1 + hstep, voffA);
;             PG8_WAIT_V(8); PG8_WAIT_L(0); PG8_BAR; PG8_MMA(0, 0, At, B0); PG8_MMA(0, 1, At, B1); PG8_BAR; PG8_SCHED;
;             PG8_LDA(At, 0, 1); PG8_STAGE(PG8_SB(0, 0), b2, voffB); PG8_STAGE(PG8_SB(0, 1), b2 + hstep, voffB); PG8_STAGE(PG8_SA(0, 0), a2, voffA);
;             PG8_WAIT_V(8); PG8_WAIT_L(0); PG8_BAR; PG8_MMA(1, 0, At, B0); PG8_MMA(1, 1, At, B1); PG8_BAR; PG8_SCHED;
.LBB0_1751:
	s_ashr_i32 s45, s44, 31
	s_lshl_b64 s[46:47], s[44:45], 17
	s_add_u32 s46, s19, s46
	s_addc_u32 s47, s21, s47
	s_and_b64 s[48:49], s[2:3], exec
	s_cselect_b32 s45, s47, s55
	s_cselect_b32 s80, s46, s54
	s_ashr_i32 s43, s42, 31
	s_lshl_b64 s[48:49], s[42:43], 17
	s_add_u32 s48, s22, s48
	s_addc_u32 s49, s23, s49
	s_and_b64 s[56:57], s[2:3], exec
	s_cselect_b32 s43, s49, s53
	s_cselect_b32 s81, s48, s52
	s_mov_b64 s[60:61], 0
	s_mov_b64 s[56:57], -1
	s_mov_b64 s[58:59], 0
	s_add_u32 s64, s54, s60
	s_addc_u32 s65, s55, s61
	ds_read_b128 v[140:143], v137
	ds_read_b128 v[148:151], v137 offset:1024
	ds_read_b128 v[152:155], v137 offset:2048
	ds_read_b128 v[156:159], v137 offset:3072
	ds_read_b128 v[160:163], v138
	ds_read_b128 v[164:167], v138 offset:1024
	ds_read_b128 v[168:171], v138 offset:2048
	ds_read_b128 v[172:175], v138 offset:3072
	s_add_u32 s82, s64, 0x8000
	s_addc_u32 s83, s65, 0
	s_and_b64 s[62:63], s[58:59], exec
	s_cselect_b32 s62, s80, s82
	s_cselect_b32 s63, s45, s83
	s_add_u32 s60, s52, s60
	s_addc_u32 s61, s53, s61
	s_add_u32 s60, s60, 0x8000
	s_addc_u32 s61, s61, 0
	s_and_b64 s[58:59], s[58:59], exec
	s_cselect_b32 s58, s81, s60
	s_cselect_b32 s59, s43, s61
	s_add_i32 s82, 0, 0x18000
	s_add_i32 s61, 0, 0x1c000
	s_add_i32 s86, s77, s30
	s_add_i32 s84, s78, s30
	s_add_i32 s60, s82, s30
	s_add_i32 s88, s61, s30
	s_add_i32 m0, s31, 0xc000
	s_add_i32 s90, s31, 0xe000
	s_add_i32 s85, s86, 0x2000
	s_add_i32 s83, s84, 0x2000
	s_add_i32 s89, s60, 0x2000
	s_add_i32 s87, s88, 0x2000
	v_lshl_add_u64 v[144:145], s[64:65], 0, v[134:135]
	v_lshl_add_u64 v[210:211], v[144:145], 0, s[36:37]
	ds_read_b128 v[176:179], v139
	ds_read_b128 v[180:183], v139 offset:1024
	ds_read_b128 v[184:187], v139 offset:2048
	ds_read_b128 v[188:191], v139 offset:3072
	ds_read_b128 v[192:195], v139 offset:4096
	ds_read_b128 v[196:199], v139 offset:5120
	ds_read_b128 v[200:203], v139 offset:6144
	ds_read_b128 v[204:207], v139 offset:7168
	global_load_lds_dwordx4 v[210:211], off
	v_lshl_add_u64 v[144:145], v[144:145], 0, s[38:39]
	s_mov_b32 m0, s90
	s_nop 0
	global_load_lds_dwordx4 v[144:145], off
	s_waitcnt vmcnt(8)
	s_waitcnt lgkmcnt(0)
	s_barrier
	s_setprio 1
	s_waitcnt lgkmcnt(0)
	v_mfma_f32_16x16x32_bf16 v[124:127], v[140:143], v[176:179], 0
	v_mfma_f32_16x16x32_bf16 v[120:123], v[152:155], v[176:179], 0
	v_mfma_f32_16x16x32_bf16 v[108:111], v[140:143], v[184:187], 0
	v_mfma_f32_16x16x32_bf16 v[104:107], v[152:155], v[184:187], 0
	v_mfma_f32_16x16x32_bf16 v[100:103], v[140:143], v[192:195], 0
	v_mfma_f32_16x16x32_bf16 v[92:95], v[152:155], v[192:195], 0
	v_mfma_f32_16x16x32_bf16 v[84:87], v[140:143], v[200:203], 0
	v_mfma_f32_16x16x32_bf16 v[76:79], v[152:155], v[200:203], 0
	v_mfma_f32_16x16x32_bf16 v[124:127], v[148:151], v[180:183], v[124:127]
	v_mfma_f32_16x16x32_bf16 v[120:123], v[156:159], v[180:183], v[120:123]
	v_mfma_f32_16x16x32_bf16 v[108:111], v[148:151], v[188:191], v[108:111]
	v_mfma_f32_16x16x32_bf16 v[104:107], v[156:159], v[188:191], v[104:107]
	v_mfma_f32_16x16x32_bf16 v[100:103], v[148:151], v[196:199], v[100:103]
	v_mfma_f32_16x16x32_bf16 v[92:95], v[156:159], v[196:199], v[92:95]
	v_mfma_f32_16x16x32_bf16 v[84:87], v[148:151], v[204:207], v[84:87]
	v_mfma_f32_16x16x32_bf16 v[76:79], v[156:159], v[204:207], v[76:79]
	s_setprio 0
	s_setprio 1
	v_mfma_f32_16x16x32_bf16 v[116:119], v[160:163], v[176:179], 0
	v_mfma_f32_16x16x32_bf16 v[112:115], v[168:171], v[176:179], 0
	v_mfma_f32_16x16x32_bf16 v[96:99], v[160:163], v[184:187], 0
	v_mfma_f32_16x16x32_bf16 v[88:91], v[168:171], v[184:187], 0
	v_mfma_f32_16x16x32_bf16 v[80:83], v[160:163], v[192:195], 0
	v_mfma_f32_16x16x32_bf16 v[72:75], v[168:171], v[192:195], 0
	v_mfma_f32_16x16x32_bf16 v[68:71], v[160:163], v[200:203], 0
	v_mfma_f32_16x16x32_bf16 v[64:67], v[168:171], v[200:203], 0
	v_mfma_f32_16x16x32_bf16 v[116:119], v[164:167], v[180:183], v[116:119]
	v_mfma_f32_16x16x32_bf16 v[112:115], v[172:175], v[180:183], v[112:115]
	v_mfma_f32_16x16x32_bf16 v[96:99], v[164:167], v[188:191], v[96:99]
	v_mfma_f32_16x16x32_bf16 v[88:91], v[172:175], v[188:191], v[88:91]
	v_mfma_f32_16x16x32_bf16 v[80:83], v[164:167], v[196:199], v[80:83]
	v_mfma_f32_16x16x32_bf16 v[72:75], v[172:175], v[196:199], v[72:75]
	v_mfma_f32_16x16x32_bf16 v[68:71], v[164:167], v[204:207], v[68:71]
	v_mfma_f32_16x16x32_bf16 v[64:67], v[172:175], v[204:207], v[64:67]
	s_setprio 0
	s_barrier
	s_mov_b32 m0, s86
	v_lshl_add_u64 v[144:145], s[58:59], 0, v[134:135]
	ds_read_b128 v[176:179], v139 offset:16384
	ds_read_b128 v[180:183], v139 offset:17408
	ds_read_b128 v[184:187], v139 offset:18432
	ds_read_b128 v[188:191], v139 offset:19456
	ds_read_b128 v[192:195], v139 offset:20480
	ds_read_b128 v[196:199], v139 offset:21504
	ds_read_b128 v[200:203], v139 offset:22528
	ds_read_b128 v[204:207], v139 offset:23552
	global_load_lds_dwordx4 v[144:145], off
	v_lshl_add_u64 v[210:211], v[144:145], 0, s[0:1]
	s_mov_b32 m0, s85
	s_nop 0
	global_load_lds_dwordx4 v[210:211], off
	v_lshl_add_u64 v[210:211], v[144:145], 0, s[4:5]
	s_mov_b32 m0, s84
	s_nop 0
	global_load_lds_dwordx4 v[210:211], off
	v_lshl_add_u64 v[210:211], v[144:145], 0, s[6:7]
	s_mov_b32 m0, s83
	s_nop 0
	global_load_lds_dwordx4 v[210:211], off
	v_lshl_add_u64 v[210:211], s[62:63], 0, v[134:135]
	s_mov_b32 m0, s31
	v_lshl_add_u64 v[212:213], v[210:211], 0, s[0:1]
	global_load_lds_dwordx4 v[210:211], off
	s_mov_b32 m0, s33
	s_nop 0
	global_load_lds_dwordx4 v[212:213], off
	s_waitcnt vmcnt(8)
	s_waitcnt lgkmcnt(0)
	s_barrier
; #define PG8_STAGE(bufoff, gbase, voff) do { _Pragma("unroll") for (int _i = 0; _i < 2; ++_i) \
;         __builtin_amdgcn_global_load_lds((const unsigned*)((const char*)(gbase) + (voff)[_i]), (PG8_LAS unsigned*)(lds + (bufoff) + ldsw + _i * 8192), 16, 0, 0); } while (0)
; #define PG8_LDA(dst, b, h) do { _Pragma("unroll") for (int m = 0; m < 4; ++m) _Pragma("unroll") for (int k = 0; k < 2; ++k) dst[m][k] = *(const PG8_LAS bf16x8*)(lds + PG8_SA(b, h) + aoff + m * 2048 + k * 1024); } while (0)
; #define PG8_LDB(dst, b, h) do { _Pragma("unroll") for (int n = 0; n < 2; ++n) _Pragma("unroll") for (int k = 0; k < 2; ++k) dst[n][k] = *(const PG8_LAS bf16x8*)(lds + PG8_SB(b, h) + boff + n * 2048 + k * 1024); } while (0)
; #define PG8_MMA(ai, bj, At, Bt) do { __builtin_amdgcn_s_setprio(1); _Pragma("unroll") for (int m = 0; m < 4; ++m) _Pragma("unroll") for (int n = 0; n < 2; ++n) _Pragma("unroll") for (int k = 0; k < 2; ++k) \
;         acc[ai][bj][m][n] = __builtin_amdgcn_mfma_f32_16x16x32_bf16(Bt[n][k], At[m][k], acc[ai][bj][m][n], 0, 0, 0); __builtin_amdgcn_s_setprio(0); } while (0)
; #define PG8_WAIT_V(n) asm volatile("s_waitcnt vmcnt(" #n ")" ::: "memory")
; #define PG8_WAIT_L(n) asm volatile("s_waitcnt lgkmcnt(" #n ")" ::: "memory")
; #define PG8_BAR __builtin_amdgcn_s_barrier()
; #define PG8_SCHED __builtin_amdgcn_sched_barrier(0)
; template <class Epi, class Sched, bool ALIGN_EPI = false, bool SP2 = false, bool TA = true>
; __device__ __forceinline__ void gemm_phase(PG8_LAS unsigned char* lds, const Gemm g, const Sched& S, const Epi& E) {
;     ...
;             PG8_WAIT_V(8); PG8_WAIT_L(0); PG8_BAR; PG8_MMA(0, 0, At, B0); PG8_MMA(0, 1, At, B1); PG8_BAR; PG8_SCHED;
;             PG8_LDA(At, 0, 1); PG8_STAGE(PG8_SB(0, 0), b2, voffB); PG8_STAGE(PG8_SB(0, 1), b2 + hstep, voffB); PG8_STAGE(PG8_SA(0, 0), a2, voffA);
;             PG8_WAIT_V(8); PG8_WAIT_L(0); PG8_BAR; PG8_MMA(1, 0, At, B0); PG8_MMA(1, 1, At, B1); PG8_BAR; PG8_SCHED;
;             PG8_LDB(B0, 1, 0); PG8_LDB(B1, 1, 1); PG8_SCHED; PG8_LDA(At, 1, 0); PG8_STAGE(PG8_SA(0, 1), a2 + hstep, voffA);
;             PG8_WAIT_V(8); PG8_WAIT_L(0); PG8_BAR; PG8_MMA(0, 0, At, B0); PG8_MMA(0, 1, At, B1); PG8_BAR; PG8_SCHED;
	s_setprio 1
	s_waitcnt lgkmcnt(0)
	v_mfma_f32_16x16x32_bf16 v[60:63], v[140:143], v[176:179], 0
	v_mfma_f32_16x16x32_bf16 v[56:59], v[152:155], v[176:179], 0
	v_mfma_f32_16x16x32_bf16 v[48:51], v[140:143], v[184:187], 0
	v_mfma_f32_16x16x32_bf16 v[40:43], v[152:155], v[184:187], 0
	v_mfma_f32_16x16x32_bf16 v[32:35], v[140:143], v[192:195], 0
	v_mfma_f32_16x16x32_bf16 v[24:27], v[152:155], v[192:195], 0
	v_mfma_f32_16x16x32_bf16 v[16:19], v[140:143], v[200:203], 0
	v_mfma_f32_16x16x32_bf16 v[8:11], v[152:155], v[200:203], 0
	v_mfma_f32_16x16x32_bf16 v[60:63], v[148:151], v[180:183], v[60:63]
	v_mfma_f32_16x16x32_bf16 v[56:59], v[156:159], v[180:183], v[56:59]
	v_mfma_f32_16x16x32_bf16 v[48:51], v[148:151], v[188:191], v[48:51]
	v_mfma_f32_16x16x32_bf16 v[40:43], v[156:159], v[188:191], v[40:43]
	v_mfma_f32_16x16x32_bf16 v[32:35], v[148:151], v[196:199], v[32:35]
	v_mfma_f32_16x16x32_bf16 v[24:27], v[156:159], v[196:199], v[24:27]
	v_mfma_f32_16x16x32_bf16 v[16:19], v[148:151], v[204:207], v[16:19]
	v_mfma_f32_16x16x32_bf16 v[8:11], v[156:159], v[204:207], v[8:11]
	s_setprio 0
	s_setprio 1
	v_mfma_f32_16x16x32_bf16 v[52:55], v[160:163], v[176:179], 0
	v_mfma_f32_16x16x32_bf16 v[44:47], v[168:171], v[176:179], 0
	v_mfma_f32_16x16x32_bf16 v[36:39], v[160:163], v[184:187], 0
	v_mfma_f32_16x16x32_bf16 v[28:31], v[168:171], v[184:187], 0
	v_mfma_f32_16x16x32_bf16 v[20:23], v[160:163], v[192:195], 0
	v_mfma_f32_16x16x32_bf16 v[12:15], v[168:171], v[192:195], 0
	v_mfma_f32_16x16x32_bf16 v[4:7], v[160:163], v[200:203], 0
	v_mfma_f32_16x16x32_bf16 v[0:3], v[168:171], v[200:203], 0
	v_mfma_f32_16x16x32_bf16 v[52:55], v[164:167], v[180:183], v[52:55]
	v_mfma_f32_16x16x32_bf16 v[44:47], v[172:175], v[180:183], v[44:47]
	v_mfma_f32_16x16x32_bf16 v[36:39], v[164:167], v[188:191], v[36:39]
	v_mfma_f32_16x16x32_bf16 v[28:31], v[172:175], v[188:191], v[28:31]
	v_mfma_f32_16x16x32_bf16 v[20:23], v[164:167], v[196:199], v[20:23]
	v_mfma_f32_16x16x32_bf16 v[12:15], v[172:175], v[196:199], v[12:15]
	v_mfma_f32_16x16x32_bf16 v[4:7], v[164:167], v[204:207], v[4:7]
	v_mfma_f32_16x16x32_bf16 v[0:3], v[172:175], v[204:207], v[0:3]
	s_setprio 0
	s_barrier
	v_add_u32_e32 v128, s82, v136
	ds_read_b128 v[140:143], v128
	ds_read_b128 v[148:151], v128 offset:1024
	ds_read_b128 v[152:155], v128 offset:2048
	ds_read_b128 v[156:159], v128 offset:3072
	v_add_u32_e32 v128, s61, v136
	ds_read_b128 v[160:163], v128
	ds_read_b128 v[164:167], v128 offset:1024
	ds_read_b128 v[168:171], v128 offset:2048
	ds_read_b128 v[172:175], v128 offset:3072
	s_mov_b32 m0, s66
	v_lshl_add_u64 v[212:213], v[210:211], 0, s[4:5]
	ds_read_b128 v[176:179], v139 offset:32768
	ds_read_b128 v[180:183], v139 offset:33792
	ds_read_b128 v[184:187], v139 offset:34816
	ds_read_b128 v[188:191], v139 offset:35840
	ds_read_b128 v[192:195], v139 offset:36864
	ds_read_b128 v[196:199], v139 offset:37888
	ds_read_b128 v[200:203], v139 offset:38912
	ds_read_b128 v[204:207], v139 offset:39936
	global_load_lds_dwordx4 v[212:213], off
	v_lshl_add_u64 v[212:213], v[210:211], 0, s[6:7]
	s_mov_b32 m0, s67
	s_nop 0
	global_load_lds_dwordx4 v[212:213], off
	s_waitcnt vmcnt(8)
	s_waitcnt lgkmcnt(0)
	s_barrier
	s_setprio 1
	s_waitcnt lgkmcnt(0)
	v_mfma_f32_16x16x32_bf16 v[124:127], v[140:143], v[176:179], v[124:127]
	v_mfma_f32_16x16x32_bf16 v[120:123], v[152:155], v[176:179], v[120:123]
	v_mfma_f32_16x16x32_bf16 v[108:111], v[140:143], v[184:187], v[108:111]
	v_mfma_f32_16x16x32_bf16 v[104:107], v[152:155], v[184:187], v[104:107]
	v_mfma_f32_16x16x32_bf16 v[100:103], v[140:143], v[192:195], v[100:103]
	v_mfma_f32_16x16x32_bf16 v[92:95], v[152:155], v[192:195], v[92:95]
	v_mfma_f32_16x16x32_bf16 v[84:87], v[140:143], v[200:203], v[84:87]
	v_mfma_f32_16x16x32_bf16 v[76:79], v[152:155], v[200:203], v[76:79]
	v_mfma_f32_16x16x32_bf16 v[124:127], v[148:151], v[180:183], v[124:127]
	v_mfma_f32_16x16x32_bf16 v[120:123], v[156:159], v[180:183], v[120:123]
	v_mfma_f32_16x16x32_bf16 v[108:111], v[148:151], v[188:191], v[108:111]
	v_mfma_f32_16x16x32_bf16 v[104:107], v[156:159], v[188:191], v[104:107]
	v_mfma_f32_16x16x32_bf16 v[100:103], v[148:151], v[196:199], v[100:103]
	v_mfma_f32_16x16x32_bf16 v[92:95], v[156:159], v[196:199], v[92:95]
	v_mfma_f32_16x16x32_bf16 v[84:87], v[148:151], v[204:207], v[84:87]
	v_mfma_f32_16x16x32_bf16 v[76:79], v[156:159], v[204:207], v[76:79]
	s_setprio 0
	s_setprio 1
	v_mfma_f32_16x16x32_bf16 v[116:119], v[160:163], v[176:179], v[116:119]
	v_mfma_f32_16x16x32_bf16 v[112:115], v[168:171], v[176:179], v[112:115]
	v_mfma_f32_16x16x32_bf16 v[96:99], v[160:163], v[184:187], v[96:99]
	v_mfma_f32_16x16x32_bf16 v[88:91], v[168:171], v[184:187], v[88:91]
	v_mfma_f32_16x16x32_bf16 v[80:83], v[160:163], v[192:195], v[80:83]
	v_mfma_f32_16x16x32_bf16 v[72:75], v[168:171], v[192:195], v[72:75]
	v_mfma_f32_16x16x32_bf16 v[68:71], v[160:163], v[200:203], v[68:71]
	v_mfma_f32_16x16x32_bf16 v[64:67], v[168:171], v[200:203], v[64:67]
	v_mfma_f32_16x16x32_bf16 v[116:119], v[164:167], v[180:183], v[116:119]
	v_mfma_f32_16x16x32_bf16 v[112:115], v[172:175], v[180:183], v[112:115]
	v_mfma_f32_16x16x32_bf16 v[96:99], v[164:167], v[188:191], v[96:99]
	v_mfma_f32_16x16x32_bf16 v[88:91], v[172:175], v[188:191], v[88:91]
	v_mfma_f32_16x16x32_bf16 v[80:83], v[164:167], v[196:199], v[80:83]
	v_mfma_f32_16x16x32_bf16 v[72:75], v[172:175], v[196:199], v[72:75]
	v_mfma_f32_16x16x32_bf16 v[68:71], v[164:167], v[204:207], v[68:71]
	v_mfma_f32_16x16x32_bf16 v[64:67], v[172:175], v[204:207], v[64:67]
	s_setprio 0
	s_barrier
; #define PG8_STAGE(bufoff, gbase, voff) do { _Pragma("unroll") for (int _i = 0; _i < 2; ++_i) \
;         __builtin_amdgcn_global_load_lds((const unsigned*)((const char*)(gbase) + (voff)[_i]), (PG8_LAS unsigned*)(lds + (bufoff) + ldsw + _i * 8192), 16, 0, 0); } while (0)
; #define PG8_LDA(dst, b, h) do { _Pragma("unroll") for (int m = 0; m < 4; ++m) _Pragma("unroll") for (int k = 0; k < 2; ++k) dst[m][k] = *(const PG8_LAS bf16x8*)(lds + PG8_SA(b, h) + aoff + m * 2048 + k * 1024); } while (0)
; #define PG8_LDB(dst, b, h) do { _Pragma("unroll") for (int n = 0; n < 2; ++n) _Pragma("unroll") for (int k = 0; k < 2; ++k) dst[n][k] = *(const PG8_LAS bf16x8*)(lds + PG8_SB(b, h) + boff + n * 2048 + k * 1024); } while (0)
; #define PG8_MMA(ai, bj, At, Bt) do { __builtin_amdgcn_s_setprio(1); _Pragma("unroll") for (int m = 0; m < 4; ++m) _Pragma("unroll") for (int n = 0; n < 2; ++n) _Pragma("unroll") for (int k = 0; k < 2; ++k) \
;         acc[ai][bj][m][n] = __builtin_amdgcn_mfma_f32_16x16x32_bf16(Bt[n][k], At[m][k], acc[ai][bj][m][n], 0, 0, 0); __builtin_amdgcn_s_setprio(0); } while (0)
; #define PG8_WAIT_V(n) asm volatile("s_waitcnt vmcnt(" #n ")" ::: "memory")
; #define PG8_WAIT_L(n) asm volatile("s_waitcnt lgkmcnt(" #n ")" ::: "memory")
; #define PG8_BAR __builtin_amdgcn_s_barrier()
; template <class Epi, class Sched, bool ALIGN_EPI = false, bool SP2 = false, bool TA = true>
; __device__ __forceinline__ void gemm_phase(PG8_LAS unsigned char* lds, const Gemm g, const Sched& S, const Epi& E) {
;     ...
;         for (int t = 0; t < nt; t += 2) {
;             const bool last = (t == nt - 2);
;             const char* a1 = cA + (size_t)(t + 1) * kstep;
;             const char* a2 = last ? nA : cA + (size_t)(t + 2) * kstep; const char* b2 = last ? nB : cB + (size_t)(t + 2) * kstepB;
;             const char* a3 = a2 + kstep; const char* b3 = b2 + kstepB;
;     ...
;             PG8_LDB(B0, 1, 0); PG8_LDB(B1, 1, 1); PG8_SCHED; PG8_LDA(At, 1, 0); PG8_STAGE(PG8_SA(0, 1), a2 + hstep, voffA);
;             PG8_WAIT_V(8); PG8_WAIT_L(0); PG8_BAR; PG8_MMA(0, 0, At, B0); PG8_MMA(0, 1, At, B1); PG8_BAR; PG8_SCHED;
;             PG8_LDA(At, 1, 1); PG8_STAGE(PG8_SB(1, 0), b3, voffB); PG8_STAGE(PG8_SB(1, 1), b3 + hstep, voffB); PG8_STAGE(PG8_SA(1, 0), a3, voffA);
;             PG8_WAIT_V(8); PG8_WAIT_L(0); PG8_BAR; PG8_MMA(1, 0, At, B0); PG8_MMA(1, 1, At, B1); PG8_BAR; PG8_SCHED;
	s_mov_b32 m0, s60
	v_lshl_add_u64 v[212:213], v[144:145], 0, s[24:25]
	ds_read_b128 v[176:179], v139 offset:49152
	ds_read_b128 v[180:183], v139 offset:50176
	ds_read_b128 v[184:187], v139 offset:51200
	ds_read_b128 v[188:191], v139 offset:52224
	ds_read_b128 v[192:195], v139 offset:53248
	ds_read_b128 v[196:199], v139 offset:54272
	ds_read_b128 v[200:203], v139 offset:55296
	ds_read_b128 v[204:207], v139 offset:56320
	global_load_lds_dwordx4 v[212:213], off
	v_lshl_add_u64 v[212:213], v[144:145], 0, s[34:35]
	s_mov_b32 m0, s89
	s_nop 0
	global_load_lds_dwordx4 v[212:213], off
	v_lshl_add_u64 v[212:213], v[144:145], 0, s[36:37]
	s_mov_b32 m0, s88
	v_lshl_add_u64 v[144:145], v[144:145], 0, s[38:39]
	global_load_lds_dwordx4 v[212:213], off
	s_mov_b32 m0, s87
	s_nop 0
	global_load_lds_dwordx4 v[144:145], off
	v_lshl_add_u64 v[144:145], v[210:211], 0, s[24:25]
	s_mov_b32 m0, s69
	s_nop 0
	global_load_lds_dwordx4 v[144:145], off
	v_lshl_add_u64 v[144:145], v[210:211], 0, s[34:35]
	s_mov_b32 m0, s70
	s_nop 0
	global_load_lds_dwordx4 v[144:145], off
	s_waitcnt vmcnt(8)
	s_waitcnt lgkmcnt(0)
	s_barrier
	s_setprio 1
	s_waitcnt lgkmcnt(0)
	v_mfma_f32_16x16x32_bf16 v[60:63], v[140:143], v[176:179], v[60:63]
	v_mfma_f32_16x16x32_bf16 v[56:59], v[152:155], v[176:179], v[56:59]
	v_mfma_f32_16x16x32_bf16 v[48:51], v[140:143], v[184:187], v[48:51]
	v_mfma_f32_16x16x32_bf16 v[40:43], v[152:155], v[184:187], v[40:43]
	v_mfma_f32_16x16x32_bf16 v[32:35], v[140:143], v[192:195], v[32:35]
	v_mfma_f32_16x16x32_bf16 v[24:27], v[152:155], v[192:195], v[24:27]
	v_mfma_f32_16x16x32_bf16 v[16:19], v[140:143], v[200:203], v[16:19]
	v_mfma_f32_16x16x32_bf16 v[8:11], v[152:155], v[200:203], v[8:11]
	v_mfma_f32_16x16x32_bf16 v[60:63], v[148:151], v[180:183], v[60:63]
	v_mfma_f32_16x16x32_bf16 v[56:59], v[156:159], v[180:183], v[56:59]
	v_mfma_f32_16x16x32_bf16 v[48:51], v[148:151], v[188:191], v[48:51]
	v_mfma_f32_16x16x32_bf16 v[40:43], v[156:159], v[188:191], v[40:43]
	v_mfma_f32_16x16x32_bf16 v[32:35], v[148:151], v[196:199], v[32:35]
	v_mfma_f32_16x16x32_bf16 v[24:27], v[156:159], v[196:199], v[24:27]
	v_mfma_f32_16x16x32_bf16 v[16:19], v[148:151], v[204:207], v[16:19]
	v_mfma_f32_16x16x32_bf16 v[8:11], v[156:159], v[204:207], v[8:11]
	s_setprio 0
	s_setprio 1
	v_mfma_f32_16x16x32_bf16 v[52:55], v[160:163], v[176:179], v[52:55]
	v_mfma_f32_16x16x32_bf16 v[44:47], v[168:171], v[176:179], v[44:47]
	v_mfma_f32_16x16x32_bf16 v[36:39], v[160:163], v[184:187], v[36:39]
	v_mfma_f32_16x16x32_bf16 v[28:31], v[168:171], v[184:187], v[28:31]
	v_mfma_f32_16x16x32_bf16 v[20:23], v[160:163], v[192:195], v[20:23]
	v_mfma_f32_16x16x32_bf16 v[12:15], v[168:171], v[192:195], v[12:15]
	v_mfma_f32_16x16x32_bf16 v[4:7], v[160:163], v[200:203], v[4:7]
	v_mfma_f32_16x16x32_bf16 v[0:3], v[168:171], v[200:203], v[0:3]
	v_mfma_f32_16x16x32_bf16 v[52:55], v[164:167], v[180:183], v[52:55]
	v_mfma_f32_16x16x32_bf16 v[44:47], v[172:175], v[180:183], v[44:47]
	v_mfma_f32_16x16x32_bf16 v[36:39], v[164:167], v[188:191], v[36:39]
	v_mfma_f32_16x16x32_bf16 v[28:31], v[172:175], v[188:191], v[28:31]
	v_mfma_f32_16x16x32_bf16 v[20:23], v[164:167], v[196:199], v[20:23]
	v_mfma_f32_16x16x32_bf16 v[12:15], v[172:175], v[196:199], v[12:15]
	v_mfma_f32_16x16x32_bf16 v[4:7], v[164:167], v[204:207], v[4:7]
	v_mfma_f32_16x16x32_bf16 v[0:3], v[172:175], v[204:207], v[0:3]
	s_setprio 0
	s_barrier
	s_andn2_b64 vcc, exec, s[56:57]
	s_mov_b64 s[58:59], -1
	s_mov_b64 s[56:57], 0
	s_mov_b64 s[60:61], 0x8000

; #define PG8_STAGE(bufoff, gbase, voff) do { _Pragma("unroll") for (int _i = 0; _i < 2; ++_i) \
;         __builtin_amdgcn_global_load_lds((const unsigned*)((const char*)(gbase) + (voff)[_i]), (PG8_LAS unsigned*)(lds + (bufoff) + ldsw + _i * 8192), 16, 0, 0); } while (0)
; #define PG8_LDA(dst, b, h) do { _Pragma("unroll") for (int m = 0; m < 4; ++m) _Pragma("unroll") for (int k = 0; k < 2; ++k) dst[m][k] = *(const PG8_LAS bf16x8*)(lds + PG8_SA(b, h) + aoff + m * 2048 + k * 1024); } while (0)
; #define PG8_LDB(dst, b, h) do { _Pragma("unroll") for (int n = 0; n < 2; ++n) _Pragma("unroll") for (int k = 0; k < 2; ++k) dst[n][k] = *(const PG8_LAS bf16x8*)(lds + PG8_SB(b, h) + boff + n * 2048 + k * 1024); } while (0)
; #define PG8_WAIT_V(n) asm volatile("s_waitcnt vmcnt(" #n ")" ::: "memory")
; #define PG8_WAIT_L(n) asm volatile("s_waitcnt lgkmcnt(" #n ")" ::: "memory")
; #define PG8_BAR __builtin_amdgcn_s_barrier()
; #define PG8_SCHED __builtin_amdgcn_sched_barrier(0)
; template <class Epi, class Sched, bool ALIGN_EPI = false, bool SP2 = false, bool TA = true>
; __device__ __forceinline__ void gemm_phase(PG8_LAS unsigned char* lds, const Gemm g, const Sched& S, const Epi& E) {
;     ...
;         const bool has_next = S.next(ui + 1, nxt);
;         const char* nA = has_next ? (const char*)g.A + (size_t)nxt.pm * tstep : cA; const char* nB = has_next ? (const char*)g.Bt + (size_t)nxt.pn * tstep : cB;
; #pragma unroll 1
;         for (int t = 0; t < nt; t += 2) {
;             const bool last = (t == nt - 2);
;             const char* a1 = cA + (size_t)(t + 1) * kstep;
;             const char* a2 = last ? nA : cA + (size_t)(t + 2) * kstep; const char* b2 = last ? nB : cB + (size_t)(t + 2) * kstepB;
;             const char* a3 = a2 + kstep; const char* b3 = b2 + kstepB;
;             if (last && has_next) S.a_ready(nxt);
;             if constexpr (SP2) {
;             PG8_LDB(B0, 0, 0); PG8_LDB(B1, 0, 1); PG8_SCHED; PG8_LDA(At, 0, 0); PG8_STAGE(PG8_SA(1, 1), a1 + hstep, voffA);
;             PG8_WAIT_V(8); PG8_WAIT_L(0); PG8_BAR; PG8_MMA(0, 0, At, B0); PG8_MMA(0, 1, At, B1); PG8_BAR; PG8_SCHED;
;             PG8_LDA(At, 0, 1); PG8_STAGE(PG8_SB(0, 0), b2, voffB); PG8_STAGE(PG8_SB(0, 1), b2 + hstep, voffB); PG8_STAGE(PG8_SA(0, 0), a2, voffA);
;             PG8_WAIT_V(8); PG8_WAIT_L(0); PG8_BAR; PG8_MMA(1, 0, At, B0); PG8_MMA(1, 1, At, B1); PG8_BAR; PG8_SCHED;
.LBB0_1832:
	s_ashr_i32 s39, s38, 31
	s_lshl_b64 s[40:41], s[38:39], 19
	s_add_u32 s40, s8, s40
	s_addc_u32 s41, s9, s41
	s_and_b64 s[42:43], s[2:3], exec
	s_cselect_b32 s39, s41, s49
	s_cselect_b32 s46, s40, s48
	s_ashr_i32 s37, s36, 31
	s_lshl_b64 s[42:43], s[36:37], 19
	s_add_u32 s42, s22, s42
	s_addc_u32 s43, s23, s43
	s_and_b64 s[66:67], s[2:3], exec
	s_cselect_b32 s37, s43, s51
	s_cselect_b32 s66, s42, s50
	s_add_u32 s48, s48, 0x44000
	s_addc_u32 s49, s49, 0
	s_add_u32 s50, s50, 0x8000
	s_addc_u32 s51, s51, 0
	s_mov_b32 s67, -2
	ds_read_b128 v[128:131], v165
	ds_read_b128 v[132:135], v165 offset:1024
	ds_read_b128 v[136:139], v165 offset:2048
	ds_read_b128 v[140:143], v165 offset:3072
	ds_read_b128 v[152:155], v166
	ds_read_b128 v[156:159], v166 offset:1024
	ds_read_b128 v[170:173], v166 offset:2048
	ds_read_b128 v[174:177], v166 offset:3072
	s_add_u32 s68, s48, 0xfffc4000
	s_addc_u32 s69, s49, -1
	s_cmp_eq_u32 s67, 12
	s_cselect_b32 s69, s39, s69
	s_cselect_b32 s68, s46, s68
	s_cselect_b32 s71, s37, s51
	s_cselect_b32 s70, s66, s50
	v_lshl_add_u64 v[206:207], s[48:49], 0, v[144:145]
	s_add_i32 m0, s52, 0xc000
	ds_read_b128 v[178:181], v167
	ds_read_b128 v[182:185], v167 offset:1024
	ds_read_b128 v[186:189], v167 offset:2048
	ds_read_b128 v[190:193], v167 offset:3072
	ds_read_b128 v[194:197], v167 offset:4096
	ds_read_b128 v[198:201], v167 offset:5120
	ds_read_b128 v[202:205], v167 offset:6144
	ds_read_b128 v[210:213], v167 offset:7168
	global_load_lds_dwordx4 v[206:207], off
	v_lshl_add_u64 v[206:207], v[206:207], 0, s[4:5]
	s_add_i32 m0, s52, 0xe000
	s_nop 0
	global_load_lds_dwordx4 v[206:207], off
	s_waitcnt vmcnt(8)
	s_waitcnt lgkmcnt(0)
	s_barrier
	s_setprio 1
	s_waitcnt lgkmcnt(0)
	v_mfma_f32_16x16x32_bf16 v[124:127], v[128:131], v[178:181], 0
	v_mfma_f32_16x16x32_bf16 v[120:123], v[136:139], v[178:181], 0
	v_mfma_f32_16x16x32_bf16 v[108:111], v[128:131], v[186:189], 0
	v_mfma_f32_16x16x32_bf16 v[104:107], v[136:139], v[186:189], 0
	v_mfma_f32_16x16x32_bf16 v[92:95], v[128:131], v[194:197], 0
	v_mfma_f32_16x16x32_bf16 v[88:91], v[136:139], v[194:197], 0
	v_mfma_f32_16x16x32_bf16 v[76:79], v[128:131], v[202:205], 0
	v_mfma_f32_16x16x32_bf16 v[72:75], v[136:139], v[202:205], 0
	v_mfma_f32_16x16x32_bf16 v[124:127], v[132:135], v[182:185], v[124:127]
	v_mfma_f32_16x16x32_bf16 v[120:123], v[140:143], v[182:185], v[120:123]
	v_mfma_f32_16x16x32_bf16 v[108:111], v[132:135], v[190:193], v[108:111]
	v_mfma_f32_16x16x32_bf16 v[104:107], v[140:143], v[190:193], v[104:107]
	v_mfma_f32_16x16x32_bf16 v[92:95], v[132:135], v[198:201], v[92:95]
	v_mfma_f32_16x16x32_bf16 v[88:91], v[140:143], v[198:201], v[88:91]
	v_mfma_f32_16x16x32_bf16 v[76:79], v[132:135], v[210:213], v[76:79]
	v_mfma_f32_16x16x32_bf16 v[72:75], v[140:143], v[210:213], v[72:75]
	s_setprio 0
	s_setprio 1
	v_mfma_f32_16x16x32_bf16 v[116:119], v[152:155], v[178:181], 0
	v_mfma_f32_16x16x32_bf16 v[112:115], v[170:173], v[178:181], 0
	v_mfma_f32_16x16x32_bf16 v[100:103], v[152:155], v[186:189], 0
	v_mfma_f32_16x16x32_bf16 v[96:99], v[170:173], v[186:189], 0
	v_mfma_f32_16x16x32_bf16 v[84:87], v[152:155], v[194:197], 0
	v_mfma_f32_16x16x32_bf16 v[80:83], v[170:173], v[194:197], 0
	v_mfma_f32_16x16x32_bf16 v[68:71], v[152:155], v[202:205], 0
	v_mfma_f32_16x16x32_bf16 v[64:67], v[170:173], v[202:205], 0
	v_mfma_f32_16x16x32_bf16 v[116:119], v[156:159], v[182:185], v[116:119]
	v_mfma_f32_16x16x32_bf16 v[112:115], v[174:177], v[182:185], v[112:115]
	v_mfma_f32_16x16x32_bf16 v[100:103], v[156:159], v[190:193], v[100:103]
	v_mfma_f32_16x16x32_bf16 v[96:99], v[174:177], v[190:193], v[96:99]
	v_mfma_f32_16x16x32_bf16 v[84:87], v[156:159], v[198:201], v[84:87]
	v_mfma_f32_16x16x32_bf16 v[80:83], v[174:177], v[198:201], v[80:83]
	v_mfma_f32_16x16x32_bf16 v[68:71], v[156:159], v[210:213], v[68:71]
	v_mfma_f32_16x16x32_bf16 v[64:67], v[174:177], v[210:213], v[64:67]
	s_setprio 0
	s_barrier
	v_lshl_add_u64 v[206:207], s[70:71], 0, v[144:145]
	s_add_i32 s70, s63, s33
	s_mov_b32 m0, s70
	ds_read_b128 v[178:181], v167 offset:16384
	ds_read_b128 v[182:185], v167 offset:17408
	ds_read_b128 v[186:189], v167 offset:18432
	ds_read_b128 v[190:193], v167 offset:19456
	ds_read_b128 v[194:197], v167 offset:20480
	ds_read_b128 v[198:201], v167 offset:21504
	ds_read_b128 v[202:205], v167 offset:22528
	ds_read_b128 v[210:213], v167 offset:23552
	global_load_lds_dwordx4 v[206:207], off
	v_lshl_add_u64 v[214:215], v[206:207], 0, s[4:5]
	s_add_i32 m0, s70, 0x2000
	s_add_i32 s70, s64, s33
	global_load_lds_dwordx4 v[214:215], off
	v_lshl_add_u64 v[214:215], v[206:207], 0, s[6:7]
	s_mov_b32 m0, s70
	s_nop 0
	global_load_lds_dwordx4 v[214:215], off
	v_lshl_add_u64 v[214:215], v[206:207], 0, s[12:13]
	s_add_i32 m0, s70, 0x2000
	s_nop 0
	global_load_lds_dwordx4 v[214:215], off
	v_lshl_add_u64 v[214:215], s[68:69], 0, v[144:145]
	s_mov_b32 m0, s52
	v_lshl_add_u64 v[216:217], v[214:215], 0, s[4:5]
	global_load_lds_dwordx4 v[214:215], off
	s_mov_b32 m0, s53
	s_nop 0
	global_load_lds_dwordx4 v[216:217], off
	s_waitcnt vmcnt(8)
	s_waitcnt lgkmcnt(0)
	s_barrier
; #define PG8_STAGE(bufoff, gbase, voff) do { _Pragma("unroll") for (int _i = 0; _i < 2; ++_i) \
;         __builtin_amdgcn_global_load_lds((const unsigned*)((const char*)(gbase) + (voff)[_i]), (PG8_LAS unsigned*)(lds + (bufoff) + ldsw + _i * 8192), 16, 0, 0); } while (0)
; #define PG8_LDA(dst, b, h) do { _Pragma("unroll") for (int m = 0; m < 4; ++m) _Pragma("unroll") for (int k = 0; k < 2; ++k) dst[m][k] = *(const PG8_LAS bf16x8*)(lds + PG8_SA(b, h) + aoff + m * 2048 + k * 1024); } while (0)
; #define PG8_LDB(dst, b, h) do { _Pragma("unroll") for (int n = 0; n < 2; ++n) _Pragma("unroll") for (int k = 0; k < 2; ++k) dst[n][k] = *(const PG8_LAS bf16x8*)(lds + PG8_SB(b, h) + boff + n * 2048 + k * 1024); } while (0)
; #define PG8_MMA(ai, bj, At, Bt) do { __builtin_amdgcn_s_setprio(1); _Pragma("unroll") for (int m = 0; m < 4; ++m) _Pragma("unroll") for (int n = 0; n < 2; ++n) _Pragma("unroll") for (int k = 0; k < 2; ++k) \
;         acc[ai][bj][m][n] = __builtin_amdgcn_mfma_f32_16x16x32_bf16(Bt[n][k], At[m][k], acc[ai][bj][m][n], 0, 0, 0); __builtin_amdgcn_s_setprio(0); } while (0)
; #define PG8_WAIT_V(n) asm volatile("s_waitcnt vmcnt(" #n ")" ::: "memory")
; #define PG8_WAIT_L(n) asm volatile("s_waitcnt lgkmcnt(" #n ")" ::: "memory")
; #define PG8_BAR __builtin_amdgcn_s_barrier()
; #define PG8_SCHED __builtin_amdgcn_sched_barrier(0)
; template <class Epi, class Sched, bool ALIGN_EPI = false, bool SP2 = false, bool TA = true>
; __device__ __forceinline__ void gemm_phase(PG8_LAS unsigned char* lds, const Gemm g, const Sched& S, const Epi& E) {
;     ...
;             PG8_WAIT_V(8); PG8_WAIT_L(0); PG8_BAR; PG8_MMA(0, 0, At, B0); PG8_MMA(0, 1, At, B1); PG8_BAR; PG8_SCHED;
;             PG8_LDA(At, 0, 1); PG8_STAGE(PG8_SB(0, 0), b2, voffB); PG8_STAGE(PG8_SB(0, 1), b2 + hstep, voffB); PG8_STAGE(PG8_SA(0, 0), a2, voffA);
;             PG8_WAIT_V(8); PG8_WAIT_L(0); PG8_BAR; PG8_MMA(1, 0, At, B0); PG8_MMA(1, 1, At, B1); PG8_BAR; PG8_SCHED;
;             PG8_LDB(B0, 1, 0); PG8_LDB(B1, 1, 1); PG8_SCHED; PG8_LDA(At, 1, 0); PG8_STAGE(PG8_SA(0, 1), a2 + hstep, voffA);
;             PG8_WAIT_V(8); PG8_WAIT_L(0); PG8_BAR; PG8_MMA(0, 0, At, B0); PG8_MMA(0, 1, At, B1); PG8_BAR; PG8_SCHED;
	s_setprio 1
	s_waitcnt lgkmcnt(0)
	v_mfma_f32_16x16x32_bf16 v[60:63], v[128:131], v[178:181], 0
	v_mfma_f32_16x16x32_bf16 v[56:59], v[136:139], v[178:181], 0
	v_mfma_f32_16x16x32_bf16 v[44:47], v[128:131], v[186:189], 0
	v_mfma_f32_16x16x32_bf16 v[40:43], v[136:139], v[186:189], 0
	v_mfma_f32_16x16x32_bf16 v[28:31], v[128:131], v[194:197], 0
	v_mfma_f32_16x16x32_bf16 v[24:27], v[136:139], v[194:197], 0
	v_mfma_f32_16x16x32_bf16 v[12:15], v[128:131], v[202:205], 0
	v_mfma_f32_16x16x32_bf16 v[8:11], v[136:139], v[202:205], 0
	v_mfma_f32_16x16x32_bf16 v[60:63], v[132:135], v[182:185], v[60:63]
	v_mfma_f32_16x16x32_bf16 v[56:59], v[140:143], v[182:185], v[56:59]
	v_mfma_f32_16x16x32_bf16 v[44:47], v[132:135], v[190:193], v[44:47]
	v_mfma_f32_16x16x32_bf16 v[40:43], v[140:143], v[190:193], v[40:43]
	v_mfma_f32_16x16x32_bf16 v[28:31], v[132:135], v[198:201], v[28:31]
	v_mfma_f32_16x16x32_bf16 v[24:27], v[140:143], v[198:201], v[24:27]
	v_mfma_f32_16x16x32_bf16 v[12:15], v[132:135], v[210:213], v[12:15]
	v_mfma_f32_16x16x32_bf16 v[8:11], v[140:143], v[210:213], v[8:11]
	s_setprio 0
	s_setprio 1
	v_mfma_f32_16x16x32_bf16 v[52:55], v[152:155], v[178:181], 0
	v_mfma_f32_16x16x32_bf16 v[48:51], v[170:173], v[178:181], 0
	v_mfma_f32_16x16x32_bf16 v[36:39], v[152:155], v[186:189], 0
	v_mfma_f32_16x16x32_bf16 v[32:35], v[170:173], v[186:189], 0
	v_mfma_f32_16x16x32_bf16 v[20:23], v[152:155], v[194:197], 0
	v_mfma_f32_16x16x32_bf16 v[16:19], v[170:173], v[194:197], 0
	v_mfma_f32_16x16x32_bf16 v[4:7], v[152:155], v[202:205], 0
	v_mfma_f32_16x16x32_bf16 v[0:3], v[170:173], v[202:205], 0
	v_mfma_f32_16x16x32_bf16 v[52:55], v[156:159], v[182:185], v[52:55]
	v_mfma_f32_16x16x32_bf16 v[48:51], v[174:177], v[182:185], v[48:51]
	v_mfma_f32_16x16x32_bf16 v[36:39], v[156:159], v[190:193], v[36:39]
	v_mfma_f32_16x16x32_bf16 v[32:35], v[174:177], v[190:193], v[32:35]
	v_mfma_f32_16x16x32_bf16 v[20:23], v[156:159], v[198:201], v[20:23]
	v_mfma_f32_16x16x32_bf16 v[16:19], v[174:177], v[198:201], v[16:19]
	v_mfma_f32_16x16x32_bf16 v[4:7], v[156:159], v[210:213], v[4:7]
	v_mfma_f32_16x16x32_bf16 v[0:3], v[174:177], v[210:213], v[0:3]
	s_setprio 0
	s_barrier
	s_add_i32 s68, 0, 0x18000
	s_add_i32 s69, 0, 0x1c000
	v_add_u32_e32 v140, s68, v162
	v_add_u32_e32 v146, s69, v162
	ds_read_b128 v[128:131], v140
	ds_read_b128 v[132:135], v140 offset:1024
	ds_read_b128 v[136:139], v140 offset:2048
	ds_read_b128 v[140:143], v140 offset:3072
	ds_read_b128 v[152:155], v146
	ds_read_b128 v[156:159], v146 offset:1024
	ds_read_b128 v[170:173], v146 offset:2048
	ds_read_b128 v[174:177], v146 offset:3072
	s_mov_b32 m0, s54
	v_lshl_add_u64 v[216:217], v[214:215], 0, s[6:7]
	ds_read_b128 v[178:181], v167 offset:32768
	ds_read_b128 v[182:185], v167 offset:33792
	ds_read_b128 v[186:189], v167 offset:34816
	ds_read_b128 v[190:193], v167 offset:35840
	ds_read_b128 v[194:197], v167 offset:36864
	ds_read_b128 v[198:201], v167 offset:37888
	ds_read_b128 v[202:205], v167 offset:38912
	ds_read_b128 v[210:213], v167 offset:39936
	global_load_lds_dwordx4 v[216:217], off
	v_lshl_add_u64 v[216:217], v[214:215], 0, s[12:13]
	s_mov_b32 m0, s55
	s_nop 0
	global_load_lds_dwordx4 v[216:217], off
	s_waitcnt vmcnt(8)
	s_waitcnt lgkmcnt(0)
	s_barrier
	s_setprio 1
	s_waitcnt lgkmcnt(0)
	v_mfma_f32_16x16x32_bf16 v[124:127], v[128:131], v[178:181], v[124:127]
	v_mfma_f32_16x16x32_bf16 v[120:123], v[136:139], v[178:181], v[120:123]
	v_mfma_f32_16x16x32_bf16 v[108:111], v[128:131], v[186:189], v[108:111]
	v_mfma_f32_16x16x32_bf16 v[104:107], v[136:139], v[186:189], v[104:107]
	v_mfma_f32_16x16x32_bf16 v[92:95], v[128:131], v[194:197], v[92:95]
	v_mfma_f32_16x16x32_bf16 v[88:91], v[136:139], v[194:197], v[88:91]
	v_mfma_f32_16x16x32_bf16 v[76:79], v[128:131], v[202:205], v[76:79]
	v_mfma_f32_16x16x32_bf16 v[72:75], v[136:139], v[202:205], v[72:75]
	v_mfma_f32_16x16x32_bf16 v[124:127], v[132:135], v[182:185], v[124:127]
	v_mfma_f32_16x16x32_bf16 v[120:123], v[140:143], v[182:185], v[120:123]
	v_mfma_f32_16x16x32_bf16 v[108:111], v[132:135], v[190:193], v[108:111]
	v_mfma_f32_16x16x32_bf16 v[104:107], v[140:143], v[190:193], v[104:107]
	v_mfma_f32_16x16x32_bf16 v[92:95], v[132:135], v[198:201], v[92:95]
	v_mfma_f32_16x16x32_bf16 v[88:91], v[140:143], v[198:201], v[88:91]
	v_mfma_f32_16x16x32_bf16 v[76:79], v[132:135], v[210:213], v[76:79]
	v_mfma_f32_16x16x32_bf16 v[72:75], v[140:143], v[210:213], v[72:75]
	s_setprio 0
	s_setprio 1
	v_mfma_f32_16x16x32_bf16 v[116:119], v[152:155], v[178:181], v[116:119]
	v_mfma_f32_16x16x32_bf16 v[112:115], v[170:173], v[178:181], v[112:115]
	v_mfma_f32_16x16x32_bf16 v[100:103], v[152:155], v[186:189], v[100:103]
	v_mfma_f32_16x16x32_bf16 v[96:99], v[170:173], v[186:189], v[96:99]
	v_mfma_f32_16x16x32_bf16 v[84:87], v[152:155], v[194:197], v[84:87]
	v_mfma_f32_16x16x32_bf16 v[80:83], v[170:173], v[194:197], v[80:83]
	v_mfma_f32_16x16x32_bf16 v[68:71], v[152:155], v[202:205], v[68:71]
	v_mfma_f32_16x16x32_bf16 v[64:67], v[170:173], v[202:205], v[64:67]
	v_mfma_f32_16x16x32_bf16 v[116:119], v[156:159], v[182:185], v[116:119]
	v_mfma_f32_16x16x32_bf16 v[112:115], v[174:177], v[182:185], v[112:115]
	v_mfma_f32_16x16x32_bf16 v[100:103], v[156:159], v[190:193], v[100:103]
	v_mfma_f32_16x16x32_bf16 v[96:99], v[174:177], v[190:193], v[96:99]
	v_mfma_f32_16x16x32_bf16 v[84:87], v[156:159], v[198:201], v[84:87]
	v_mfma_f32_16x16x32_bf16 v[80:83], v[174:177], v[198:201], v[80:83]
	v_mfma_f32_16x16x32_bf16 v[68:71], v[156:159], v[210:213], v[68:71]
	v_mfma_f32_16x16x32_bf16 v[64:67], v[174:177], v[210:213], v[64:67]
	s_setprio 0
	s_barrier
; #define PG8_STAGE(bufoff, gbase, voff) do { _Pragma("unroll") for (int _i = 0; _i < 2; ++_i) \
;         __builtin_amdgcn_global_load_lds((const unsigned*)((const char*)(gbase) + (voff)[_i]), (PG8_LAS unsigned*)(lds + (bufoff) + ldsw + _i * 8192), 16, 0, 0); } while (0)
; #define PG8_LDA(dst, b, h) do { _Pragma("unroll") for (int m = 0; m < 4; ++m) _Pragma("unroll") for (int k = 0; k < 2; ++k) dst[m][k] = *(const PG8_LAS bf16x8*)(lds + PG8_SA(b, h) + aoff + m * 2048 + k * 1024); } while (0)
; #define PG8_LDB(dst, b, h) do { _Pragma("unroll") for (int n = 0; n < 2; ++n) _Pragma("unroll") for (int k = 0; k < 2; ++k) dst[n][k] = *(const PG8_LAS bf16x8*)(lds + PG8_SB(b, h) + boff + n * 2048 + k * 1024); } while (0)
; #define PG8_MMA(ai, bj, At, Bt) do { __builtin_amdgcn_s_setprio(1); _Pragma("unroll") for (int m = 0; m < 4; ++m) _Pragma("unroll") for (int n = 0; n < 2; ++n) _Pragma("unroll") for (int k = 0; k < 2; ++k) \
;         acc[ai][bj][m][n] = __builtin_amdgcn_mfma_f32_16x16x32_bf16(Bt[n][k], At[m][k], acc[ai][bj][m][n], 0, 0, 0); __builtin_amdgcn_s_setprio(0); } while (0)
; #define PG8_WAIT_V(n) asm volatile("s_waitcnt vmcnt(" #n ")" ::: "memory")
; #define PG8_WAIT_L(n) asm volatile("s_waitcnt lgkmcnt(" #n ")" ::: "memory")
; #define PG8_BAR __builtin_amdgcn_s_barrier()
; template <class Epi, class Sched, bool ALIGN_EPI = false, bool SP2 = false, bool TA = true>
; __device__ __forceinline__ void gemm_phase(PG8_LAS unsigned char* lds, const Gemm g, const Sched& S, const Epi& E) {
;     ...
;         for (int t = 0; t < nt; t += 2) {
;             const bool last = (t == nt - 2);
;             const char* a1 = cA + (size_t)(t + 1) * kstep;
;             const char* a2 = last ? nA : cA + (size_t)(t + 2) * kstep; const char* b2 = last ? nB : cB + (size_t)(t + 2) * kstepB;
;             const char* a3 = a2 + kstep; const char* b3 = b2 + kstepB;
;     ...
;             PG8_LDB(B0, 1, 0); PG8_LDB(B1, 1, 1); PG8_SCHED; PG8_LDA(At, 1, 0); PG8_STAGE(PG8_SA(0, 1), a2 + hstep, voffA);
;             PG8_WAIT_V(8); PG8_WAIT_L(0); PG8_BAR; PG8_MMA(0, 0, At, B0); PG8_MMA(0, 1, At, B1); PG8_BAR; PG8_SCHED;
;             PG8_LDA(At, 1, 1); PG8_STAGE(PG8_SB(1, 0), b3, voffB); PG8_STAGE(PG8_SB(1, 1), b3 + hstep, voffB); PG8_STAGE(PG8_SA(1, 0), a3, voffA);
;             PG8_WAIT_V(8); PG8_WAIT_L(0); PG8_BAR; PG8_MMA(1, 0, At, B0); PG8_MMA(1, 1, At, B1); PG8_BAR; PG8_SCHED;
	s_add_i32 s68, s68, s33
	v_lshl_add_u64 v[216:217], v[206:207], 0, s[18:19]
	s_mov_b32 m0, s68
	ds_read_b128 v[178:181], v167 offset:49152
	ds_read_b128 v[182:185], v167 offset:50176
	ds_read_b128 v[186:189], v167 offset:51200
	ds_read_b128 v[190:193], v167 offset:52224
	ds_read_b128 v[194:197], v167 offset:53248
	ds_read_b128 v[198:201], v167 offset:54272
	ds_read_b128 v[202:205], v167 offset:55296
	ds_read_b128 v[210:213], v167 offset:56320
	global_load_lds_dwordx4 v[216:217], off
	v_lshl_add_u64 v[216:217], v[206:207], 0, s[24:25]
	s_add_i32 m0, s68, 0x2000
	s_add_i32 s68, s69, s33
	global_load_lds_dwordx4 v[216:217], off
	v_lshl_add_u64 v[216:217], v[206:207], 0, s[28:29]
	s_mov_b32 m0, s68
	v_lshl_add_u64 v[206:207], v[206:207], 0, s[30:31]
	global_load_lds_dwordx4 v[216:217], off
	s_add_i32 m0, s68, 0x2000
	s_nop 0
	global_load_lds_dwordx4 v[206:207], off
	v_lshl_add_u64 v[206:207], v[214:215], 0, s[18:19]
	s_mov_b32 m0, s58
	s_nop 0
	global_load_lds_dwordx4 v[206:207], off
	v_lshl_add_u64 v[206:207], v[214:215], 0, s[24:25]
	s_mov_b32 m0, s59
	s_nop 0
	global_load_lds_dwordx4 v[206:207], off
	s_waitcnt vmcnt(8)
	s_waitcnt lgkmcnt(0)
	s_barrier
	s_setprio 1
	s_waitcnt lgkmcnt(0)
	v_mfma_f32_16x16x32_bf16 v[60:63], v[128:131], v[178:181], v[60:63]
	v_mfma_f32_16x16x32_bf16 v[56:59], v[136:139], v[178:181], v[56:59]
	v_mfma_f32_16x16x32_bf16 v[44:47], v[128:131], v[186:189], v[44:47]
	v_mfma_f32_16x16x32_bf16 v[40:43], v[136:139], v[186:189], v[40:43]
	v_mfma_f32_16x16x32_bf16 v[28:31], v[128:131], v[194:197], v[28:31]
	v_mfma_f32_16x16x32_bf16 v[24:27], v[136:139], v[194:197], v[24:27]
	v_mfma_f32_16x16x32_bf16 v[12:15], v[128:131], v[202:205], v[12:15]
	v_mfma_f32_16x16x32_bf16 v[8:11], v[136:139], v[202:205], v[8:11]
	v_mfma_f32_16x16x32_bf16 v[60:63], v[132:135], v[182:185], v[60:63]
	v_mfma_f32_16x16x32_bf16 v[56:59], v[140:143], v[182:185], v[56:59]
	v_mfma_f32_16x16x32_bf16 v[44:47], v[132:135], v[190:193], v[44:47]
	v_mfma_f32_16x16x32_bf16 v[40:43], v[140:143], v[190:193], v[40:43]
	v_mfma_f32_16x16x32_bf16 v[28:31], v[132:135], v[198:201], v[28:31]
	v_mfma_f32_16x16x32_bf16 v[24:27], v[140:143], v[198:201], v[24:27]
	v_mfma_f32_16x16x32_bf16 v[12:15], v[132:135], v[210:213], v[12:15]
	v_mfma_f32_16x16x32_bf16 v[8:11], v[140:143], v[210:213], v[8:11]
	s_setprio 0
	s_setprio 1
	v_mfma_f32_16x16x32_bf16 v[52:55], v[152:155], v[178:181], v[52:55]
	v_mfma_f32_16x16x32_bf16 v[48:51], v[170:173], v[178:181], v[48:51]
	v_mfma_f32_16x16x32_bf16 v[36:39], v[152:155], v[186:189], v[36:39]
	v_mfma_f32_16x16x32_bf16 v[32:35], v[170:173], v[186:189], v[32:35]
	v_mfma_f32_16x16x32_bf16 v[20:23], v[152:155], v[194:197], v[20:23]
	v_mfma_f32_16x16x32_bf16 v[16:19], v[170:173], v[194:197], v[16:19]
	v_mfma_f32_16x16x32_bf16 v[4:7], v[152:155], v[202:205], v[4:7]
	v_mfma_f32_16x16x32_bf16 v[0:3], v[170:173], v[202:205], v[0:3]
	v_mfma_f32_16x16x32_bf16 v[52:55], v[156:159], v[182:185], v[52:55]
	v_mfma_f32_16x16x32_bf16 v[48:51], v[174:177], v[182:185], v[48:51]
	v_mfma_f32_16x16x32_bf16 v[36:39], v[156:159], v[190:193], v[36:39]
	v_mfma_f32_16x16x32_bf16 v[32:35], v[174:177], v[190:193], v[32:35]
	v_mfma_f32_16x16x32_bf16 v[20:23], v[156:159], v[198:201], v[20:23]
	v_mfma_f32_16x16x32_bf16 v[16:19], v[174:177], v[198:201], v[16:19]
	v_mfma_f32_16x16x32_bf16 v[4:7], v[156:159], v[210:213], v[4:7]
	v_mfma_f32_16x16x32_bf16 v[0:3], v[174:177], v[210:213], v[0:3]
	s_setprio 0
	s_barrier
	s_add_i32 s67, s67, 2
	s_add_u32 s48, s48, 0x8000
	s_addc_u32 s49, s49, 0
	s_add_u32 s50, s50, 0x8000
	s_addc_u32 s51, s51, 0
	s_cmp_gt_u32 s67, 13
